# streaming loops (P0 rmsnorm, P5b, P7b): last row handled by a tail without the redundant reload (6 percent fewer read bytes)
# speedup vs baseline: 1.0025x; 1.0022x over previous
; __device__ __forceinline__ unsigned pk2(float lo, float hi) { return pg8::cvt_pk_bf16(lo, hi); }
; #define INP(i) ((const float*)(const GAS float*)KARG(8 * (i)))
; #define X_IN INP(0)
; __global__ void __launch_bounds__(512, 2) fwd(Params P) {
;     ...
;         const f32x4* gr = (const f32x4*)INP(3) + lane;
;         for (int m = gw; m < T_TOK; m += NGW) {
;             const f32x4* xr = (const f32x4*)(X_IN + (size_t)m * DM) + lane; f32x4 v[8]; float s = 0.f;
; #pragma unroll
;             for (int j = 0; j < 8; ++j) { v[j] = __builtin_nontemporal_load(&xr[64 * j]); s += (v[j].x * v[j].x + v[j].y * v[j].y) + (v[j].z * v[j].z + v[j].w * v[j].w); }
;             const float rs = __builtin_amdgcn_rsqf(wave_sum(s) * (1.f / DM) + EPS);
;             u32x2* o = (u32x2*)(XN + (size_t)m * DM) + lane;
; #pragma unroll
;             for (int j = 0; j < 8; ++j) { const f32x4 g = gr[64 * j]; u32x2 w; w.x = pk2(v[j].x * rs * g.x, v[j].y * rs * g.y); w.y = pk2(v[j].z * rs * g.z, v[j].w * rs * g.w); o[64 * j] = w; }
;         }
.LBB0_151:
	s_cmp_lt_i32 s80, 0x8000
	s_cselect_b64 s[6:7], -1, 0
	s_mov_b64 s[4:5], s[0:1]
	v_mov_b32_e32 v167, 0
	v_writelane_b32 v246, s6, 4
	s_cmpk_gt_i32 s80, 0x7fff
	v_lshlrev_b32_e32 v166, 4, v179
	v_mbcnt_lo_u32_b32 v180, -1, 0
	v_writelane_b32 v246, s7, 5
	s_cbranch_scc1 .LBB0_154
	s_load_dwordx2 s[8:9], s[0:1], 0x18
	s_load_dwordx2 s[4:5], s[0:1], 0x0
	s_load_dwordx2 s[6:7], s[0:1], 0xa8
	v_lshlrev_b32_e32 v106, 3, v179
	v_mov_b32_e32 v101, 0x358637bd
	s_mov_b32 s12, s80
	s_waitcnt lgkmcnt(0)
	s_add_u32 s10, s8, 0x1000
	s_addc_u32 s11, s9, 0
	s_add_u32 s4, s4, 0x1000
	s_addc_u32 s5, s5, 0
	s_add_u32 s6, s6, 0x8000000
	s_addc_u32 s7, s7, 0
	global_load_dwordx4 v[0:3], v166, s[8:9] offset:0
	global_load_dwordx4 v[4:7], v166, s[8:9] offset:1024
	global_load_dwordx4 v[8:11], v166, s[8:9] offset:2048
	global_load_dwordx4 v[12:15], v166, s[8:9] offset:3072
	global_load_dwordx4 v[16:19], v166, s[10:11] offset:0
	global_load_dwordx4 v[20:23], v166, s[10:11] offset:1024
	global_load_dwordx4 v[24:27], v166, s[10:11] offset:2048
	global_load_dwordx4 v[28:31], v166, s[10:11] offset:3072
	s_lshl_b32 s13, s12, 13
	s_add_u32 s8, s4, s13
	s_addc_u32 s9, s5, 0
	global_load_dwordx4 v[32:35], v166, s[8:9] offset:-4096 nt
	global_load_dwordx4 v[36:39], v166, s[8:9] offset:-3072 nt
	global_load_dwordx4 v[40:43], v166, s[8:9] offset:-2048 nt
	global_load_dwordx4 v[44:47], v166, s[8:9] offset:-1024 nt
	global_load_dwordx4 v[48:51], v166, s[8:9] offset:0 nt
	global_load_dwordx4 v[52:55], v166, s[8:9] offset:1024 nt
	global_load_dwordx4 v[56:59], v166, s[8:9] offset:2048 nt
	global_load_dwordx4 v[60:63], v166, s[8:9] offset:3072 nt
	s_lshl_b32 s13, s12, 12
	s_add_u32 s10, s6, s13
	s_addc_u32 s11, s7, 0
	s_add_i32 s13, s12, s82
	s_cmpk_gt_i32 s13, 0x7fff
	s_cbranch_scc1 .Lp0n_tail_a
	s_mov_b32 s12, s13
	s_lshl_b32 s13, s13, 13
	s_add_u32 s8, s4, s13
	s_addc_u32 s9, s5, 0
	global_load_dwordx4 v[64:67], v166, s[8:9] offset:-4096 nt
	global_load_dwordx4 v[68:71], v166, s[8:9] offset:-3072 nt
	global_load_dwordx4 v[72:75], v166, s[8:9] offset:-2048 nt
	global_load_dwordx4 v[76:79], v166, s[8:9] offset:-1024 nt
	global_load_dwordx4 v[80:83], v166, s[8:9] offset:0 nt
	global_load_dwordx4 v[84:87], v166, s[8:9] offset:1024 nt
	global_load_dwordx4 v[88:91], v166, s[8:9] offset:2048 nt
	global_load_dwordx4 v[92:95], v166, s[8:9] offset:3072 nt
	s_waitcnt vmcnt(15)
	v_mul_f32_e32 v102, v32, v32
	v_mul_f32_e32 v103, v33, v33
	v_mul_f32_e32 v104, v34, v34
	v_mul_f32_e32 v105, v35, v35
	s_waitcnt vmcnt(14)
	v_fma_f32 v102, v36, v36, v102
	v_fma_f32 v103, v37, v37, v103
	v_fma_f32 v104, v38, v38, v104
	v_fma_f32 v105, v39, v39, v105
	s_waitcnt vmcnt(13)
	v_fma_f32 v102, v40, v40, v102
	v_fma_f32 v103, v41, v41, v103
	v_fma_f32 v104, v42, v42, v104
	v_fma_f32 v105, v43, v43, v105
	s_waitcnt vmcnt(12)
	v_fma_f32 v102, v44, v44, v102
	v_fma_f32 v103, v45, v45, v103
	v_fma_f32 v104, v46, v46, v104
	v_fma_f32 v105, v47, v47, v105
	s_waitcnt vmcnt(11)
	v_fma_f32 v102, v48, v48, v102
	v_fma_f32 v103, v49, v49, v103
	v_fma_f32 v104, v50, v50, v104
	v_fma_f32 v105, v51, v51, v105
	s_waitcnt vmcnt(10)
	v_fma_f32 v102, v52, v52, v102
	v_fma_f32 v103, v53, v53, v103
	v_fma_f32 v104, v54, v54, v104
	v_fma_f32 v105, v55, v55, v105
	s_waitcnt vmcnt(9)
	v_fma_f32 v102, v56, v56, v102
	v_fma_f32 v103, v57, v57, v103
	v_fma_f32 v104, v58, v58, v104
	v_fma_f32 v105, v59, v59, v105
	s_waitcnt vmcnt(8)
	v_fma_f32 v102, v60, v60, v102
	v_fma_f32 v103, v61, v61, v103
	v_fma_f32 v104, v62, v62, v104
	v_fma_f32 v105, v63, v63, v105
	v_add_f32_e32 v102, v102, v103
	v_add_f32_e32 v104, v104, v105
	v_add_f32_e32 v102, v102, v104
	s_nop 1
	v_add_f32_dpp v102, v102, v102 quad_perm:[1,0,3,2] row_mask:0xf bank_mask:0xf
	s_nop 1
	v_add_f32_dpp v102, v102, v102 quad_perm:[2,3,0,1] row_mask:0xf bank_mask:0xf
	s_nop 1
	v_add_f32_dpp v102, v102, v102 row_half_mirror row_mask:0xf bank_mask:0xf
	s_nop 1
	v_add_f32_dpp v102, v102, v102 row_mirror row_mask:0xf bank_mask:0xf
	s_nop 1
	v_readlane_b32 s8, v102, 0
	v_readlane_b32 s9, v102, 16
	v_readlane_b32 vcc_lo, v102, 32
	v_readlane_b32 vcc_hi, v102, 48
	v_mov_b32_e32 v100, s8
	v_add_f32_e32 v100, s9, v100
	v_add_f32_e32 v100, vcc_lo, v100
	v_add_f32_e32 v100, vcc_hi, v100
	v_fmamk_f32 v100, v100, 0x3a000000, v101
	v_rsq_f32_e32 v100, v100
	s_nop 0
	v_mul_f32_e32 v96, v100, v32
	v_mul_f32_e32 v97, v100, v33
	v_mul_f32_e32 v98, v100, v34
	v_mul_f32_e32 v99, v100, v35
	v_mul_f32_e32 v96, v96, v0
	v_mul_f32_e32 v97, v97, v1
	v_mul_f32_e32 v98, v98, v2
	v_mul_f32_e32 v99, v99, v3
	v_cvt_pk_bf16_f32 v32, v96, v97
	v_cvt_pk_bf16_f32 v33, v98, v99
	global_store_dwordx2 v106, v[32:33], s[10:11] offset:0
	v_mul_f32_e32 v96, v100, v36
	v_mul_f32_e32 v97, v100, v37
	v_mul_f32_e32 v98, v100, v38
	v_mul_f32_e32 v99, v100, v39
	v_mul_f32_e32 v96, v96, v4
	v_mul_f32_e32 v97, v97, v5
	v_mul_f32_e32 v98, v98, v6
	v_mul_f32_e32 v99, v99, v7
	v_cvt_pk_bf16_f32 v36, v96, v97
	v_cvt_pk_bf16_f32 v37, v98, v99
	global_store_dwordx2 v106, v[36:37], s[10:11] offset:512
	v_mul_f32_e32 v96, v100, v40
	v_mul_f32_e32 v97, v100, v41
	v_mul_f32_e32 v98, v100, v42
	v_mul_f32_e32 v99, v100, v43
	v_mul_f32_e32 v96, v96, v8
	v_mul_f32_e32 v97, v97, v9
	v_mul_f32_e32 v98, v98, v10
	v_mul_f32_e32 v99, v99, v11
	v_cvt_pk_bf16_f32 v40, v96, v97
	v_cvt_pk_bf16_f32 v41, v98, v99
	global_store_dwordx2 v106, v[40:41], s[10:11] offset:1024
	v_mul_f32_e32 v96, v100, v44
	v_mul_f32_e32 v97, v100, v45
	v_mul_f32_e32 v98, v100, v46
	v_mul_f32_e32 v99, v100, v47
	v_mul_f32_e32 v96, v96, v12
	v_mul_f32_e32 v97, v97, v13
	v_mul_f32_e32 v98, v98, v14
	v_mul_f32_e32 v99, v99, v15
	v_cvt_pk_bf16_f32 v44, v96, v97
; __device__ __forceinline__ unsigned pk2(float lo, float hi) { return pg8::cvt_pk_bf16(lo, hi); }
; #define X_IN INP(0)
; __global__ void __launch_bounds__(512, 2) fwd(Params P) {
;     ...
;         for (int m = gw; m < T_TOK; m += NGW) {
;             const f32x4* xr = (const f32x4*)(X_IN + (size_t)m * DM) + lane; f32x4 v[8]; float s = 0.f;
; #pragma unroll
;             for (int j = 0; j < 8; ++j) { v[j] = __builtin_nontemporal_load(&xr[64 * j]); s += (v[j].x * v[j].x + v[j].y * v[j].y) + (v[j].z * v[j].z + v[j].w * v[j].w); }
;             const float rs = __builtin_amdgcn_rsqf(wave_sum(s) * (1.f / DM) + EPS);
;             u32x2* o = (u32x2*)(XN + (size_t)m * DM) + lane;
; #pragma unroll
;             for (int j = 0; j < 8; ++j) { const f32x4 g = gr[64 * j]; u32x2 w; w.x = pk2(v[j].x * rs * g.x, v[j].y * rs * g.y); w.y = pk2(v[j].z * rs * g.z, v[j].w * rs * g.w); o[64 * j] = w; }
;         }
	v_cvt_pk_bf16_f32 v45, v98, v99
	global_store_dwordx2 v106, v[44:45], s[10:11] offset:1536
	v_mul_f32_e32 v96, v100, v48
	v_mul_f32_e32 v97, v100, v49
	v_mul_f32_e32 v98, v100, v50
	v_mul_f32_e32 v99, v100, v51
	v_mul_f32_e32 v96, v96, v16
	v_mul_f32_e32 v97, v97, v17
	v_mul_f32_e32 v98, v98, v18
	v_mul_f32_e32 v99, v99, v19
	v_cvt_pk_bf16_f32 v48, v96, v97
	v_cvt_pk_bf16_f32 v49, v98, v99
	global_store_dwordx2 v106, v[48:49], s[10:11] offset:2048
	v_mul_f32_e32 v96, v100, v52
	v_mul_f32_e32 v97, v100, v53
	v_mul_f32_e32 v98, v100, v54
	v_mul_f32_e32 v99, v100, v55
	v_mul_f32_e32 v96, v96, v20
	v_mul_f32_e32 v97, v97, v21
	v_mul_f32_e32 v98, v98, v22
	v_mul_f32_e32 v99, v99, v23
	v_cvt_pk_bf16_f32 v52, v96, v97
	v_cvt_pk_bf16_f32 v53, v98, v99
	global_store_dwordx2 v106, v[52:53], s[10:11] offset:2560
	v_mul_f32_e32 v96, v100, v56
	v_mul_f32_e32 v97, v100, v57
	v_mul_f32_e32 v98, v100, v58
	v_mul_f32_e32 v99, v100, v59
	v_mul_f32_e32 v96, v96, v24
	v_mul_f32_e32 v97, v97, v25
	v_mul_f32_e32 v98, v98, v26
	v_mul_f32_e32 v99, v99, v27
	v_cvt_pk_bf16_f32 v56, v96, v97
	v_cvt_pk_bf16_f32 v57, v98, v99
	global_store_dwordx2 v106, v[56:57], s[10:11] offset:3072
	v_mul_f32_e32 v96, v100, v60
	v_mul_f32_e32 v97, v100, v61
	v_mul_f32_e32 v98, v100, v62
	v_mul_f32_e32 v99, v100, v63
	v_mul_f32_e32 v96, v96, v28
	v_mul_f32_e32 v97, v97, v29
	v_mul_f32_e32 v98, v98, v30
	v_mul_f32_e32 v99, v99, v31
	v_cvt_pk_bf16_f32 v60, v96, v97
	v_cvt_pk_bf16_f32 v61, v98, v99
	global_store_dwordx2 v106, v[60:61], s[10:11] offset:3584
.Lp0n_loop:
	s_lshl_b32 s13, s12, 12
	s_add_u32 s10, s6, s13
	s_addc_u32 s11, s7, 0
	s_add_i32 s13, s12, s82
	s_cmpk_gt_i32 s13, 0x7fff
	s_cbranch_scc1 .Lp0n_tail_b
	s_mov_b32 s12, s13
	s_lshl_b32 s13, s13, 13
	s_add_u32 s8, s4, s13
	s_addc_u32 s9, s5, 0
	global_load_dwordx4 v[32:35], v166, s[8:9] offset:-4096 nt
	global_load_dwordx4 v[36:39], v166, s[8:9] offset:-3072 nt
	global_load_dwordx4 v[40:43], v166, s[8:9] offset:-2048 nt
	global_load_dwordx4 v[44:47], v166, s[8:9] offset:-1024 nt
	global_load_dwordx4 v[48:51], v166, s[8:9] offset:0 nt
	global_load_dwordx4 v[52:55], v166, s[8:9] offset:1024 nt
	global_load_dwordx4 v[56:59], v166, s[8:9] offset:2048 nt
	global_load_dwordx4 v[60:63], v166, s[8:9] offset:3072 nt
	s_waitcnt vmcnt(23)
	v_mul_f32_e32 v102, v64, v64
	v_mul_f32_e32 v103, v65, v65
	v_mul_f32_e32 v104, v66, v66
	v_mul_f32_e32 v105, v67, v67
	s_waitcnt vmcnt(22)
	v_fma_f32 v102, v68, v68, v102
	v_fma_f32 v103, v69, v69, v103
	v_fma_f32 v104, v70, v70, v104
	v_fma_f32 v105, v71, v71, v105
	s_waitcnt vmcnt(21)
	v_fma_f32 v102, v72, v72, v102
	v_fma_f32 v103, v73, v73, v103
	v_fma_f32 v104, v74, v74, v104
	v_fma_f32 v105, v75, v75, v105
	s_waitcnt vmcnt(20)
	v_fma_f32 v102, v76, v76, v102
	v_fma_f32 v103, v77, v77, v103
	v_fma_f32 v104, v78, v78, v104
	v_fma_f32 v105, v79, v79, v105
	s_waitcnt vmcnt(19)
	v_fma_f32 v102, v80, v80, v102
	v_fma_f32 v103, v81, v81, v103
	v_fma_f32 v104, v82, v82, v104
	v_fma_f32 v105, v83, v83, v105
	s_waitcnt vmcnt(18)
	v_fma_f32 v102, v84, v84, v102
	v_fma_f32 v103, v85, v85, v103
	v_fma_f32 v104, v86, v86, v104
	v_fma_f32 v105, v87, v87, v105
	s_waitcnt vmcnt(17)
	v_fma_f32 v102, v88, v88, v102
	v_fma_f32 v103, v89, v89, v103
	v_fma_f32 v104, v90, v90, v104
	v_fma_f32 v105, v91, v91, v105
	s_waitcnt vmcnt(16)
	v_fma_f32 v102, v92, v92, v102
	v_fma_f32 v103, v93, v93, v103
	v_fma_f32 v104, v94, v94, v104
	v_fma_f32 v105, v95, v95, v105
	v_add_f32_e32 v102, v102, v103
	v_add_f32_e32 v104, v104, v105
	v_add_f32_e32 v102, v102, v104
	s_nop 1
	v_add_f32_dpp v102, v102, v102 quad_perm:[1,0,3,2] row_mask:0xf bank_mask:0xf
	s_nop 1
	v_add_f32_dpp v102, v102, v102 quad_perm:[2,3,0,1] row_mask:0xf bank_mask:0xf
	s_nop 1
	v_add_f32_dpp v102, v102, v102 row_half_mirror row_mask:0xf bank_mask:0xf
	s_nop 1
	v_add_f32_dpp v102, v102, v102 row_mirror row_mask:0xf bank_mask:0xf
	s_nop 1
	v_readlane_b32 s8, v102, 0
	v_readlane_b32 s9, v102, 16
	v_readlane_b32 vcc_lo, v102, 32
	v_readlane_b32 vcc_hi, v102, 48
	v_mov_b32_e32 v100, s8
	v_add_f32_e32 v100, s9, v100
	v_add_f32_e32 v100, vcc_lo, v100
	v_add_f32_e32 v100, vcc_hi, v100
	v_fmamk_f32 v100, v100, 0x3a000000, v101
	v_rsq_f32_e32 v100, v100
	s_nop 0
	v_mul_f32_e32 v96, v100, v64
	v_mul_f32_e32 v97, v100, v65
	v_mul_f32_e32 v98, v100, v66
	v_mul_f32_e32 v99, v100, v67
	v_mul_f32_e32 v96, v96, v0
	v_mul_f32_e32 v97, v97, v1
	v_mul_f32_e32 v98, v98, v2
	v_mul_f32_e32 v99, v99, v3
	v_cvt_pk_bf16_f32 v64, v96, v97
	v_cvt_pk_bf16_f32 v65, v98, v99
	global_store_dwordx2 v106, v[64:65], s[10:11] offset:0
	v_mul_f32_e32 v96, v100, v68
	v_mul_f32_e32 v97, v100, v69
	v_mul_f32_e32 v98, v100, v70
	v_mul_f32_e32 v99, v100, v71
	v_mul_f32_e32 v96, v96, v4
	v_mul_f32_e32 v97, v97, v5
	v_mul_f32_e32 v98, v98, v6
	v_mul_f32_e32 v99, v99, v7
	v_cvt_pk_bf16_f32 v68, v96, v97
	v_cvt_pk_bf16_f32 v69, v98, v99
	global_store_dwordx2 v106, v[68:69], s[10:11] offset:512
	v_mul_f32_e32 v96, v100, v72
	v_mul_f32_e32 v97, v100, v73
	v_mul_f32_e32 v98, v100, v74
	v_mul_f32_e32 v99, v100, v75
	v_mul_f32_e32 v96, v96, v8
	v_mul_f32_e32 v97, v97, v9
	v_mul_f32_e32 v98, v98, v10
	v_mul_f32_e32 v99, v99, v11
	v_cvt_pk_bf16_f32 v72, v96, v97
	v_cvt_pk_bf16_f32 v73, v98, v99
	global_store_dwordx2 v106, v[72:73], s[10:11] offset:1024
	v_mul_f32_e32 v96, v100, v76
	v_mul_f32_e32 v97, v100, v77
	v_mul_f32_e32 v98, v100, v78
	v_mul_f32_e32 v99, v100, v79
	v_mul_f32_e32 v96, v96, v12
	v_mul_f32_e32 v97, v97, v13
	v_mul_f32_e32 v98, v98, v14
	v_mul_f32_e32 v99, v99, v15
	v_cvt_pk_bf16_f32 v76, v96, v97
	v_cvt_pk_bf16_f32 v77, v98, v99
	global_store_dwordx2 v106, v[76:77], s[10:11] offset:1536
; __device__ __forceinline__ unsigned pk2(float lo, float hi) { return pg8::cvt_pk_bf16(lo, hi); }
; #define X_IN INP(0)
; __global__ void __launch_bounds__(512, 2) fwd(Params P) {
;     ...
;         for (int m = gw; m < T_TOK; m += NGW) {
;             const f32x4* xr = (const f32x4*)(X_IN + (size_t)m * DM) + lane; f32x4 v[8]; float s = 0.f;
; #pragma unroll
;             for (int j = 0; j < 8; ++j) { v[j] = __builtin_nontemporal_load(&xr[64 * j]); s += (v[j].x * v[j].x + v[j].y * v[j].y) + (v[j].z * v[j].z + v[j].w * v[j].w); }
;             const float rs = __builtin_amdgcn_rsqf(wave_sum(s) * (1.f / DM) + EPS);
;             u32x2* o = (u32x2*)(XN + (size_t)m * DM) + lane;
; #pragma unroll
;             for (int j = 0; j < 8; ++j) { const f32x4 g = gr[64 * j]; u32x2 w; w.x = pk2(v[j].x * rs * g.x, v[j].y * rs * g.y); w.y = pk2(v[j].z * rs * g.z, v[j].w * rs * g.w); o[64 * j] = w; }
;         }
	v_mul_f32_e32 v96, v100, v80
	v_mul_f32_e32 v97, v100, v81
	v_mul_f32_e32 v98, v100, v82
	v_mul_f32_e32 v99, v100, v83
	v_mul_f32_e32 v96, v96, v16
	v_mul_f32_e32 v97, v97, v17
	v_mul_f32_e32 v98, v98, v18
	v_mul_f32_e32 v99, v99, v19
	v_cvt_pk_bf16_f32 v80, v96, v97
	v_cvt_pk_bf16_f32 v81, v98, v99
	global_store_dwordx2 v106, v[80:81], s[10:11] offset:2048
	v_mul_f32_e32 v96, v100, v84
	v_mul_f32_e32 v97, v100, v85
	v_mul_f32_e32 v98, v100, v86
	v_mul_f32_e32 v99, v100, v87
	v_mul_f32_e32 v96, v96, v20
	v_mul_f32_e32 v97, v97, v21
	v_mul_f32_e32 v98, v98, v22
	v_mul_f32_e32 v99, v99, v23
	v_cvt_pk_bf16_f32 v84, v96, v97
	v_cvt_pk_bf16_f32 v85, v98, v99
	global_store_dwordx2 v106, v[84:85], s[10:11] offset:2560
	v_mul_f32_e32 v96, v100, v88
	v_mul_f32_e32 v97, v100, v89
	v_mul_f32_e32 v98, v100, v90
	v_mul_f32_e32 v99, v100, v91
	v_mul_f32_e32 v96, v96, v24
	v_mul_f32_e32 v97, v97, v25
	v_mul_f32_e32 v98, v98, v26
	v_mul_f32_e32 v99, v99, v27
	v_cvt_pk_bf16_f32 v88, v96, v97
	v_cvt_pk_bf16_f32 v89, v98, v99
	global_store_dwordx2 v106, v[88:89], s[10:11] offset:3072
	v_mul_f32_e32 v96, v100, v92
	v_mul_f32_e32 v97, v100, v93
	v_mul_f32_e32 v98, v100, v94
	v_mul_f32_e32 v99, v100, v95
	v_mul_f32_e32 v96, v96, v28
	v_mul_f32_e32 v97, v97, v29
	v_mul_f32_e32 v98, v98, v30
	v_mul_f32_e32 v99, v99, v31
	v_cvt_pk_bf16_f32 v92, v96, v97
	v_cvt_pk_bf16_f32 v93, v98, v99
	global_store_dwordx2 v106, v[92:93], s[10:11] offset:3584
	s_lshl_b32 s13, s12, 12
	s_add_u32 s10, s6, s13
	s_addc_u32 s11, s7, 0
	s_add_i32 s13, s12, s82
	s_cmpk_gt_i32 s13, 0x7fff
	s_cbranch_scc1 .Lp0n_tail_a
	s_mov_b32 s12, s13
	s_lshl_b32 s13, s13, 13
	s_add_u32 s8, s4, s13
	s_addc_u32 s9, s5, 0
	global_load_dwordx4 v[64:67], v166, s[8:9] offset:-4096 nt
	global_load_dwordx4 v[68:71], v166, s[8:9] offset:-3072 nt
	global_load_dwordx4 v[72:75], v166, s[8:9] offset:-2048 nt
	global_load_dwordx4 v[76:79], v166, s[8:9] offset:-1024 nt
	global_load_dwordx4 v[80:83], v166, s[8:9] offset:0 nt
	global_load_dwordx4 v[84:87], v166, s[8:9] offset:1024 nt
	global_load_dwordx4 v[88:91], v166, s[8:9] offset:2048 nt
	global_load_dwordx4 v[92:95], v166, s[8:9] offset:3072 nt
	s_waitcnt vmcnt(23)
	v_mul_f32_e32 v102, v32, v32
	v_mul_f32_e32 v103, v33, v33
	v_mul_f32_e32 v104, v34, v34
	v_mul_f32_e32 v105, v35, v35
	s_waitcnt vmcnt(22)
	v_fma_f32 v102, v36, v36, v102
	v_fma_f32 v103, v37, v37, v103
	v_fma_f32 v104, v38, v38, v104
	v_fma_f32 v105, v39, v39, v105
	s_waitcnt vmcnt(21)
	v_fma_f32 v102, v40, v40, v102
	v_fma_f32 v103, v41, v41, v103
	v_fma_f32 v104, v42, v42, v104
	v_fma_f32 v105, v43, v43, v105
	s_waitcnt vmcnt(20)
	v_fma_f32 v102, v44, v44, v102
	v_fma_f32 v103, v45, v45, v103
	v_fma_f32 v104, v46, v46, v104
	v_fma_f32 v105, v47, v47, v105
	s_waitcnt vmcnt(19)
	v_fma_f32 v102, v48, v48, v102
	v_fma_f32 v103, v49, v49, v103
	v_fma_f32 v104, v50, v50, v104
	v_fma_f32 v105, v51, v51, v105
	s_waitcnt vmcnt(18)
	v_fma_f32 v102, v52, v52, v102
	v_fma_f32 v103, v53, v53, v103
	v_fma_f32 v104, v54, v54, v104
	v_fma_f32 v105, v55, v55, v105
	s_waitcnt vmcnt(17)
	v_fma_f32 v102, v56, v56, v102
	v_fma_f32 v103, v57, v57, v103
	v_fma_f32 v104, v58, v58, v104
	v_fma_f32 v105, v59, v59, v105
	s_waitcnt vmcnt(16)
	v_fma_f32 v102, v60, v60, v102
	v_fma_f32 v103, v61, v61, v103
	v_fma_f32 v104, v62, v62, v104
	v_fma_f32 v105, v63, v63, v105
	v_add_f32_e32 v102, v102, v103
	v_add_f32_e32 v104, v104, v105
	v_add_f32_e32 v102, v102, v104
	s_nop 1
	v_add_f32_dpp v102, v102, v102 quad_perm:[1,0,3,2] row_mask:0xf bank_mask:0xf
	s_nop 1
	v_add_f32_dpp v102, v102, v102 quad_perm:[2,3,0,1] row_mask:0xf bank_mask:0xf
	s_nop 1
	v_add_f32_dpp v102, v102, v102 row_half_mirror row_mask:0xf bank_mask:0xf
	s_nop 1
	v_add_f32_dpp v102, v102, v102 row_mirror row_mask:0xf bank_mask:0xf
	s_nop 1
	v_readlane_b32 s8, v102, 0
	v_readlane_b32 s9, v102, 16
	v_readlane_b32 vcc_lo, v102, 32
	v_readlane_b32 vcc_hi, v102, 48
	v_mov_b32_e32 v100, s8
	v_add_f32_e32 v100, s9, v100
	v_add_f32_e32 v100, vcc_lo, v100
	v_add_f32_e32 v100, vcc_hi, v100
	v_fmamk_f32 v100, v100, 0x3a000000, v101
	v_rsq_f32_e32 v100, v100
	s_nop 0
	v_mul_f32_e32 v96, v100, v32
	v_mul_f32_e32 v97, v100, v33
	v_mul_f32_e32 v98, v100, v34
	v_mul_f32_e32 v99, v100, v35
	v_mul_f32_e32 v96, v96, v0
	v_mul_f32_e32 v97, v97, v1
	v_mul_f32_e32 v98, v98, v2
	v_mul_f32_e32 v99, v99, v3
	v_cvt_pk_bf16_f32 v32, v96, v97
	v_cvt_pk_bf16_f32 v33, v98, v99
	global_store_dwordx2 v106, v[32:33], s[10:11] offset:0
	v_mul_f32_e32 v96, v100, v36
	v_mul_f32_e32 v97, v100, v37
	v_mul_f32_e32 v98, v100, v38
	v_mul_f32_e32 v99, v100, v39
	v_mul_f32_e32 v96, v96, v4
	v_mul_f32_e32 v97, v97, v5
	v_mul_f32_e32 v98, v98, v6
	v_mul_f32_e32 v99, v99, v7
	v_cvt_pk_bf16_f32 v36, v96, v97
	v_cvt_pk_bf16_f32 v37, v98, v99
	global_store_dwordx2 v106, v[36:37], s[10:11] offset:512
	v_mul_f32_e32 v96, v100, v40
	v_mul_f32_e32 v97, v100, v41
	v_mul_f32_e32 v98, v100, v42
	v_mul_f32_e32 v99, v100, v43
	v_mul_f32_e32 v96, v96, v8
	v_mul_f32_e32 v97, v97, v9
	v_mul_f32_e32 v98, v98, v10
	v_mul_f32_e32 v99, v99, v11
	v_cvt_pk_bf16_f32 v40, v96, v97
	v_cvt_pk_bf16_f32 v41, v98, v99
	global_store_dwordx2 v106, v[40:41], s[10:11] offset:1024
	v_mul_f32_e32 v96, v100, v44
	v_mul_f32_e32 v97, v100, v45
	v_mul_f32_e32 v98, v100, v46
	v_mul_f32_e32 v99, v100, v47
	v_mul_f32_e32 v96, v96, v12
	v_mul_f32_e32 v97, v97, v13
	v_mul_f32_e32 v98, v98, v14
	v_mul_f32_e32 v99, v99, v15
	v_cvt_pk_bf16_f32 v44, v96, v97
	v_cvt_pk_bf16_f32 v45, v98, v99
	global_store_dwordx2 v106, v[44:45], s[10:11] offset:1536
	v_mul_f32_e32 v96, v100, v48
	v_mul_f32_e32 v97, v100, v49
	v_mul_f32_e32 v98, v100, v50
	v_mul_f32_e32 v99, v100, v51
	v_mul_f32_e32 v96, v96, v16
	v_mul_f32_e32 v97, v97, v17
	v_mul_f32_e32 v98, v98, v18
	v_mul_f32_e32 v99, v99, v19
	v_cvt_pk_bf16_f32 v48, v96, v97
	v_cvt_pk_bf16_f32 v49, v98, v99
	global_store_dwordx2 v106, v[48:49], s[10:11] offset:2048
	v_mul_f32_e32 v96, v100, v52
	v_mul_f32_e32 v97, v100, v53
	v_mul_f32_e32 v98, v100, v54
	v_mul_f32_e32 v99, v100, v55
	v_mul_f32_e32 v96, v96, v20
	v_mul_f32_e32 v97, v97, v21
	v_mul_f32_e32 v98, v98, v22
	v_mul_f32_e32 v99, v99, v23
	v_cvt_pk_bf16_f32 v52, v96, v97
	v_cvt_pk_bf16_f32 v53, v98, v99
	global_store_dwordx2 v106, v[52:53], s[10:11] offset:2560
	v_mul_f32_e32 v96, v100, v56
	v_mul_f32_e32 v97, v100, v57
	v_mul_f32_e32 v98, v100, v58
	v_mul_f32_e32 v99, v100, v59
	v_mul_f32_e32 v96, v96, v24
	v_mul_f32_e32 v97, v97, v25
	v_mul_f32_e32 v98, v98, v26
	v_mul_f32_e32 v99, v99, v27
	v_cvt_pk_bf16_f32 v56, v96, v97
	v_cvt_pk_bf16_f32 v57, v98, v99
	global_store_dwordx2 v106, v[56:57], s[10:11] offset:3072
	v_mul_f32_e32 v96, v100, v60
	v_mul_f32_e32 v97, v100, v61
	v_mul_f32_e32 v98, v100, v62
	v_mul_f32_e32 v99, v100, v63
	v_mul_f32_e32 v96, v96, v28
	v_mul_f32_e32 v97, v97, v29
	v_mul_f32_e32 v98, v98, v30
	v_mul_f32_e32 v99, v99, v31
	v_cvt_pk_bf16_f32 v60, v96, v97
	v_cvt_pk_bf16_f32 v61, v98, v99
	global_store_dwordx2 v106, v[60:61], s[10:11] offset:3584
	s_branch .Lp0n_loop
; __device__ __forceinline__ unsigned pk2(float lo, float hi) { return pg8::cvt_pk_bf16(lo, hi); }
; #define X_IN INP(0)
; __global__ void __launch_bounds__(512, 2) fwd(Params P) {
;     ...
;             const f32x4* xr = (const f32x4*)(X_IN + (size_t)m * DM) + lane; f32x4 v[8]; float s = 0.f;
; #pragma unroll
;             for (int j = 0; j < 8; ++j) { v[j] = __builtin_nontemporal_load(&xr[64 * j]); s += (v[j].x * v[j].x + v[j].y * v[j].y) + (v[j].z * v[j].z + v[j].w * v[j].w); }
;             const float rs = __builtin_amdgcn_rsqf(wave_sum(s) * (1.f / DM) + EPS);
;             u32x2* o = (u32x2*)(XN + (size_t)m * DM) + lane;
; #pragma unroll
;             for (int j = 0; j < 8; ++j) { const f32x4 g = gr[64 * j]; u32x2 w; w.x = pk2(v[j].x * rs * g.x, v[j].y * rs * g.y); w.y = pk2(v[j].z * rs * g.z, v[j].w * rs * g.w); o[64 * j] = w; }
.Lp0n_tail_a:
	s_waitcnt vmcnt(15)
	v_mul_f32_e32 v102, v32, v32
	v_mul_f32_e32 v103, v33, v33
	v_mul_f32_e32 v104, v34, v34
	v_mul_f32_e32 v105, v35, v35
	s_waitcnt vmcnt(14)
	v_fma_f32 v102, v36, v36, v102
	v_fma_f32 v103, v37, v37, v103
	v_fma_f32 v104, v38, v38, v104
	v_fma_f32 v105, v39, v39, v105
	s_waitcnt vmcnt(13)
	v_fma_f32 v102, v40, v40, v102
	v_fma_f32 v103, v41, v41, v103
	v_fma_f32 v104, v42, v42, v104
	v_fma_f32 v105, v43, v43, v105
	s_waitcnt vmcnt(12)
	v_fma_f32 v102, v44, v44, v102
	v_fma_f32 v103, v45, v45, v103
	v_fma_f32 v104, v46, v46, v104
	v_fma_f32 v105, v47, v47, v105
	s_waitcnt vmcnt(11)
	v_fma_f32 v102, v48, v48, v102
	v_fma_f32 v103, v49, v49, v103
	v_fma_f32 v104, v50, v50, v104
	v_fma_f32 v105, v51, v51, v105
	s_waitcnt vmcnt(10)
	v_fma_f32 v102, v52, v52, v102
	v_fma_f32 v103, v53, v53, v103
	v_fma_f32 v104, v54, v54, v104
	v_fma_f32 v105, v55, v55, v105
	s_waitcnt vmcnt(9)
	v_fma_f32 v102, v56, v56, v102
	v_fma_f32 v103, v57, v57, v103
	v_fma_f32 v104, v58, v58, v104
	v_fma_f32 v105, v59, v59, v105
	s_waitcnt vmcnt(8)
	v_fma_f32 v102, v60, v60, v102
	v_fma_f32 v103, v61, v61, v103
	v_fma_f32 v104, v62, v62, v104
	v_fma_f32 v105, v63, v63, v105
	v_add_f32_e32 v102, v102, v103
	v_add_f32_e32 v104, v104, v105
	v_add_f32_e32 v102, v102, v104
	s_nop 1
	v_add_f32_dpp v102, v102, v102 quad_perm:[1,0,3,2] row_mask:0xf bank_mask:0xf
	s_nop 1
	v_add_f32_dpp v102, v102, v102 quad_perm:[2,3,0,1] row_mask:0xf bank_mask:0xf
	s_nop 1
	v_add_f32_dpp v102, v102, v102 row_half_mirror row_mask:0xf bank_mask:0xf
	s_nop 1
	v_add_f32_dpp v102, v102, v102 row_mirror row_mask:0xf bank_mask:0xf
	s_nop 1
	v_readlane_b32 s8, v102, 0
	v_readlane_b32 s9, v102, 16
	v_readlane_b32 vcc_lo, v102, 32
	v_readlane_b32 vcc_hi, v102, 48
	v_mov_b32_e32 v100, s8
	v_add_f32_e32 v100, s9, v100
	v_add_f32_e32 v100, vcc_lo, v100
	v_add_f32_e32 v100, vcc_hi, v100
	v_fmamk_f32 v100, v100, 0x3a000000, v101
	v_rsq_f32_e32 v100, v100
	s_nop 0
	v_mul_f32_e32 v96, v100, v32
	v_mul_f32_e32 v97, v100, v33
	v_mul_f32_e32 v98, v100, v34
	v_mul_f32_e32 v99, v100, v35
	v_mul_f32_e32 v96, v96, v0
	v_mul_f32_e32 v97, v97, v1
	v_mul_f32_e32 v98, v98, v2
	v_mul_f32_e32 v99, v99, v3
	v_cvt_pk_bf16_f32 v32, v96, v97
	v_cvt_pk_bf16_f32 v33, v98, v99
	global_store_dwordx2 v106, v[32:33], s[10:11] offset:0
	v_mul_f32_e32 v96, v100, v36
	v_mul_f32_e32 v97, v100, v37
	v_mul_f32_e32 v98, v100, v38
	v_mul_f32_e32 v99, v100, v39
	v_mul_f32_e32 v96, v96, v4
	v_mul_f32_e32 v97, v97, v5
	v_mul_f32_e32 v98, v98, v6
	v_mul_f32_e32 v99, v99, v7
	v_cvt_pk_bf16_f32 v36, v96, v97
	v_cvt_pk_bf16_f32 v37, v98, v99
	global_store_dwordx2 v106, v[36:37], s[10:11] offset:512
	v_mul_f32_e32 v96, v100, v40
	v_mul_f32_e32 v97, v100, v41
	v_mul_f32_e32 v98, v100, v42
	v_mul_f32_e32 v99, v100, v43
	v_mul_f32_e32 v96, v96, v8
	v_mul_f32_e32 v97, v97, v9
	v_mul_f32_e32 v98, v98, v10
	v_mul_f32_e32 v99, v99, v11
	v_cvt_pk_bf16_f32 v40, v96, v97
	v_cvt_pk_bf16_f32 v41, v98, v99
	global_store_dwordx2 v106, v[40:41], s[10:11] offset:1024
	v_mul_f32_e32 v96, v100, v44
	v_mul_f32_e32 v97, v100, v45
	v_mul_f32_e32 v98, v100, v46
	v_mul_f32_e32 v99, v100, v47
	v_mul_f32_e32 v96, v96, v12
	v_mul_f32_e32 v97, v97, v13
	v_mul_f32_e32 v98, v98, v14
	v_mul_f32_e32 v99, v99, v15
	v_cvt_pk_bf16_f32 v44, v96, v97
	v_cvt_pk_bf16_f32 v45, v98, v99
	global_store_dwordx2 v106, v[44:45], s[10:11] offset:1536
	v_mul_f32_e32 v96, v100, v48
	v_mul_f32_e32 v97, v100, v49
	v_mul_f32_e32 v98, v100, v50
	v_mul_f32_e32 v99, v100, v51
	v_mul_f32_e32 v96, v96, v16
	v_mul_f32_e32 v97, v97, v17
	v_mul_f32_e32 v98, v98, v18
	v_mul_f32_e32 v99, v99, v19
	v_cvt_pk_bf16_f32 v48, v96, v97
	v_cvt_pk_bf16_f32 v49, v98, v99
	global_store_dwordx2 v106, v[48:49], s[10:11] offset:2048
	v_mul_f32_e32 v96, v100, v52
	v_mul_f32_e32 v97, v100, v53
	v_mul_f32_e32 v98, v100, v54
	v_mul_f32_e32 v99, v100, v55
	v_mul_f32_e32 v96, v96, v20
	v_mul_f32_e32 v97, v97, v21
	v_mul_f32_e32 v98, v98, v22
	v_mul_f32_e32 v99, v99, v23
	v_cvt_pk_bf16_f32 v52, v96, v97
	v_cvt_pk_bf16_f32 v53, v98, v99
	global_store_dwordx2 v106, v[52:53], s[10:11] offset:2560
	v_mul_f32_e32 v96, v100, v56
	v_mul_f32_e32 v97, v100, v57
	v_mul_f32_e32 v98, v100, v58
	v_mul_f32_e32 v99, v100, v59
	v_mul_f32_e32 v96, v96, v24
	v_mul_f32_e32 v97, v97, v25
	v_mul_f32_e32 v98, v98, v26
	v_mul_f32_e32 v99, v99, v27
	v_cvt_pk_bf16_f32 v56, v96, v97
	v_cvt_pk_bf16_f32 v57, v98, v99
	global_store_dwordx2 v106, v[56:57], s[10:11] offset:3072
	v_mul_f32_e32 v96, v100, v60
	v_mul_f32_e32 v97, v100, v61
	v_mul_f32_e32 v98, v100, v62
	v_mul_f32_e32 v99, v100, v63
	v_mul_f32_e32 v96, v96, v28
	v_mul_f32_e32 v97, v97, v29
	v_mul_f32_e32 v98, v98, v30
	v_mul_f32_e32 v99, v99, v31
	v_cvt_pk_bf16_f32 v60, v96, v97
	v_cvt_pk_bf16_f32 v61, v98, v99
	global_store_dwordx2 v106, v[60:61], s[10:11] offset:3584
	s_branch .Lp0n_done
; __device__ __forceinline__ unsigned pk2(float lo, float hi) { return pg8::cvt_pk_bf16(lo, hi); }
; #define X_IN INP(0)
; __global__ void __launch_bounds__(512, 2) fwd(Params P) {
;     ...
;             const f32x4* xr = (const f32x4*)(X_IN + (size_t)m * DM) + lane; f32x4 v[8]; float s = 0.f;
; #pragma unroll
;             for (int j = 0; j < 8; ++j) { v[j] = __builtin_nontemporal_load(&xr[64 * j]); s += (v[j].x * v[j].x + v[j].y * v[j].y) + (v[j].z * v[j].z + v[j].w * v[j].w); }
;             const float rs = __builtin_amdgcn_rsqf(wave_sum(s) * (1.f / DM) + EPS);
;             u32x2* o = (u32x2*)(XN + (size_t)m * DM) + lane;
; #pragma unroll
;             for (int j = 0; j < 8; ++j) { const f32x4 g = gr[64 * j]; u32x2 w; w.x = pk2(v[j].x * rs * g.x, v[j].y * rs * g.y); w.y = pk2(v[j].z * rs * g.z, v[j].w * rs * g.w); o[64 * j] = w; }
.Lp0n_tail_b:
	s_waitcnt vmcnt(15)
	v_mul_f32_e32 v102, v64, v64
	v_mul_f32_e32 v103, v65, v65
	v_mul_f32_e32 v104, v66, v66
	v_mul_f32_e32 v105, v67, v67
	s_waitcnt vmcnt(14)
	v_fma_f32 v102, v68, v68, v102
	v_fma_f32 v103, v69, v69, v103
	v_fma_f32 v104, v70, v70, v104
	v_fma_f32 v105, v71, v71, v105
	s_waitcnt vmcnt(13)
	v_fma_f32 v102, v72, v72, v102
	v_fma_f32 v103, v73, v73, v103
	v_fma_f32 v104, v74, v74, v104
	v_fma_f32 v105, v75, v75, v105
	s_waitcnt vmcnt(12)
	v_fma_f32 v102, v76, v76, v102
	v_fma_f32 v103, v77, v77, v103
	v_fma_f32 v104, v78, v78, v104
	v_fma_f32 v105, v79, v79, v105
	s_waitcnt vmcnt(11)
	v_fma_f32 v102, v80, v80, v102
	v_fma_f32 v103, v81, v81, v103
	v_fma_f32 v104, v82, v82, v104
	v_fma_f32 v105, v83, v83, v105
	s_waitcnt vmcnt(10)
	v_fma_f32 v102, v84, v84, v102
	v_fma_f32 v103, v85, v85, v103
	v_fma_f32 v104, v86, v86, v104
	v_fma_f32 v105, v87, v87, v105
	s_waitcnt vmcnt(9)
	v_fma_f32 v102, v88, v88, v102
	v_fma_f32 v103, v89, v89, v103
	v_fma_f32 v104, v90, v90, v104
	v_fma_f32 v105, v91, v91, v105
	s_waitcnt vmcnt(8)
	v_fma_f32 v102, v92, v92, v102
	v_fma_f32 v103, v93, v93, v103
	v_fma_f32 v104, v94, v94, v104
	v_fma_f32 v105, v95, v95, v105
	v_add_f32_e32 v102, v102, v103
	v_add_f32_e32 v104, v104, v105
	v_add_f32_e32 v102, v102, v104
	s_nop 1
	v_add_f32_dpp v102, v102, v102 quad_perm:[1,0,3,2] row_mask:0xf bank_mask:0xf
	s_nop 1
	v_add_f32_dpp v102, v102, v102 quad_perm:[2,3,0,1] row_mask:0xf bank_mask:0xf
	s_nop 1
	v_add_f32_dpp v102, v102, v102 row_half_mirror row_mask:0xf bank_mask:0xf
	s_nop 1
	v_add_f32_dpp v102, v102, v102 row_mirror row_mask:0xf bank_mask:0xf
	s_nop 1
	v_readlane_b32 s8, v102, 0
	v_readlane_b32 s9, v102, 16
	v_readlane_b32 vcc_lo, v102, 32
	v_readlane_b32 vcc_hi, v102, 48
	v_mov_b32_e32 v100, s8
	v_add_f32_e32 v100, s9, v100
	v_add_f32_e32 v100, vcc_lo, v100
	v_add_f32_e32 v100, vcc_hi, v100
	v_fmamk_f32 v100, v100, 0x3a000000, v101
	v_rsq_f32_e32 v100, v100
	s_nop 0
	v_mul_f32_e32 v96, v100, v64
	v_mul_f32_e32 v97, v100, v65
	v_mul_f32_e32 v98, v100, v66
	v_mul_f32_e32 v99, v100, v67
	v_mul_f32_e32 v96, v96, v0
	v_mul_f32_e32 v97, v97, v1
	v_mul_f32_e32 v98, v98, v2
	v_mul_f32_e32 v99, v99, v3
	v_cvt_pk_bf16_f32 v64, v96, v97
	v_cvt_pk_bf16_f32 v65, v98, v99
	global_store_dwordx2 v106, v[64:65], s[10:11] offset:0
	v_mul_f32_e32 v96, v100, v68
	v_mul_f32_e32 v97, v100, v69
	v_mul_f32_e32 v98, v100, v70
	v_mul_f32_e32 v99, v100, v71
	v_mul_f32_e32 v96, v96, v4
	v_mul_f32_e32 v97, v97, v5
	v_mul_f32_e32 v98, v98, v6
	v_mul_f32_e32 v99, v99, v7
	v_cvt_pk_bf16_f32 v68, v96, v97
	v_cvt_pk_bf16_f32 v69, v98, v99
	global_store_dwordx2 v106, v[68:69], s[10:11] offset:512
	v_mul_f32_e32 v96, v100, v72
	v_mul_f32_e32 v97, v100, v73
	v_mul_f32_e32 v98, v100, v74
	v_mul_f32_e32 v99, v100, v75
	v_mul_f32_e32 v96, v96, v8
	v_mul_f32_e32 v97, v97, v9
	v_mul_f32_e32 v98, v98, v10
	v_mul_f32_e32 v99, v99, v11
	v_cvt_pk_bf16_f32 v72, v96, v97
	v_cvt_pk_bf16_f32 v73, v98, v99
	global_store_dwordx2 v106, v[72:73], s[10:11] offset:1024
	v_mul_f32_e32 v96, v100, v76
	v_mul_f32_e32 v97, v100, v77
	v_mul_f32_e32 v98, v100, v78
	v_mul_f32_e32 v99, v100, v79
	v_mul_f32_e32 v96, v96, v12
	v_mul_f32_e32 v97, v97, v13
	v_mul_f32_e32 v98, v98, v14
	v_mul_f32_e32 v99, v99, v15
	v_cvt_pk_bf16_f32 v76, v96, v97
	v_cvt_pk_bf16_f32 v77, v98, v99
	global_store_dwordx2 v106, v[76:77], s[10:11] offset:1536
	v_mul_f32_e32 v96, v100, v80
	v_mul_f32_e32 v97, v100, v81
	v_mul_f32_e32 v98, v100, v82
	v_mul_f32_e32 v99, v100, v83
	v_mul_f32_e32 v96, v96, v16
	v_mul_f32_e32 v97, v97, v17
	v_mul_f32_e32 v98, v98, v18
	v_mul_f32_e32 v99, v99, v19
	v_cvt_pk_bf16_f32 v80, v96, v97
	v_cvt_pk_bf16_f32 v81, v98, v99
	global_store_dwordx2 v106, v[80:81], s[10:11] offset:2048
	v_mul_f32_e32 v96, v100, v84
	v_mul_f32_e32 v97, v100, v85
	v_mul_f32_e32 v98, v100, v86
	v_mul_f32_e32 v99, v100, v87
	v_mul_f32_e32 v96, v96, v20
	v_mul_f32_e32 v97, v97, v21
	v_mul_f32_e32 v98, v98, v22
	v_mul_f32_e32 v99, v99, v23
	v_cvt_pk_bf16_f32 v84, v96, v97
	v_cvt_pk_bf16_f32 v85, v98, v99
	global_store_dwordx2 v106, v[84:85], s[10:11] offset:2560
	v_mul_f32_e32 v96, v100, v88
	v_mul_f32_e32 v97, v100, v89
	v_mul_f32_e32 v98, v100, v90
	v_mul_f32_e32 v99, v100, v91
	v_mul_f32_e32 v96, v96, v24
	v_mul_f32_e32 v97, v97, v25
	v_mul_f32_e32 v98, v98, v26
	v_mul_f32_e32 v99, v99, v27
	v_cvt_pk_bf16_f32 v88, v96, v97
	v_cvt_pk_bf16_f32 v89, v98, v99
	global_store_dwordx2 v106, v[88:89], s[10:11] offset:3072
	v_mul_f32_e32 v96, v100, v92
	v_mul_f32_e32 v97, v100, v93
	v_mul_f32_e32 v98, v100, v94
	v_mul_f32_e32 v99, v100, v95
	v_mul_f32_e32 v96, v96, v28
	v_mul_f32_e32 v97, v97, v29
	v_mul_f32_e32 v98, v98, v30
	v_mul_f32_e32 v99, v99, v31
	v_cvt_pk_bf16_f32 v92, v96, v97
	v_cvt_pk_bf16_f32 v93, v98, v99
	global_store_dwordx2 v106, v[92:93], s[10:11] offset:3584

; __device__ __forceinline__ float bf_lo(unsigned w) { return __uint_as_float(w << 16); }
; __device__ __forceinline__ float bf_hi(unsigned w) { return __uint_as_float(w & 0xffff0000u); }
; #define INP(i) ((const float*)(const GAS float*)KARG(8 * (i)))
; #define X_IN INP(0)
; __global__ void __launch_bounds__(512, 2) fwd(Params P) {
;     ...
;     if (PHASE_MASK & (1 << 6)) {
;         const f32x4* g1 = (const f32x4*)INP(12) + lane; const f32x4* g2 = (const f32x4*)INP(13) + lane;
;         for (int m = gw; m < T_TOK; m += NGW) {
;             const float rsy = __builtin_amdgcn_rsqf(ssq_y[m] * (1.f / DM) + EPS);
;             const f32x4* xr = (const f32x4*)(X_IN + (size_t)m * DM) + lane; const u32x2* yr = (const u32x2*)(YB + (size_t)m * DM) + lane;
;             f32x4* orow = (f32x4*)(OUT_P + (size_t)m * DM) + lane;
;             f32x4 v[8]; float s = 0.f;
; #pragma unroll
;             for (int j = 0; j < 8; ++j) { const f32x4 xv = __builtin_nontemporal_load(&xr[64 * j]); const u32x2 yw = __builtin_nontemporal_load(&yr[64 * j]); const f32x4 g = g1[64 * j];
;                 f32x4 t; t.x = xv.x + bf_lo(yw.x) * rsy * g.x; t.y = xv.y + bf_hi(yw.x) * rsy * g.y; t.z = xv.z + bf_lo(yw.y) * rsy * g.z; t.w = xv.w + bf_hi(yw.y) * rsy * g.w;
;                 v[j] = t; __builtin_nontemporal_store(t, &orow[64 * j]); s += (t.x * t.x + t.y * t.y) + (t.z * t.z + t.w * t.w); }
.LBB0_1226:
	s_or_b64 exec, exec, s[6:7]
	v_readlane_b32 s12, v246, 4
	v_readlane_b32 s13, v246, 5
	s_mov_b64 s[8:9], s[0:1]
	s_mov_b64 s[10:11], s[0:1]
	s_waitcnt lgkmcnt(0)
	v_cndmask_b32_e64 v0, 0, 1, s[12:13]
	v_cmp_ne_u32_e64 s[6:7], 1, v0
	s_andn2_b64 vcc, exec, s[12:13]
	s_barrier
	s_cbranch_vccnz .LBB0_1229
	s_load_dwordx2 s[8:9], s[0:1], 0x0
	s_load_dwordx2 s[10:11], s[0:1], 0xa8
	s_load_dwordx2 s[18:19], s[0:1], 0xa0
	s_load_dwordx2 s[20:21], s[0:1], 0x8
	s_load_dwordx2 s[24:25], s[0:1], 0x60
	s_load_dwordx2 s[26:27], s[0:1], 0x68
	v_mov_b32_e32 v167, 0
	v_lshlrev_b32_e32 v181, 3, v179
	v_mov_b32_e32 v182, 0x358637bd
	s_mov_b32 s30, s80
	s_waitcnt lgkmcnt(0)
	s_add_u32 s8, s8, 0x1000
	s_addc_u32 s9, s9, 0
	s_add_u32 s18, s18, 0x1000
	s_addc_u32 s19, s19, 0
	s_add_u32 s12, s10, 0x40000
	s_addc_u32 s13, s11, 0
	s_add_u32 s14, s10, 0x18000000
	s_addc_u32 s15, s11, 0
	s_add_u32 s16, s10, 0x8000000
	s_addc_u32 s17, s11, 0
	s_add_u32 s22, s10, 0x30000000
	s_addc_u32 s23, s11, 0
	s_add_u32 s28, s24, 0x1000
	s_addc_u32 s29, s25, 0
	s_add_u32 s34, s26, 0x1000
	s_addc_u32 s35, s27, 0
	global_load_dwordx4 v[0:3], v166, s[24:25] offset:0
	global_load_dwordx4 v[4:7], v166, s[24:25] offset:1024
	global_load_dwordx4 v[8:11], v166, s[24:25] offset:2048
	global_load_dwordx4 v[12:15], v166, s[24:25] offset:3072
	global_load_dwordx4 v[16:19], v166, s[28:29] offset:0
	global_load_dwordx4 v[20:23], v166, s[28:29] offset:1024
	global_load_dwordx4 v[24:27], v166, s[28:29] offset:2048
	global_load_dwordx4 v[28:31], v166, s[28:29] offset:3072
	global_load_dwordx4 v[32:35], v166, s[26:27] offset:0
	global_load_dwordx4 v[36:39], v166, s[26:27] offset:1024
	global_load_dwordx4 v[40:43], v166, s[26:27] offset:2048
	global_load_dwordx4 v[44:47], v166, s[26:27] offset:3072
	global_load_dwordx4 v[48:51], v166, s[34:35] offset:0
	global_load_dwordx4 v[52:55], v166, s[34:35] offset:1024
	global_load_dwordx4 v[56:59], v166, s[34:35] offset:2048
	global_load_dwordx4 v[60:63], v166, s[34:35] offset:3072
	s_lshl_b32 s2, s30, 13
	s_add_u32 s24, s8, s2
	s_addc_u32 s25, s9, 0
	s_lshl_b32 s2, s30, 12
	s_add_u32 s26, s14, s2
	s_addc_u32 s27, s15, 0
	s_lshl_b32 s2, s30, 2
	s_add_u32 s28, s12, s2
	s_addc_u32 s29, s13, 0
	s_lshl_b32 s2, s30, 10
	s_add_u32 s34, s20, s2
	s_addc_u32 s35, s21, 0
	global_load_dword v112, v167, s[28:29]
	global_load_dwordx4 v[64:67], v166, s[24:25] offset:-4096 nt
	global_load_dwordx2 v[96:97], v181, s[26:27] offset:0 nt
	global_load_dwordx4 v[68:71], v166, s[24:25] offset:-3072 nt
	global_load_dwordx2 v[98:99], v181, s[26:27] offset:512 nt
	global_load_dwordx4 v[72:75], v166, s[24:25] offset:-2048 nt
	global_load_dwordx2 v[100:101], v181, s[26:27] offset:1024 nt
	global_load_dwordx4 v[76:79], v166, s[24:25] offset:-1024 nt
	global_load_dwordx2 v[102:103], v181, s[26:27] offset:1536 nt
	global_load_dwordx4 v[80:83], v166, s[24:25] offset:0 nt
	global_load_dwordx2 v[104:105], v181, s[26:27] offset:2048 nt
	global_load_dwordx4 v[84:87], v166, s[24:25] offset:1024 nt
	global_load_dwordx2 v[106:107], v181, s[26:27] offset:2560 nt
	global_load_dwordx4 v[88:91], v166, s[24:25] offset:2048 nt
	global_load_dwordx2 v[108:109], v181, s[26:27] offset:3072 nt
	global_load_dwordx4 v[92:95], v166, s[24:25] offset:3072 nt
	global_load_dwordx2 v[110:111], v181, s[26:27] offset:3584 nt
	global_load_dwordx4 v[114:117], v166, s[34:35]
	s_lshl_b32 s2, s30, 13
	s_add_u32 s36, s18, s2
	s_addc_u32 s37, s19, 0
	s_lshl_b32 s2, s30, 12
	s_add_u32 s38, s16, s2
	s_addc_u32 s39, s17, 0
	s_lshl_b32 s2, s30, 9
	s_add_u32 s40, s22, s2
	s_addc_u32 s41, s23, 0
	s_add_i32 s10, s30, s82
	s_cmpk_gt_i32 s10, 0x7fff
	s_cbranch_scc1 .Lp5b_tail_a
	s_lshl_b32 s2, s10, 13
	s_add_u32 s24, s8, s2
	s_addc_u32 s25, s9, 0
	s_lshl_b32 s2, s10, 12
	s_add_u32 s26, s14, s2
	s_addc_u32 s27, s15, 0
	s_lshl_b32 s2, s10, 2
	s_add_u32 s28, s12, s2
	s_addc_u32 s29, s13, 0
	s_lshl_b32 s2, s10, 10
	s_add_u32 s34, s20, s2
	s_addc_u32 s35, s21, 0
	global_load_dword v168, v167, s[28:29]
	global_load_dwordx4 v[118:121], v166, s[24:25] offset:-4096 nt
	global_load_dwordx2 v[150:151], v181, s[26:27] offset:0 nt
	global_load_dwordx4 v[122:125], v166, s[24:25] offset:-3072 nt
	global_load_dwordx2 v[152:153], v181, s[26:27] offset:512 nt
	global_load_dwordx4 v[126:129], v166, s[24:25] offset:-2048 nt
	global_load_dwordx2 v[154:155], v181, s[26:27] offset:1024 nt
	global_load_dwordx4 v[130:133], v166, s[24:25] offset:-1024 nt
	global_load_dwordx2 v[156:157], v181, s[26:27] offset:1536 nt
	global_load_dwordx4 v[134:137], v166, s[24:25] offset:0 nt
	global_load_dwordx2 v[158:159], v181, s[26:27] offset:2048 nt
	global_load_dwordx4 v[138:141], v166, s[24:25] offset:1024 nt
	global_load_dwordx2 v[160:161], v181, s[26:27] offset:2560 nt
	global_load_dwordx4 v[142:145], v166, s[24:25] offset:2048 nt
	global_load_dwordx2 v[162:163], v181, s[26:27] offset:3072 nt
	global_load_dwordx4 v[146:149], v166, s[24:25] offset:3072 nt
	global_load_dwordx2 v[164:165], v181, s[26:27] offset:3584 nt
	global_load_dwordx4 v[170:173], v166, s[34:35]
	s_waitcnt vmcnt(33)
	v_fmamk_f32 v183, v112, 0x3a000000, v182
	v_rsq_f32_e32 v183, v183
	v_lshlrev_b32_e32 v174, 16, v96
	v_and_b32_e32 v175, 0xffff0000, v96
	v_lshlrev_b32_e32 v176, 16, v97
	v_and_b32_e32 v177, 0xffff0000, v97
	v_mul_f32_e32 v174, v183, v174
	v_mul_f32_e32 v175, v183, v175
	v_mul_f32_e32 v176, v183, v176
	v_mul_f32_e32 v177, v183, v177
	v_fma_f32 v64, v0, v174, v64
	v_fma_f32 v65, v1, v175, v65
	v_fma_f32 v66, v2, v176, v66
	v_fma_f32 v67, v3, v177, v67
	global_store_dwordx4 v166, v[64:67], s[36:37] offset:-4096 nt
	v_mul_f32_e32 v185, v64, v64
	v_mul_f32_e32 v186, v65, v65
	v_mul_f32_e32 v187, v66, v66
	v_mul_f32_e32 v188, v67, v67
	s_waitcnt vmcnt(32)
; __device__ __forceinline__ unsigned pk2(float lo, float hi) { return pg8::cvt_pk_bf16(lo, hi); }
; __device__ __forceinline__ float bf_lo(unsigned w) { return __uint_as_float(w << 16); }
; __device__ __forceinline__ float bf_hi(unsigned w) { return __uint_as_float(w & 0xffff0000u); }
; __global__ void __launch_bounds__(512, 2) fwd(Params P) {
;     ...
;             for (int j = 0; j < 8; ++j) { const f32x4 xv = __builtin_nontemporal_load(&xr[64 * j]); const u32x2 yw = __builtin_nontemporal_load(&yr[64 * j]); const f32x4 g = g1[64 * j];
;                 f32x4 t; t.x = xv.x + bf_lo(yw.x) * rsy * g.x; t.y = xv.y + bf_hi(yw.x) * rsy * g.y; t.z = xv.z + bf_lo(yw.y) * rsy * g.z; t.w = xv.w + bf_hi(yw.y) * rsy * g.w;
;                 v[j] = t; __builtin_nontemporal_store(t, &orow[64 * j]); s += (t.x * t.x + t.y * t.y) + (t.z * t.z + t.w * t.w); }
;             const float rs = __builtin_amdgcn_rsqf(wave_sum(s) * (1.f / DM) + EPS);
;             u32x2* o = (u32x2*)(XN + (size_t)m * DM) + lane;
; #pragma unroll
;             for (int j = 0; j < 8; ++j) { const f32x4 g = g2[64 * j]; u32x2 w; w.x = pk2(v[j].x * rs * g.x, v[j].y * rs * g.y); w.y = pk2(v[j].z * rs * g.z, v[j].w * rs * g.w); o[64 * j] = w; }
	v_lshlrev_b32_e32 v174, 16, v98
	v_and_b32_e32 v175, 0xffff0000, v98
	v_lshlrev_b32_e32 v176, 16, v99
	v_and_b32_e32 v177, 0xffff0000, v99
	v_mul_f32_e32 v174, v183, v174
	v_mul_f32_e32 v175, v183, v175
	v_mul_f32_e32 v176, v183, v176
	v_mul_f32_e32 v177, v183, v177
	v_fma_f32 v68, v4, v174, v68
	v_fma_f32 v69, v5, v175, v69
	v_fma_f32 v70, v6, v176, v70
	v_fma_f32 v71, v7, v177, v71
	global_store_dwordx4 v166, v[68:71], s[36:37] offset:-3072 nt
	v_fma_f32 v185, v68, v68, v185
	v_fma_f32 v186, v69, v69, v186
	v_fma_f32 v187, v70, v70, v187
	v_fma_f32 v188, v71, v71, v188
	s_waitcnt vmcnt(31)
	v_lshlrev_b32_e32 v174, 16, v100
	v_and_b32_e32 v175, 0xffff0000, v100
	v_lshlrev_b32_e32 v176, 16, v101
	v_and_b32_e32 v177, 0xffff0000, v101
	v_mul_f32_e32 v174, v183, v174
	v_mul_f32_e32 v175, v183, v175
	v_mul_f32_e32 v176, v183, v176
	v_mul_f32_e32 v177, v183, v177
	v_fma_f32 v72, v8, v174, v72
	v_fma_f32 v73, v9, v175, v73
	v_fma_f32 v74, v10, v176, v74
	v_fma_f32 v75, v11, v177, v75
	global_store_dwordx4 v166, v[72:75], s[36:37] offset:-2048 nt
	v_fma_f32 v185, v72, v72, v185
	v_fma_f32 v186, v73, v73, v186
	v_fma_f32 v187, v74, v74, v187
	v_fma_f32 v188, v75, v75, v188
	s_waitcnt vmcnt(30)
	v_lshlrev_b32_e32 v174, 16, v102
	v_and_b32_e32 v175, 0xffff0000, v102
	v_lshlrev_b32_e32 v176, 16, v103
	v_and_b32_e32 v177, 0xffff0000, v103
	v_mul_f32_e32 v174, v183, v174
	v_mul_f32_e32 v175, v183, v175
	v_mul_f32_e32 v176, v183, v176
	v_mul_f32_e32 v177, v183, v177
	v_fma_f32 v76, v12, v174, v76
	v_fma_f32 v77, v13, v175, v77
	v_fma_f32 v78, v14, v176, v78
	v_fma_f32 v79, v15, v177, v79
	global_store_dwordx4 v166, v[76:79], s[36:37] offset:-1024 nt
	v_fma_f32 v185, v76, v76, v185
	v_fma_f32 v186, v77, v77, v186
	v_fma_f32 v187, v78, v78, v187
	v_fma_f32 v188, v79, v79, v188
	s_waitcnt vmcnt(29)
	v_lshlrev_b32_e32 v174, 16, v104
	v_and_b32_e32 v175, 0xffff0000, v104
	v_lshlrev_b32_e32 v176, 16, v105
	v_and_b32_e32 v177, 0xffff0000, v105
	v_mul_f32_e32 v174, v183, v174
	v_mul_f32_e32 v175, v183, v175
	v_mul_f32_e32 v176, v183, v176
	v_mul_f32_e32 v177, v183, v177
	v_fma_f32 v80, v16, v174, v80
	v_fma_f32 v81, v17, v175, v81
	v_fma_f32 v82, v18, v176, v82
	v_fma_f32 v83, v19, v177, v83
	global_store_dwordx4 v166, v[80:83], s[36:37] offset:0 nt
	v_fma_f32 v185, v80, v80, v185
	v_fma_f32 v186, v81, v81, v186
	v_fma_f32 v187, v82, v82, v187
	v_fma_f32 v188, v83, v83, v188
	s_waitcnt vmcnt(28)
	v_lshlrev_b32_e32 v174, 16, v106
	v_and_b32_e32 v175, 0xffff0000, v106
	v_lshlrev_b32_e32 v176, 16, v107
	v_and_b32_e32 v177, 0xffff0000, v107
	v_mul_f32_e32 v174, v183, v174
	v_mul_f32_e32 v175, v183, v175
	v_mul_f32_e32 v176, v183, v176
	v_mul_f32_e32 v177, v183, v177
	v_fma_f32 v84, v20, v174, v84
	v_fma_f32 v85, v21, v175, v85
	v_fma_f32 v86, v22, v176, v86
	v_fma_f32 v87, v23, v177, v87
	global_store_dwordx4 v166, v[84:87], s[36:37] offset:1024 nt
	v_fma_f32 v185, v84, v84, v185
	v_fma_f32 v186, v85, v85, v186
	v_fma_f32 v187, v86, v86, v187
	v_fma_f32 v188, v87, v87, v188
	s_waitcnt vmcnt(27)
	v_lshlrev_b32_e32 v174, 16, v108
	v_and_b32_e32 v175, 0xffff0000, v108
	v_lshlrev_b32_e32 v176, 16, v109
	v_and_b32_e32 v177, 0xffff0000, v109
	v_mul_f32_e32 v174, v183, v174
	v_mul_f32_e32 v175, v183, v175
	v_mul_f32_e32 v176, v183, v176
	v_mul_f32_e32 v177, v183, v177
	v_fma_f32 v88, v24, v174, v88
	v_fma_f32 v89, v25, v175, v89
	v_fma_f32 v90, v26, v176, v90
	v_fma_f32 v91, v27, v177, v91
	global_store_dwordx4 v166, v[88:91], s[36:37] offset:2048 nt
	v_fma_f32 v185, v88, v88, v185
	v_fma_f32 v186, v89, v89, v186
	v_fma_f32 v187, v90, v90, v187
	v_fma_f32 v188, v91, v91, v188
	s_waitcnt vmcnt(26)
	v_lshlrev_b32_e32 v174, 16, v110
	v_and_b32_e32 v175, 0xffff0000, v110
	v_lshlrev_b32_e32 v176, 16, v111
	v_and_b32_e32 v177, 0xffff0000, v111
	v_mul_f32_e32 v174, v183, v174
	v_mul_f32_e32 v175, v183, v175
	v_mul_f32_e32 v176, v183, v176
	v_mul_f32_e32 v177, v183, v177
	v_fma_f32 v92, v28, v174, v92
	v_fma_f32 v93, v29, v175, v93
	v_fma_f32 v94, v30, v176, v94
	v_fma_f32 v95, v31, v177, v95
	global_store_dwordx4 v166, v[92:95], s[36:37] offset:3072 nt
	v_fma_f32 v185, v92, v92, v185
	v_fma_f32 v186, v93, v93, v186
	v_fma_f32 v187, v94, v94, v187
	v_fma_f32 v188, v95, v95, v188
	v_add_f32_e32 v185, v185, v186
	v_add_f32_e32 v187, v187, v188
	v_add_f32_e32 v185, v185, v187
	s_nop 1
	v_add_f32_dpp v185, v185, v185 quad_perm:[1,0,3,2] row_mask:0xf bank_mask:0xf
	s_nop 1
	v_add_f32_dpp v185, v185, v185 quad_perm:[2,3,0,1] row_mask:0xf bank_mask:0xf
	s_nop 1
	v_add_f32_dpp v185, v185, v185 row_half_mirror row_mask:0xf bank_mask:0xf
	s_nop 1
	v_add_f32_dpp v185, v185, v185 row_mirror row_mask:0xf bank_mask:0xf
	s_nop 1
	v_readlane_b32 s24, v185, 0
	v_readlane_b32 s25, v185, 16
	v_readlane_b32 s26, v185, 32
	v_readlane_b32 s27, v185, 48
	v_mov_b32_e32 v184, s24
	v_add_f32_e32 v184, s25, v184
	v_add_f32_e32 v184, s26, v184
	v_add_f32_e32 v184, s27, v184
	v_fmamk_f32 v184, v184, 0x3a000000, v182
	v_rsq_f32_e32 v184, v184
	s_nop 0
	v_mul_f32_e32 v174, v184, v64
	v_mul_f32_e32 v175, v184, v65
	v_mul_f32_e32 v176, v184, v66
	v_mul_f32_e32 v177, v184, v67
	v_mul_f32_e32 v174, v174, v32
	v_mul_f32_e32 v175, v175, v33
	v_mul_f32_e32 v176, v176, v34
	v_mul_f32_e32 v177, v177, v35
	v_cvt_pk_bf16_f32 v96, v174, v175
	v_cvt_pk_bf16_f32 v97, v176, v177
	global_store_dwordx2 v181, v[96:97], s[38:39] offset:0
	v_mul_f32_e32 v174, v184, v68
	v_mul_f32_e32 v175, v184, v69
	v_mul_f32_e32 v176, v184, v70
	v_mul_f32_e32 v177, v184, v71
	v_mul_f32_e32 v174, v174, v36
	v_mul_f32_e32 v175, v175, v37
	v_mul_f32_e32 v176, v176, v38
	v_mul_f32_e32 v177, v177, v39
	v_cvt_pk_bf16_f32 v98, v174, v175
; __device__ __forceinline__ unsigned pk2(float lo, float hi) { return pg8::cvt_pk_bf16(lo, hi); }
; __device__ __forceinline__ float bf_lo(unsigned w) { return __uint_as_float(w << 16); }
; __device__ __forceinline__ float bf_hi(unsigned w) { return __uint_as_float(w & 0xffff0000u); }
; #define X_IN INP(0)
; #define P_IN INP(1)
; __global__ void __launch_bounds__(512, 2) fwd(Params P) {
;     ...
;         for (int m = gw; m < T_TOK; m += NGW) {
;             const float rsy = __builtin_amdgcn_rsqf(ssq_y[m] * (1.f / DM) + EPS);
;             const f32x4* xr = (const f32x4*)(X_IN + (size_t)m * DM) + lane; const u32x2* yr = (const u32x2*)(YB + (size_t)m * DM) + lane;
;             f32x4* orow = (f32x4*)(OUT_P + (size_t)m * DM) + lane;
;             f32x4 v[8]; float s = 0.f;
; #pragma unroll
;             for (int j = 0; j < 8; ++j) { const f32x4 xv = __builtin_nontemporal_load(&xr[64 * j]); const u32x2 yw = __builtin_nontemporal_load(&yr[64 * j]); const f32x4 g = g1[64 * j];
;                 f32x4 t; t.x = xv.x + bf_lo(yw.x) * rsy * g.x; t.y = xv.y + bf_hi(yw.x) * rsy * g.y; t.z = xv.z + bf_lo(yw.y) * rsy * g.z; t.w = xv.w + bf_hi(yw.y) * rsy * g.w;
;                 v[j] = t; __builtin_nontemporal_store(t, &orow[64 * j]); s += (t.x * t.x + t.y * t.y) + (t.z * t.z + t.w * t.w); }
;     ...
;             u32x2* o = (u32x2*)(XN + (size_t)m * DM) + lane;
; #pragma unroll
;             for (int j = 0; j < 8; ++j) { const f32x4 g = g2[64 * j]; u32x2 w; w.x = pk2(v[j].x * rs * g.x, v[j].y * rs * g.y); w.y = pk2(v[j].z * rs * g.z, v[j].w * rs * g.w); o[64 * j] = w; }
;             const f32x4 pv = ((const f32x4*)(P_IN + (size_t)m * PLE))[lane]; u32x2 pw; pw.x = pk2(pv.x, pv.y); pw.y = pk2(pv.z, pv.w);
;             ((u32x2*)(PB + (size_t)m * PLE))[lane] = pw;
	v_cvt_pk_bf16_f32 v99, v176, v177
	global_store_dwordx2 v181, v[98:99], s[38:39] offset:512
	v_mul_f32_e32 v174, v184, v72
	v_mul_f32_e32 v175, v184, v73
	v_mul_f32_e32 v176, v184, v74
	v_mul_f32_e32 v177, v184, v75
	v_mul_f32_e32 v174, v174, v40
	v_mul_f32_e32 v175, v175, v41
	v_mul_f32_e32 v176, v176, v42
	v_mul_f32_e32 v177, v177, v43
	v_cvt_pk_bf16_f32 v100, v174, v175
	v_cvt_pk_bf16_f32 v101, v176, v177
	global_store_dwordx2 v181, v[100:101], s[38:39] offset:1024
	v_mul_f32_e32 v174, v184, v76
	v_mul_f32_e32 v175, v184, v77
	v_mul_f32_e32 v176, v184, v78
	v_mul_f32_e32 v177, v184, v79
	v_mul_f32_e32 v174, v174, v44
	v_mul_f32_e32 v175, v175, v45
	v_mul_f32_e32 v176, v176, v46
	v_mul_f32_e32 v177, v177, v47
	v_cvt_pk_bf16_f32 v102, v174, v175
	v_cvt_pk_bf16_f32 v103, v176, v177
	global_store_dwordx2 v181, v[102:103], s[38:39] offset:1536
	v_mul_f32_e32 v174, v184, v80
	v_mul_f32_e32 v175, v184, v81
	v_mul_f32_e32 v176, v184, v82
	v_mul_f32_e32 v177, v184, v83
	v_mul_f32_e32 v174, v174, v48
	v_mul_f32_e32 v175, v175, v49
	v_mul_f32_e32 v176, v176, v50
	v_mul_f32_e32 v177, v177, v51
	v_cvt_pk_bf16_f32 v104, v174, v175
	v_cvt_pk_bf16_f32 v105, v176, v177
	global_store_dwordx2 v181, v[104:105], s[38:39] offset:2048
	v_mul_f32_e32 v174, v184, v84
	v_mul_f32_e32 v175, v184, v85
	v_mul_f32_e32 v176, v184, v86
	v_mul_f32_e32 v177, v184, v87
	v_mul_f32_e32 v174, v174, v52
	v_mul_f32_e32 v175, v175, v53
	v_mul_f32_e32 v176, v176, v54
	v_mul_f32_e32 v177, v177, v55
	v_cvt_pk_bf16_f32 v106, v174, v175
	v_cvt_pk_bf16_f32 v107, v176, v177
	global_store_dwordx2 v181, v[106:107], s[38:39] offset:2560
	v_mul_f32_e32 v174, v184, v88
	v_mul_f32_e32 v175, v184, v89
	v_mul_f32_e32 v176, v184, v90
	v_mul_f32_e32 v177, v184, v91
	v_mul_f32_e32 v174, v174, v56
	v_mul_f32_e32 v175, v175, v57
	v_mul_f32_e32 v176, v176, v58
	v_mul_f32_e32 v177, v177, v59
	v_cvt_pk_bf16_f32 v108, v174, v175
	v_cvt_pk_bf16_f32 v109, v176, v177
	global_store_dwordx2 v181, v[108:109], s[38:39] offset:3072
	v_mul_f32_e32 v174, v184, v92
	v_mul_f32_e32 v175, v184, v93
	v_mul_f32_e32 v176, v184, v94
	v_mul_f32_e32 v177, v184, v95
	v_mul_f32_e32 v174, v174, v60
	v_mul_f32_e32 v175, v175, v61
	v_mul_f32_e32 v176, v176, v62
	v_mul_f32_e32 v177, v177, v63
	v_cvt_pk_bf16_f32 v110, v174, v175
	v_cvt_pk_bf16_f32 v111, v176, v177
	global_store_dwordx2 v181, v[110:111], s[38:39] offset:3584
	s_waitcnt vmcnt(34)
	v_cvt_pk_bf16_f32 v114, v114, v115
	v_cvt_pk_bf16_f32 v115, v116, v117
	global_store_dwordx2 v181, v[114:115], s[40:41]
	s_mov_b32 s30, s10
.Lp5b_loop:
	s_lshl_b32 s2, s30, 13
	s_add_u32 s36, s18, s2
	s_addc_u32 s37, s19, 0
	s_lshl_b32 s2, s30, 12
	s_add_u32 s38, s16, s2
	s_addc_u32 s39, s17, 0
	s_lshl_b32 s2, s30, 9
	s_add_u32 s40, s22, s2
	s_addc_u32 s41, s23, 0
	s_add_i32 s10, s30, s82
	s_cmpk_gt_i32 s10, 0x7fff
	s_cbranch_scc1 .Lp5b_tail_b
	s_lshl_b32 s2, s10, 13
	s_add_u32 s24, s8, s2
	s_addc_u32 s25, s9, 0
	s_lshl_b32 s2, s10, 12
	s_add_u32 s26, s14, s2
	s_addc_u32 s27, s15, 0
	s_lshl_b32 s2, s10, 2
	s_add_u32 s28, s12, s2
	s_addc_u32 s29, s13, 0
	s_lshl_b32 s2, s10, 10
	s_add_u32 s34, s20, s2
	s_addc_u32 s35, s21, 0
	global_load_dword v112, v167, s[28:29]
	global_load_dwordx4 v[64:67], v166, s[24:25] offset:-4096 nt
	global_load_dwordx2 v[96:97], v181, s[26:27] offset:0 nt
	global_load_dwordx4 v[68:71], v166, s[24:25] offset:-3072 nt
	global_load_dwordx2 v[98:99], v181, s[26:27] offset:512 nt
	global_load_dwordx4 v[72:75], v166, s[24:25] offset:-2048 nt
	global_load_dwordx2 v[100:101], v181, s[26:27] offset:1024 nt
	global_load_dwordx4 v[76:79], v166, s[24:25] offset:-1024 nt
	global_load_dwordx2 v[102:103], v181, s[26:27] offset:1536 nt
	global_load_dwordx4 v[80:83], v166, s[24:25] offset:0 nt
	global_load_dwordx2 v[104:105], v181, s[26:27] offset:2048 nt
	global_load_dwordx4 v[84:87], v166, s[24:25] offset:1024 nt
	global_load_dwordx2 v[106:107], v181, s[26:27] offset:2560 nt
	global_load_dwordx4 v[88:91], v166, s[24:25] offset:2048 nt
	global_load_dwordx2 v[108:109], v181, s[26:27] offset:3072 nt
	global_load_dwordx4 v[92:95], v166, s[24:25] offset:3072 nt
	global_load_dwordx2 v[110:111], v181, s[26:27] offset:3584 nt
	global_load_dwordx4 v[114:117], v166, s[34:35]
	s_waitcnt vmcnt(50)
	v_fmamk_f32 v183, v168, 0x3a000000, v182
	v_rsq_f32_e32 v183, v183
	v_lshlrev_b32_e32 v174, 16, v150
	v_and_b32_e32 v175, 0xffff0000, v150
	v_lshlrev_b32_e32 v176, 16, v151
	v_and_b32_e32 v177, 0xffff0000, v151
	v_mul_f32_e32 v174, v183, v174
	v_mul_f32_e32 v175, v183, v175
	v_mul_f32_e32 v176, v183, v176
	v_mul_f32_e32 v177, v183, v177
	v_fma_f32 v118, v0, v174, v118
	v_fma_f32 v119, v1, v175, v119
	v_fma_f32 v120, v2, v176, v120
	v_fma_f32 v121, v3, v177, v121
	global_store_dwordx4 v166, v[118:121], s[36:37] offset:-4096 nt
	v_mul_f32_e32 v185, v118, v118
	v_mul_f32_e32 v186, v119, v119
	v_mul_f32_e32 v187, v120, v120
	v_mul_f32_e32 v188, v121, v121
	s_waitcnt vmcnt(49)
	v_lshlrev_b32_e32 v174, 16, v152
	v_and_b32_e32 v175, 0xffff0000, v152
	v_lshlrev_b32_e32 v176, 16, v153
	v_and_b32_e32 v177, 0xffff0000, v153
	v_mul_f32_e32 v174, v183, v174
	v_mul_f32_e32 v175, v183, v175
	v_mul_f32_e32 v176, v183, v176
	v_mul_f32_e32 v177, v183, v177
	v_fma_f32 v122, v4, v174, v122
	v_fma_f32 v123, v5, v175, v123
	v_fma_f32 v124, v6, v176, v124
	v_fma_f32 v125, v7, v177, v125
	global_store_dwordx4 v166, v[122:125], s[36:37] offset:-3072 nt
	v_fma_f32 v185, v122, v122, v185
	v_fma_f32 v186, v123, v123, v186
	v_fma_f32 v187, v124, v124, v187
	v_fma_f32 v188, v125, v125, v188
	s_waitcnt vmcnt(48)
; __device__ __forceinline__ unsigned pk2(float lo, float hi) { return pg8::cvt_pk_bf16(lo, hi); }
; __device__ __forceinline__ float bf_lo(unsigned w) { return __uint_as_float(w << 16); }
; __device__ __forceinline__ float bf_hi(unsigned w) { return __uint_as_float(w & 0xffff0000u); }
; __global__ void __launch_bounds__(512, 2) fwd(Params P) {
;     ...
;             for (int j = 0; j < 8; ++j) { const f32x4 xv = __builtin_nontemporal_load(&xr[64 * j]); const u32x2 yw = __builtin_nontemporal_load(&yr[64 * j]); const f32x4 g = g1[64 * j];
;                 f32x4 t; t.x = xv.x + bf_lo(yw.x) * rsy * g.x; t.y = xv.y + bf_hi(yw.x) * rsy * g.y; t.z = xv.z + bf_lo(yw.y) * rsy * g.z; t.w = xv.w + bf_hi(yw.y) * rsy * g.w;
;                 v[j] = t; __builtin_nontemporal_store(t, &orow[64 * j]); s += (t.x * t.x + t.y * t.y) + (t.z * t.z + t.w * t.w); }
;             const float rs = __builtin_amdgcn_rsqf(wave_sum(s) * (1.f / DM) + EPS);
;             u32x2* o = (u32x2*)(XN + (size_t)m * DM) + lane;
; #pragma unroll
;             for (int j = 0; j < 8; ++j) { const f32x4 g = g2[64 * j]; u32x2 w; w.x = pk2(v[j].x * rs * g.x, v[j].y * rs * g.y); w.y = pk2(v[j].z * rs * g.z, v[j].w * rs * g.w); o[64 * j] = w; }
	v_lshlrev_b32_e32 v174, 16, v154
	v_and_b32_e32 v175, 0xffff0000, v154
	v_lshlrev_b32_e32 v176, 16, v155
	v_and_b32_e32 v177, 0xffff0000, v155
	v_mul_f32_e32 v174, v183, v174
	v_mul_f32_e32 v175, v183, v175
	v_mul_f32_e32 v176, v183, v176
	v_mul_f32_e32 v177, v183, v177
	v_fma_f32 v126, v8, v174, v126
	v_fma_f32 v127, v9, v175, v127
	v_fma_f32 v128, v10, v176, v128
	v_fma_f32 v129, v11, v177, v129
	global_store_dwordx4 v166, v[126:129], s[36:37] offset:-2048 nt
	v_fma_f32 v185, v126, v126, v185
	v_fma_f32 v186, v127, v127, v186
	v_fma_f32 v187, v128, v128, v187
	v_fma_f32 v188, v129, v129, v188
	s_waitcnt vmcnt(47)
	v_lshlrev_b32_e32 v174, 16, v156
	v_and_b32_e32 v175, 0xffff0000, v156
	v_lshlrev_b32_e32 v176, 16, v157
	v_and_b32_e32 v177, 0xffff0000, v157
	v_mul_f32_e32 v174, v183, v174
	v_mul_f32_e32 v175, v183, v175
	v_mul_f32_e32 v176, v183, v176
	v_mul_f32_e32 v177, v183, v177
	v_fma_f32 v130, v12, v174, v130
	v_fma_f32 v131, v13, v175, v131
	v_fma_f32 v132, v14, v176, v132
	v_fma_f32 v133, v15, v177, v133
	global_store_dwordx4 v166, v[130:133], s[36:37] offset:-1024 nt
	v_fma_f32 v185, v130, v130, v185
	v_fma_f32 v186, v131, v131, v186
	v_fma_f32 v187, v132, v132, v187
	v_fma_f32 v188, v133, v133, v188
	s_waitcnt vmcnt(46)
	v_lshlrev_b32_e32 v174, 16, v158
	v_and_b32_e32 v175, 0xffff0000, v158
	v_lshlrev_b32_e32 v176, 16, v159
	v_and_b32_e32 v177, 0xffff0000, v159
	v_mul_f32_e32 v174, v183, v174
	v_mul_f32_e32 v175, v183, v175
	v_mul_f32_e32 v176, v183, v176
	v_mul_f32_e32 v177, v183, v177
	v_fma_f32 v134, v16, v174, v134
	v_fma_f32 v135, v17, v175, v135
	v_fma_f32 v136, v18, v176, v136
	v_fma_f32 v137, v19, v177, v137
	global_store_dwordx4 v166, v[134:137], s[36:37] offset:0 nt
	v_fma_f32 v185, v134, v134, v185
	v_fma_f32 v186, v135, v135, v186
	v_fma_f32 v187, v136, v136, v187
	v_fma_f32 v188, v137, v137, v188
	s_waitcnt vmcnt(45)
	v_lshlrev_b32_e32 v174, 16, v160
	v_and_b32_e32 v175, 0xffff0000, v160
	v_lshlrev_b32_e32 v176, 16, v161
	v_and_b32_e32 v177, 0xffff0000, v161
	v_mul_f32_e32 v174, v183, v174
	v_mul_f32_e32 v175, v183, v175
	v_mul_f32_e32 v176, v183, v176
	v_mul_f32_e32 v177, v183, v177
	v_fma_f32 v138, v20, v174, v138
	v_fma_f32 v139, v21, v175, v139
	v_fma_f32 v140, v22, v176, v140
	v_fma_f32 v141, v23, v177, v141
	global_store_dwordx4 v166, v[138:141], s[36:37] offset:1024 nt
	v_fma_f32 v185, v138, v138, v185
	v_fma_f32 v186, v139, v139, v186
	v_fma_f32 v187, v140, v140, v187
	v_fma_f32 v188, v141, v141, v188
	s_waitcnt vmcnt(44)
	v_lshlrev_b32_e32 v174, 16, v162
	v_and_b32_e32 v175, 0xffff0000, v162
	v_lshlrev_b32_e32 v176, 16, v163
	v_and_b32_e32 v177, 0xffff0000, v163
	v_mul_f32_e32 v174, v183, v174
	v_mul_f32_e32 v175, v183, v175
	v_mul_f32_e32 v176, v183, v176
	v_mul_f32_e32 v177, v183, v177
	v_fma_f32 v142, v24, v174, v142
	v_fma_f32 v143, v25, v175, v143
	v_fma_f32 v144, v26, v176, v144
	v_fma_f32 v145, v27, v177, v145
	global_store_dwordx4 v166, v[142:145], s[36:37] offset:2048 nt
	v_fma_f32 v185, v142, v142, v185
	v_fma_f32 v186, v143, v143, v186
	v_fma_f32 v187, v144, v144, v187
	v_fma_f32 v188, v145, v145, v188
	s_waitcnt vmcnt(43)
	v_lshlrev_b32_e32 v174, 16, v164
	v_and_b32_e32 v175, 0xffff0000, v164
	v_lshlrev_b32_e32 v176, 16, v165
	v_and_b32_e32 v177, 0xffff0000, v165
	v_mul_f32_e32 v174, v183, v174
	v_mul_f32_e32 v175, v183, v175
	v_mul_f32_e32 v176, v183, v176
	v_mul_f32_e32 v177, v183, v177
	v_fma_f32 v146, v28, v174, v146
	v_fma_f32 v147, v29, v175, v147
	v_fma_f32 v148, v30, v176, v148
	v_fma_f32 v149, v31, v177, v149
	global_store_dwordx4 v166, v[146:149], s[36:37] offset:3072 nt
	v_fma_f32 v185, v146, v146, v185
	v_fma_f32 v186, v147, v147, v186
	v_fma_f32 v187, v148, v148, v187
	v_fma_f32 v188, v149, v149, v188
	v_add_f32_e32 v185, v185, v186
	v_add_f32_e32 v187, v187, v188
	v_add_f32_e32 v185, v185, v187
	s_nop 1
	v_add_f32_dpp v185, v185, v185 quad_perm:[1,0,3,2] row_mask:0xf bank_mask:0xf
	s_nop 1
	v_add_f32_dpp v185, v185, v185 quad_perm:[2,3,0,1] row_mask:0xf bank_mask:0xf
	s_nop 1
	v_add_f32_dpp v185, v185, v185 row_half_mirror row_mask:0xf bank_mask:0xf
	s_nop 1
	v_add_f32_dpp v185, v185, v185 row_mirror row_mask:0xf bank_mask:0xf
	s_nop 1
	v_readlane_b32 s24, v185, 0
	v_readlane_b32 s25, v185, 16
	v_readlane_b32 s26, v185, 32
	v_readlane_b32 s27, v185, 48
	v_mov_b32_e32 v184, s24
	v_add_f32_e32 v184, s25, v184
	v_add_f32_e32 v184, s26, v184
	v_add_f32_e32 v184, s27, v184
	v_fmamk_f32 v184, v184, 0x3a000000, v182
	v_rsq_f32_e32 v184, v184
	s_nop 0
	v_mul_f32_e32 v174, v184, v118
	v_mul_f32_e32 v175, v184, v119
	v_mul_f32_e32 v176, v184, v120
	v_mul_f32_e32 v177, v184, v121
	v_mul_f32_e32 v174, v174, v32
	v_mul_f32_e32 v175, v175, v33
	v_mul_f32_e32 v176, v176, v34
	v_mul_f32_e32 v177, v177, v35
	v_cvt_pk_bf16_f32 v150, v174, v175
	v_cvt_pk_bf16_f32 v151, v176, v177
	global_store_dwordx2 v181, v[150:151], s[38:39] offset:0
	v_mul_f32_e32 v174, v184, v122
	v_mul_f32_e32 v175, v184, v123
	v_mul_f32_e32 v176, v184, v124
	v_mul_f32_e32 v177, v184, v125
	v_mul_f32_e32 v174, v174, v36
	v_mul_f32_e32 v175, v175, v37
	v_mul_f32_e32 v176, v176, v38
	v_mul_f32_e32 v177, v177, v39
	v_cvt_pk_bf16_f32 v152, v174, v175
	v_cvt_pk_bf16_f32 v153, v176, v177
	global_store_dwordx2 v181, v[152:153], s[38:39] offset:512
	v_mul_f32_e32 v174, v184, v126
	v_mul_f32_e32 v175, v184, v127
	v_mul_f32_e32 v176, v184, v128
	v_mul_f32_e32 v177, v184, v129
	v_mul_f32_e32 v174, v174, v40
	v_mul_f32_e32 v175, v175, v41
	v_mul_f32_e32 v176, v176, v42
	v_mul_f32_e32 v177, v177, v43
	v_cvt_pk_bf16_f32 v154, v174, v175
	v_cvt_pk_bf16_f32 v155, v176, v177
	global_store_dwordx2 v181, v[154:155], s[38:39] offset:1024
; __device__ __forceinline__ unsigned pk2(float lo, float hi) { return pg8::cvt_pk_bf16(lo, hi); }
; __device__ __forceinline__ float bf_lo(unsigned w) { return __uint_as_float(w << 16); }
; __device__ __forceinline__ float bf_hi(unsigned w) { return __uint_as_float(w & 0xffff0000u); }
; #define X_IN INP(0)
; #define P_IN INP(1)
; __global__ void __launch_bounds__(512, 2) fwd(Params P) {
;     ...
;         for (int m = gw; m < T_TOK; m += NGW) {
;             const float rsy = __builtin_amdgcn_rsqf(ssq_y[m] * (1.f / DM) + EPS);
;             const f32x4* xr = (const f32x4*)(X_IN + (size_t)m * DM) + lane; const u32x2* yr = (const u32x2*)(YB + (size_t)m * DM) + lane;
;             f32x4* orow = (f32x4*)(OUT_P + (size_t)m * DM) + lane;
;             f32x4 v[8]; float s = 0.f;
; #pragma unroll
;             for (int j = 0; j < 8; ++j) { const f32x4 xv = __builtin_nontemporal_load(&xr[64 * j]); const u32x2 yw = __builtin_nontemporal_load(&yr[64 * j]); const f32x4 g = g1[64 * j];
;                 f32x4 t; t.x = xv.x + bf_lo(yw.x) * rsy * g.x; t.y = xv.y + bf_hi(yw.x) * rsy * g.y; t.z = xv.z + bf_lo(yw.y) * rsy * g.z; t.w = xv.w + bf_hi(yw.y) * rsy * g.w;
;                 v[j] = t; __builtin_nontemporal_store(t, &orow[64 * j]); s += (t.x * t.x + t.y * t.y) + (t.z * t.z + t.w * t.w); }
;     ...
;             u32x2* o = (u32x2*)(XN + (size_t)m * DM) + lane;
; #pragma unroll
;             for (int j = 0; j < 8; ++j) { const f32x4 g = g2[64 * j]; u32x2 w; w.x = pk2(v[j].x * rs * g.x, v[j].y * rs * g.y); w.y = pk2(v[j].z * rs * g.z, v[j].w * rs * g.w); o[64 * j] = w; }
;             const f32x4 pv = ((const f32x4*)(P_IN + (size_t)m * PLE))[lane]; u32x2 pw; pw.x = pk2(pv.x, pv.y); pw.y = pk2(pv.z, pv.w);
;             ((u32x2*)(PB + (size_t)m * PLE))[lane] = pw;
	v_mul_f32_e32 v174, v184, v130
	v_mul_f32_e32 v175, v184, v131
	v_mul_f32_e32 v176, v184, v132
	v_mul_f32_e32 v177, v184, v133
	v_mul_f32_e32 v174, v174, v44
	v_mul_f32_e32 v175, v175, v45
	v_mul_f32_e32 v176, v176, v46
	v_mul_f32_e32 v177, v177, v47
	v_cvt_pk_bf16_f32 v156, v174, v175
	v_cvt_pk_bf16_f32 v157, v176, v177
	global_store_dwordx2 v181, v[156:157], s[38:39] offset:1536
	v_mul_f32_e32 v174, v184, v134
	v_mul_f32_e32 v175, v184, v135
	v_mul_f32_e32 v176, v184, v136
	v_mul_f32_e32 v177, v184, v137
	v_mul_f32_e32 v174, v174, v48
	v_mul_f32_e32 v175, v175, v49
	v_mul_f32_e32 v176, v176, v50
	v_mul_f32_e32 v177, v177, v51
	v_cvt_pk_bf16_f32 v158, v174, v175
	v_cvt_pk_bf16_f32 v159, v176, v177
	global_store_dwordx2 v181, v[158:159], s[38:39] offset:2048
	v_mul_f32_e32 v174, v184, v138
	v_mul_f32_e32 v175, v184, v139
	v_mul_f32_e32 v176, v184, v140
	v_mul_f32_e32 v177, v184, v141
	v_mul_f32_e32 v174, v174, v52
	v_mul_f32_e32 v175, v175, v53
	v_mul_f32_e32 v176, v176, v54
	v_mul_f32_e32 v177, v177, v55
	v_cvt_pk_bf16_f32 v160, v174, v175
	v_cvt_pk_bf16_f32 v161, v176, v177
	global_store_dwordx2 v181, v[160:161], s[38:39] offset:2560
	v_mul_f32_e32 v174, v184, v142
	v_mul_f32_e32 v175, v184, v143
	v_mul_f32_e32 v176, v184, v144
	v_mul_f32_e32 v177, v184, v145
	v_mul_f32_e32 v174, v174, v56
	v_mul_f32_e32 v175, v175, v57
	v_mul_f32_e32 v176, v176, v58
	v_mul_f32_e32 v177, v177, v59
	v_cvt_pk_bf16_f32 v162, v174, v175
	v_cvt_pk_bf16_f32 v163, v176, v177
	global_store_dwordx2 v181, v[162:163], s[38:39] offset:3072
	v_mul_f32_e32 v174, v184, v146
	v_mul_f32_e32 v175, v184, v147
	v_mul_f32_e32 v176, v184, v148
	v_mul_f32_e32 v177, v184, v149
	v_mul_f32_e32 v174, v174, v60
	v_mul_f32_e32 v175, v175, v61
	v_mul_f32_e32 v176, v176, v62
	v_mul_f32_e32 v177, v177, v63
	v_cvt_pk_bf16_f32 v164, v174, v175
	v_cvt_pk_bf16_f32 v165, v176, v177
	global_store_dwordx2 v181, v[164:165], s[38:39] offset:3584
	s_waitcnt vmcnt(51)
	v_cvt_pk_bf16_f32 v170, v170, v171
	v_cvt_pk_bf16_f32 v171, v172, v173
	global_store_dwordx2 v181, v[170:171], s[40:41]
	s_mov_b32 s30, s10
	s_lshl_b32 s2, s30, 13
	s_add_u32 s36, s18, s2
	s_addc_u32 s37, s19, 0
	s_lshl_b32 s2, s30, 12
	s_add_u32 s38, s16, s2
	s_addc_u32 s39, s17, 0
	s_lshl_b32 s2, s30, 9
	s_add_u32 s40, s22, s2
	s_addc_u32 s41, s23, 0
	s_add_i32 s10, s30, s82
	s_cmpk_gt_i32 s10, 0x7fff
	s_cbranch_scc1 .Lp5b_tail_a
	s_lshl_b32 s2, s10, 13
	s_add_u32 s24, s8, s2
	s_addc_u32 s25, s9, 0
	s_lshl_b32 s2, s10, 12
	s_add_u32 s26, s14, s2
	s_addc_u32 s27, s15, 0
	s_lshl_b32 s2, s10, 2
	s_add_u32 s28, s12, s2
	s_addc_u32 s29, s13, 0
	s_lshl_b32 s2, s10, 10
	s_add_u32 s34, s20, s2
	s_addc_u32 s35, s21, 0
	global_load_dword v168, v167, s[28:29]
	global_load_dwordx4 v[118:121], v166, s[24:25] offset:-4096 nt
	global_load_dwordx2 v[150:151], v181, s[26:27] offset:0 nt
	global_load_dwordx4 v[122:125], v166, s[24:25] offset:-3072 nt
	global_load_dwordx2 v[152:153], v181, s[26:27] offset:512 nt
	global_load_dwordx4 v[126:129], v166, s[24:25] offset:-2048 nt
	global_load_dwordx2 v[154:155], v181, s[26:27] offset:1024 nt
	global_load_dwordx4 v[130:133], v166, s[24:25] offset:-1024 nt
	global_load_dwordx2 v[156:157], v181, s[26:27] offset:1536 nt
	global_load_dwordx4 v[134:137], v166, s[24:25] offset:0 nt
	global_load_dwordx2 v[158:159], v181, s[26:27] offset:2048 nt
	global_load_dwordx4 v[138:141], v166, s[24:25] offset:1024 nt
	global_load_dwordx2 v[160:161], v181, s[26:27] offset:2560 nt
	global_load_dwordx4 v[142:145], v166, s[24:25] offset:2048 nt
	global_load_dwordx2 v[162:163], v181, s[26:27] offset:3072 nt
	global_load_dwordx4 v[146:149], v166, s[24:25] offset:3072 nt
	global_load_dwordx2 v[164:165], v181, s[26:27] offset:3584 nt
	global_load_dwordx4 v[170:173], v166, s[34:35]
	s_waitcnt vmcnt(50)
	v_fmamk_f32 v183, v112, 0x3a000000, v182
	v_rsq_f32_e32 v183, v183
	v_lshlrev_b32_e32 v174, 16, v96
	v_and_b32_e32 v175, 0xffff0000, v96
	v_lshlrev_b32_e32 v176, 16, v97
	v_and_b32_e32 v177, 0xffff0000, v97
	v_mul_f32_e32 v174, v183, v174
	v_mul_f32_e32 v175, v183, v175
	v_mul_f32_e32 v176, v183, v176
	v_mul_f32_e32 v177, v183, v177
	v_fma_f32 v64, v0, v174, v64
	v_fma_f32 v65, v1, v175, v65
	v_fma_f32 v66, v2, v176, v66
	v_fma_f32 v67, v3, v177, v67
	global_store_dwordx4 v166, v[64:67], s[36:37] offset:-4096 nt
	v_mul_f32_e32 v185, v64, v64
	v_mul_f32_e32 v186, v65, v65
	v_mul_f32_e32 v187, v66, v66
	v_mul_f32_e32 v188, v67, v67
	s_waitcnt vmcnt(49)
	v_lshlrev_b32_e32 v174, 16, v98
	v_and_b32_e32 v175, 0xffff0000, v98
	v_lshlrev_b32_e32 v176, 16, v99
	v_and_b32_e32 v177, 0xffff0000, v99
	v_mul_f32_e32 v174, v183, v174
	v_mul_f32_e32 v175, v183, v175
	v_mul_f32_e32 v176, v183, v176
	v_mul_f32_e32 v177, v183, v177
	v_fma_f32 v68, v4, v174, v68
	v_fma_f32 v69, v5, v175, v69
	v_fma_f32 v70, v6, v176, v70
	v_fma_f32 v71, v7, v177, v71
	global_store_dwordx4 v166, v[68:71], s[36:37] offset:-3072 nt
	v_fma_f32 v185, v68, v68, v185
	v_fma_f32 v186, v69, v69, v186
	v_fma_f32 v187, v70, v70, v187
	v_fma_f32 v188, v71, v71, v188
	s_waitcnt vmcnt(48)
	v_lshlrev_b32_e32 v174, 16, v100
	v_and_b32_e32 v175, 0xffff0000, v100
	v_lshlrev_b32_e32 v176, 16, v101
	v_and_b32_e32 v177, 0xffff0000, v101
	v_mul_f32_e32 v174, v183, v174
	v_mul_f32_e32 v175, v183, v175
	v_mul_f32_e32 v176, v183, v176
	v_mul_f32_e32 v177, v183, v177
	v_fma_f32 v72, v8, v174, v72
	v_fma_f32 v73, v9, v175, v73
	v_fma_f32 v74, v10, v176, v74
	v_fma_f32 v75, v11, v177, v75
	global_store_dwordx4 v166, v[72:75], s[36:37] offset:-2048 nt
	v_fma_f32 v185, v72, v72, v185
	v_fma_f32 v186, v73, v73, v186
	v_fma_f32 v187, v74, v74, v187
	v_fma_f32 v188, v75, v75, v188
	s_waitcnt vmcnt(47)
; __device__ __forceinline__ unsigned pk2(float lo, float hi) { return pg8::cvt_pk_bf16(lo, hi); }
; __device__ __forceinline__ float bf_lo(unsigned w) { return __uint_as_float(w << 16); }
; __device__ __forceinline__ float bf_hi(unsigned w) { return __uint_as_float(w & 0xffff0000u); }
; #define P_IN INP(1)
; __global__ void __launch_bounds__(512, 2) fwd(Params P) {
;     ...
;             for (int j = 0; j < 8; ++j) { const f32x4 xv = __builtin_nontemporal_load(&xr[64 * j]); const u32x2 yw = __builtin_nontemporal_load(&yr[64 * j]); const f32x4 g = g1[64 * j];
;                 f32x4 t; t.x = xv.x + bf_lo(yw.x) * rsy * g.x; t.y = xv.y + bf_hi(yw.x) * rsy * g.y; t.z = xv.z + bf_lo(yw.y) * rsy * g.z; t.w = xv.w + bf_hi(yw.y) * rsy * g.w;
;                 v[j] = t; __builtin_nontemporal_store(t, &orow[64 * j]); s += (t.x * t.x + t.y * t.y) + (t.z * t.z + t.w * t.w); }
;             const float rs = __builtin_amdgcn_rsqf(wave_sum(s) * (1.f / DM) + EPS);
;             u32x2* o = (u32x2*)(XN + (size_t)m * DM) + lane;
; #pragma unroll
;             for (int j = 0; j < 8; ++j) { const f32x4 g = g2[64 * j]; u32x2 w; w.x = pk2(v[j].x * rs * g.x, v[j].y * rs * g.y); w.y = pk2(v[j].z * rs * g.z, v[j].w * rs * g.w); o[64 * j] = w; }
;             const f32x4 pv = ((const f32x4*)(P_IN + (size_t)m * PLE))[lane]; u32x2 pw; pw.x = pk2(pv.x, pv.y); pw.y = pk2(pv.z, pv.w);
;             ((u32x2*)(PB + (size_t)m * PLE))[lane] = pw;
	v_lshlrev_b32_e32 v174, 16, v102
	v_and_b32_e32 v175, 0xffff0000, v102
	v_lshlrev_b32_e32 v176, 16, v103
	v_and_b32_e32 v177, 0xffff0000, v103
	v_mul_f32_e32 v174, v183, v174
	v_mul_f32_e32 v175, v183, v175
	v_mul_f32_e32 v176, v183, v176
	v_mul_f32_e32 v177, v183, v177
	v_fma_f32 v76, v12, v174, v76
	v_fma_f32 v77, v13, v175, v77
	v_fma_f32 v78, v14, v176, v78
	v_fma_f32 v79, v15, v177, v79
	global_store_dwordx4 v166, v[76:79], s[36:37] offset:-1024 nt
	v_fma_f32 v185, v76, v76, v185
	v_fma_f32 v186, v77, v77, v186
	v_fma_f32 v187, v78, v78, v187
	v_fma_f32 v188, v79, v79, v188
	s_waitcnt vmcnt(46)
	v_lshlrev_b32_e32 v174, 16, v104
	v_and_b32_e32 v175, 0xffff0000, v104
	v_lshlrev_b32_e32 v176, 16, v105
	v_and_b32_e32 v177, 0xffff0000, v105
	v_mul_f32_e32 v174, v183, v174
	v_mul_f32_e32 v175, v183, v175
	v_mul_f32_e32 v176, v183, v176
	v_mul_f32_e32 v177, v183, v177
	v_fma_f32 v80, v16, v174, v80
	v_fma_f32 v81, v17, v175, v81
	v_fma_f32 v82, v18, v176, v82
	v_fma_f32 v83, v19, v177, v83
	global_store_dwordx4 v166, v[80:83], s[36:37] offset:0 nt
	v_fma_f32 v185, v80, v80, v185
	v_fma_f32 v186, v81, v81, v186
	v_fma_f32 v187, v82, v82, v187
	v_fma_f32 v188, v83, v83, v188
	s_waitcnt vmcnt(45)
	v_lshlrev_b32_e32 v174, 16, v106
	v_and_b32_e32 v175, 0xffff0000, v106
	v_lshlrev_b32_e32 v176, 16, v107
	v_and_b32_e32 v177, 0xffff0000, v107
	v_mul_f32_e32 v174, v183, v174
	v_mul_f32_e32 v175, v183, v175
	v_mul_f32_e32 v176, v183, v176
	v_mul_f32_e32 v177, v183, v177
	v_fma_f32 v84, v20, v174, v84
	v_fma_f32 v85, v21, v175, v85
	v_fma_f32 v86, v22, v176, v86
	v_fma_f32 v87, v23, v177, v87
	global_store_dwordx4 v166, v[84:87], s[36:37] offset:1024 nt
	v_fma_f32 v185, v84, v84, v185
	v_fma_f32 v186, v85, v85, v186
	v_fma_f32 v187, v86, v86, v187
	v_fma_f32 v188, v87, v87, v188
	s_waitcnt vmcnt(44)
	v_lshlrev_b32_e32 v174, 16, v108
	v_and_b32_e32 v175, 0xffff0000, v108
	v_lshlrev_b32_e32 v176, 16, v109
	v_and_b32_e32 v177, 0xffff0000, v109
	v_mul_f32_e32 v174, v183, v174
	v_mul_f32_e32 v175, v183, v175
	v_mul_f32_e32 v176, v183, v176
	v_mul_f32_e32 v177, v183, v177
	v_fma_f32 v88, v24, v174, v88
	v_fma_f32 v89, v25, v175, v89
	v_fma_f32 v90, v26, v176, v90
	v_fma_f32 v91, v27, v177, v91
	global_store_dwordx4 v166, v[88:91], s[36:37] offset:2048 nt
	v_fma_f32 v185, v88, v88, v185
	v_fma_f32 v186, v89, v89, v186
	v_fma_f32 v187, v90, v90, v187
	v_fma_f32 v188, v91, v91, v188
	s_waitcnt vmcnt(43)
	v_lshlrev_b32_e32 v174, 16, v110
	v_and_b32_e32 v175, 0xffff0000, v110
	v_lshlrev_b32_e32 v176, 16, v111
	v_and_b32_e32 v177, 0xffff0000, v111
	v_mul_f32_e32 v174, v183, v174
	v_mul_f32_e32 v175, v183, v175
	v_mul_f32_e32 v176, v183, v176
	v_mul_f32_e32 v177, v183, v177
	v_fma_f32 v92, v28, v174, v92
	v_fma_f32 v93, v29, v175, v93
	v_fma_f32 v94, v30, v176, v94
	v_fma_f32 v95, v31, v177, v95
	global_store_dwordx4 v166, v[92:95], s[36:37] offset:3072 nt
	v_fma_f32 v185, v92, v92, v185
	v_fma_f32 v186, v93, v93, v186
	v_fma_f32 v187, v94, v94, v187
	v_fma_f32 v188, v95, v95, v188
	v_add_f32_e32 v185, v185, v186
	v_add_f32_e32 v187, v187, v188
	v_add_f32_e32 v185, v185, v187
	s_nop 1
	v_add_f32_dpp v185, v185, v185 quad_perm:[1,0,3,2] row_mask:0xf bank_mask:0xf
	s_nop 1
	v_add_f32_dpp v185, v185, v185 quad_perm:[2,3,0,1] row_mask:0xf bank_mask:0xf
	s_nop 1
	v_add_f32_dpp v185, v185, v185 row_half_mirror row_mask:0xf bank_mask:0xf
	s_nop 1
	v_add_f32_dpp v185, v185, v185 row_mirror row_mask:0xf bank_mask:0xf
	s_nop 1
	v_readlane_b32 s24, v185, 0
	v_readlane_b32 s25, v185, 16
	v_readlane_b32 s26, v185, 32
	v_readlane_b32 s27, v185, 48
	v_mov_b32_e32 v184, s24
	v_add_f32_e32 v184, s25, v184
	v_add_f32_e32 v184, s26, v184
	v_add_f32_e32 v184, s27, v184
	v_fmamk_f32 v184, v184, 0x3a000000, v182
	v_rsq_f32_e32 v184, v184
	s_nop 0
	v_mul_f32_e32 v174, v184, v64
	v_mul_f32_e32 v175, v184, v65
	v_mul_f32_e32 v176, v184, v66
	v_mul_f32_e32 v177, v184, v67
	v_mul_f32_e32 v174, v174, v32
	v_mul_f32_e32 v175, v175, v33
	v_mul_f32_e32 v176, v176, v34
	v_mul_f32_e32 v177, v177, v35
	v_cvt_pk_bf16_f32 v96, v174, v175
	v_cvt_pk_bf16_f32 v97, v176, v177
	global_store_dwordx2 v181, v[96:97], s[38:39] offset:0
	v_mul_f32_e32 v174, v184, v68
	v_mul_f32_e32 v175, v184, v69
	v_mul_f32_e32 v176, v184, v70
	v_mul_f32_e32 v177, v184, v71
	v_mul_f32_e32 v174, v174, v36
	v_mul_f32_e32 v175, v175, v37
	v_mul_f32_e32 v176, v176, v38
	v_mul_f32_e32 v177, v177, v39
	v_cvt_pk_bf16_f32 v98, v174, v175
	v_cvt_pk_bf16_f32 v99, v176, v177
	global_store_dwordx2 v181, v[98:99], s[38:39] offset:512
	v_mul_f32_e32 v174, v184, v72
	v_mul_f32_e32 v175, v184, v73
	v_mul_f32_e32 v176, v184, v74
	v_mul_f32_e32 v177, v184, v75
	v_mul_f32_e32 v174, v174, v40
	v_mul_f32_e32 v175, v175, v41
	v_mul_f32_e32 v176, v176, v42
	v_mul_f32_e32 v177, v177, v43
	v_cvt_pk_bf16_f32 v100, v174, v175
	v_cvt_pk_bf16_f32 v101, v176, v177
	global_store_dwordx2 v181, v[100:101], s[38:39] offset:1024
	v_mul_f32_e32 v174, v184, v76
	v_mul_f32_e32 v175, v184, v77
	v_mul_f32_e32 v176, v184, v78
	v_mul_f32_e32 v177, v184, v79
	v_mul_f32_e32 v174, v174, v44
	v_mul_f32_e32 v175, v175, v45
	v_mul_f32_e32 v176, v176, v46
	v_mul_f32_e32 v177, v177, v47
	v_cvt_pk_bf16_f32 v102, v174, v175
	v_cvt_pk_bf16_f32 v103, v176, v177
	global_store_dwordx2 v181, v[102:103], s[38:39] offset:1536
	v_mul_f32_e32 v174, v184, v80
	v_mul_f32_e32 v175, v184, v81
	v_mul_f32_e32 v176, v184, v82
	v_mul_f32_e32 v177, v184, v83
	v_mul_f32_e32 v174, v174, v48
	v_mul_f32_e32 v175, v175, v49
	v_mul_f32_e32 v176, v176, v50
	v_mul_f32_e32 v177, v177, v51
	v_cvt_pk_bf16_f32 v104, v174, v175
	v_cvt_pk_bf16_f32 v105, v176, v177
	global_store_dwordx2 v181, v[104:105], s[38:39] offset:2048
	v_mul_f32_e32 v174, v184, v84
	v_mul_f32_e32 v175, v184, v85
	v_mul_f32_e32 v176, v184, v86
	v_mul_f32_e32 v177, v184, v87
	v_mul_f32_e32 v174, v174, v52
	v_mul_f32_e32 v175, v175, v53
	v_mul_f32_e32 v176, v176, v54
	v_mul_f32_e32 v177, v177, v55
	v_cvt_pk_bf16_f32 v106, v174, v175
	v_cvt_pk_bf16_f32 v107, v176, v177
	global_store_dwordx2 v181, v[106:107], s[38:39] offset:2560
	v_mul_f32_e32 v174, v184, v88
	v_mul_f32_e32 v175, v184, v89
	v_mul_f32_e32 v176, v184, v90
	v_mul_f32_e32 v177, v184, v91
	v_mul_f32_e32 v174, v174, v56
	v_mul_f32_e32 v175, v175, v57
	v_mul_f32_e32 v176, v176, v58
	v_mul_f32_e32 v177, v177, v59
	v_cvt_pk_bf16_f32 v108, v174, v175
	v_cvt_pk_bf16_f32 v109, v176, v177
	global_store_dwordx2 v181, v[108:109], s[38:39] offset:3072
	v_mul_f32_e32 v174, v184, v92
	v_mul_f32_e32 v175, v184, v93
	v_mul_f32_e32 v176, v184, v94
	v_mul_f32_e32 v177, v184, v95
	v_mul_f32_e32 v174, v174, v60
	v_mul_f32_e32 v175, v175, v61
	v_mul_f32_e32 v176, v176, v62
	v_mul_f32_e32 v177, v177, v63
	v_cvt_pk_bf16_f32 v110, v174, v175
	v_cvt_pk_bf16_f32 v111, v176, v177
	global_store_dwordx2 v181, v[110:111], s[38:39] offset:3584
	s_waitcnt vmcnt(51)
	v_cvt_pk_bf16_f32 v114, v114, v115
	v_cvt_pk_bf16_f32 v115, v116, v117
	global_store_dwordx2 v181, v[114:115], s[40:41]
	s_mov_b32 s30, s10
	s_branch .Lp5b_loop
; __device__ __forceinline__ float bf_lo(unsigned w) { return __uint_as_float(w << 16); }
; __device__ __forceinline__ float bf_hi(unsigned w) { return __uint_as_float(w & 0xffff0000u); }
; __global__ void __launch_bounds__(512, 2) fwd(Params P) {
;     ...
; #pragma unroll
;             for (int j = 0; j < 8; ++j) { const f32x4 xv = __builtin_nontemporal_load(&xr[64 * j]); const u32x2 yw = __builtin_nontemporal_load(&yr[64 * j]); const f32x4 g = g1[64 * j];
;                 f32x4 t; t.x = xv.x + bf_lo(yw.x) * rsy * g.x; t.y = xv.y + bf_hi(yw.x) * rsy * g.y; t.z = xv.z + bf_lo(yw.y) * rsy * g.z; t.w = xv.w + bf_hi(yw.y) * rsy * g.w;
;                 v[j] = t; __builtin_nontemporal_store(t, &orow[64 * j]); s += (t.x * t.x + t.y * t.y) + (t.z * t.z + t.w * t.w); }
.Lp5b_tail_a:
	s_waitcnt vmcnt(32)
	v_fmamk_f32 v183, v112, 0x3a000000, v182
	v_rsq_f32_e32 v183, v183
	v_lshlrev_b32_e32 v174, 16, v96
	v_and_b32_e32 v175, 0xffff0000, v96
	v_lshlrev_b32_e32 v176, 16, v97
	v_and_b32_e32 v177, 0xffff0000, v97
	v_mul_f32_e32 v174, v183, v174
	v_mul_f32_e32 v175, v183, v175
	v_mul_f32_e32 v176, v183, v176
	v_mul_f32_e32 v177, v183, v177
	v_fma_f32 v64, v0, v174, v64
	v_fma_f32 v65, v1, v175, v65
	v_fma_f32 v66, v2, v176, v66
	v_fma_f32 v67, v3, v177, v67
	global_store_dwordx4 v166, v[64:67], s[36:37] offset:-4096 nt
	v_mul_f32_e32 v185, v64, v64
	v_mul_f32_e32 v186, v65, v65
	v_mul_f32_e32 v187, v66, v66
	v_mul_f32_e32 v188, v67, v67
	s_waitcnt vmcnt(31)
	v_lshlrev_b32_e32 v174, 16, v98
	v_and_b32_e32 v175, 0xffff0000, v98
	v_lshlrev_b32_e32 v176, 16, v99
	v_and_b32_e32 v177, 0xffff0000, v99
	v_mul_f32_e32 v174, v183, v174
	v_mul_f32_e32 v175, v183, v175
	v_mul_f32_e32 v176, v183, v176
	v_mul_f32_e32 v177, v183, v177
	v_fma_f32 v68, v4, v174, v68
	v_fma_f32 v69, v5, v175, v69
	v_fma_f32 v70, v6, v176, v70
	v_fma_f32 v71, v7, v177, v71
	global_store_dwordx4 v166, v[68:71], s[36:37] offset:-3072 nt
	v_fma_f32 v185, v68, v68, v185
	v_fma_f32 v186, v69, v69, v186
	v_fma_f32 v187, v70, v70, v187
	v_fma_f32 v188, v71, v71, v188
	s_waitcnt vmcnt(30)
	v_lshlrev_b32_e32 v174, 16, v100
	v_and_b32_e32 v175, 0xffff0000, v100
	v_lshlrev_b32_e32 v176, 16, v101
	v_and_b32_e32 v177, 0xffff0000, v101
	v_mul_f32_e32 v174, v183, v174
	v_mul_f32_e32 v175, v183, v175
	v_mul_f32_e32 v176, v183, v176
	v_mul_f32_e32 v177, v183, v177
	v_fma_f32 v72, v8, v174, v72
	v_fma_f32 v73, v9, v175, v73
	v_fma_f32 v74, v10, v176, v74
	v_fma_f32 v75, v11, v177, v75
	global_store_dwordx4 v166, v[72:75], s[36:37] offset:-2048 nt
	v_fma_f32 v185, v72, v72, v185
	v_fma_f32 v186, v73, v73, v186
	v_fma_f32 v187, v74, v74, v187
	v_fma_f32 v188, v75, v75, v188
	s_waitcnt vmcnt(29)
	v_lshlrev_b32_e32 v174, 16, v102
	v_and_b32_e32 v175, 0xffff0000, v102
	v_lshlrev_b32_e32 v176, 16, v103
	v_and_b32_e32 v177, 0xffff0000, v103
	v_mul_f32_e32 v174, v183, v174
	v_mul_f32_e32 v175, v183, v175
	v_mul_f32_e32 v176, v183, v176
	v_mul_f32_e32 v177, v183, v177
	v_fma_f32 v76, v12, v174, v76
	v_fma_f32 v77, v13, v175, v77
	v_fma_f32 v78, v14, v176, v78
	v_fma_f32 v79, v15, v177, v79
	global_store_dwordx4 v166, v[76:79], s[36:37] offset:-1024 nt
	v_fma_f32 v185, v76, v76, v185
	v_fma_f32 v186, v77, v77, v186
	v_fma_f32 v187, v78, v78, v187
	v_fma_f32 v188, v79, v79, v188
	s_waitcnt vmcnt(28)
	v_lshlrev_b32_e32 v174, 16, v104
	v_and_b32_e32 v175, 0xffff0000, v104
	v_lshlrev_b32_e32 v176, 16, v105
	v_and_b32_e32 v177, 0xffff0000, v105
	v_mul_f32_e32 v174, v183, v174
	v_mul_f32_e32 v175, v183, v175
	v_mul_f32_e32 v176, v183, v176
	v_mul_f32_e32 v177, v183, v177
	v_fma_f32 v80, v16, v174, v80
	v_fma_f32 v81, v17, v175, v81
	v_fma_f32 v82, v18, v176, v82
	v_fma_f32 v83, v19, v177, v83
	global_store_dwordx4 v166, v[80:83], s[36:37] offset:0 nt
	v_fma_f32 v185, v80, v80, v185
	v_fma_f32 v186, v81, v81, v186
	v_fma_f32 v187, v82, v82, v187
	v_fma_f32 v188, v83, v83, v188
	s_waitcnt vmcnt(27)
	v_lshlrev_b32_e32 v174, 16, v106
	v_and_b32_e32 v175, 0xffff0000, v106
	v_lshlrev_b32_e32 v176, 16, v107
	v_and_b32_e32 v177, 0xffff0000, v107
	v_mul_f32_e32 v174, v183, v174
	v_mul_f32_e32 v175, v183, v175
	v_mul_f32_e32 v176, v183, v176
	v_mul_f32_e32 v177, v183, v177
	v_fma_f32 v84, v20, v174, v84
	v_fma_f32 v85, v21, v175, v85
	v_fma_f32 v86, v22, v176, v86
	v_fma_f32 v87, v23, v177, v87
	global_store_dwordx4 v166, v[84:87], s[36:37] offset:1024 nt
	v_fma_f32 v185, v84, v84, v185
	v_fma_f32 v186, v85, v85, v186
	v_fma_f32 v187, v86, v86, v187
	v_fma_f32 v188, v87, v87, v188
	s_waitcnt vmcnt(26)
	v_lshlrev_b32_e32 v174, 16, v108
	v_and_b32_e32 v175, 0xffff0000, v108
	v_lshlrev_b32_e32 v176, 16, v109
	v_and_b32_e32 v177, 0xffff0000, v109
	v_mul_f32_e32 v174, v183, v174
	v_mul_f32_e32 v175, v183, v175
	v_mul_f32_e32 v176, v183, v176
	v_mul_f32_e32 v177, v183, v177
	v_fma_f32 v88, v24, v174, v88
	v_fma_f32 v89, v25, v175, v89
	v_fma_f32 v90, v26, v176, v90
	v_fma_f32 v91, v27, v177, v91
	global_store_dwordx4 v166, v[88:91], s[36:37] offset:2048 nt
	v_fma_f32 v185, v88, v88, v185
	v_fma_f32 v186, v89, v89, v186
	v_fma_f32 v187, v90, v90, v187
	v_fma_f32 v188, v91, v91, v188
	s_waitcnt vmcnt(25)
; __device__ __forceinline__ unsigned pk2(float lo, float hi) { return pg8::cvt_pk_bf16(lo, hi); }
; __device__ __forceinline__ float bf_lo(unsigned w) { return __uint_as_float(w << 16); }
; __device__ __forceinline__ float bf_hi(unsigned w) { return __uint_as_float(w & 0xffff0000u); }
; #define P_IN INP(1)
; __global__ void __launch_bounds__(512, 2) fwd(Params P) {
;     ...
;             for (int j = 0; j < 8; ++j) { const f32x4 xv = __builtin_nontemporal_load(&xr[64 * j]); const u32x2 yw = __builtin_nontemporal_load(&yr[64 * j]); const f32x4 g = g1[64 * j];
;                 f32x4 t; t.x = xv.x + bf_lo(yw.x) * rsy * g.x; t.y = xv.y + bf_hi(yw.x) * rsy * g.y; t.z = xv.z + bf_lo(yw.y) * rsy * g.z; t.w = xv.w + bf_hi(yw.y) * rsy * g.w;
;                 v[j] = t; __builtin_nontemporal_store(t, &orow[64 * j]); s += (t.x * t.x + t.y * t.y) + (t.z * t.z + t.w * t.w); }
;             const float rs = __builtin_amdgcn_rsqf(wave_sum(s) * (1.f / DM) + EPS);
;             u32x2* o = (u32x2*)(XN + (size_t)m * DM) + lane;
; #pragma unroll
;             for (int j = 0; j < 8; ++j) { const f32x4 g = g2[64 * j]; u32x2 w; w.x = pk2(v[j].x * rs * g.x, v[j].y * rs * g.y); w.y = pk2(v[j].z * rs * g.z, v[j].w * rs * g.w); o[64 * j] = w; }
;             const f32x4 pv = ((const f32x4*)(P_IN + (size_t)m * PLE))[lane]; u32x2 pw; pw.x = pk2(pv.x, pv.y); pw.y = pk2(pv.z, pv.w);
;             ((u32x2*)(PB + (size_t)m * PLE))[lane] = pw;
	v_lshlrev_b32_e32 v174, 16, v110
	v_and_b32_e32 v175, 0xffff0000, v110
	v_lshlrev_b32_e32 v176, 16, v111
	v_and_b32_e32 v177, 0xffff0000, v111
	v_mul_f32_e32 v174, v183, v174
	v_mul_f32_e32 v175, v183, v175
	v_mul_f32_e32 v176, v183, v176
	v_mul_f32_e32 v177, v183, v177
	v_fma_f32 v92, v28, v174, v92
	v_fma_f32 v93, v29, v175, v93
	v_fma_f32 v94, v30, v176, v94
	v_fma_f32 v95, v31, v177, v95
	global_store_dwordx4 v166, v[92:95], s[36:37] offset:3072 nt
	v_fma_f32 v185, v92, v92, v185
	v_fma_f32 v186, v93, v93, v186
	v_fma_f32 v187, v94, v94, v187
	v_fma_f32 v188, v95, v95, v188
	v_add_f32_e32 v185, v185, v186
	v_add_f32_e32 v187, v187, v188
	v_add_f32_e32 v185, v185, v187
	s_nop 1
	v_add_f32_dpp v185, v185, v185 quad_perm:[1,0,3,2] row_mask:0xf bank_mask:0xf
	s_nop 1
	v_add_f32_dpp v185, v185, v185 quad_perm:[2,3,0,1] row_mask:0xf bank_mask:0xf
	s_nop 1
	v_add_f32_dpp v185, v185, v185 row_half_mirror row_mask:0xf bank_mask:0xf
	s_nop 1
	v_add_f32_dpp v185, v185, v185 row_mirror row_mask:0xf bank_mask:0xf
	s_nop 1
	v_readlane_b32 s24, v185, 0
	v_readlane_b32 s25, v185, 16
	v_readlane_b32 s26, v185, 32
	v_readlane_b32 s27, v185, 48
	v_mov_b32_e32 v184, s24
	v_add_f32_e32 v184, s25, v184
	v_add_f32_e32 v184, s26, v184
	v_add_f32_e32 v184, s27, v184
	v_fmamk_f32 v184, v184, 0x3a000000, v182
	v_rsq_f32_e32 v184, v184
	s_nop 0
	v_mul_f32_e32 v174, v184, v64
	v_mul_f32_e32 v175, v184, v65
	v_mul_f32_e32 v176, v184, v66
	v_mul_f32_e32 v177, v184, v67
	v_mul_f32_e32 v174, v174, v32
	v_mul_f32_e32 v175, v175, v33
	v_mul_f32_e32 v176, v176, v34
	v_mul_f32_e32 v177, v177, v35
	v_cvt_pk_bf16_f32 v96, v174, v175
	v_cvt_pk_bf16_f32 v97, v176, v177
	global_store_dwordx2 v181, v[96:97], s[38:39] offset:0
	v_mul_f32_e32 v174, v184, v68
	v_mul_f32_e32 v175, v184, v69
	v_mul_f32_e32 v176, v184, v70
	v_mul_f32_e32 v177, v184, v71
	v_mul_f32_e32 v174, v174, v36
	v_mul_f32_e32 v175, v175, v37
	v_mul_f32_e32 v176, v176, v38
	v_mul_f32_e32 v177, v177, v39
	v_cvt_pk_bf16_f32 v98, v174, v175
	v_cvt_pk_bf16_f32 v99, v176, v177
	global_store_dwordx2 v181, v[98:99], s[38:39] offset:512
	v_mul_f32_e32 v174, v184, v72
	v_mul_f32_e32 v175, v184, v73
	v_mul_f32_e32 v176, v184, v74
	v_mul_f32_e32 v177, v184, v75
	v_mul_f32_e32 v174, v174, v40
	v_mul_f32_e32 v175, v175, v41
	v_mul_f32_e32 v176, v176, v42
	v_mul_f32_e32 v177, v177, v43
	v_cvt_pk_bf16_f32 v100, v174, v175
	v_cvt_pk_bf16_f32 v101, v176, v177
	global_store_dwordx2 v181, v[100:101], s[38:39] offset:1024
	v_mul_f32_e32 v174, v184, v76
	v_mul_f32_e32 v175, v184, v77
	v_mul_f32_e32 v176, v184, v78
	v_mul_f32_e32 v177, v184, v79
	v_mul_f32_e32 v174, v174, v44
	v_mul_f32_e32 v175, v175, v45
	v_mul_f32_e32 v176, v176, v46
	v_mul_f32_e32 v177, v177, v47
	v_cvt_pk_bf16_f32 v102, v174, v175
	v_cvt_pk_bf16_f32 v103, v176, v177
	global_store_dwordx2 v181, v[102:103], s[38:39] offset:1536
	v_mul_f32_e32 v174, v184, v80
	v_mul_f32_e32 v175, v184, v81
	v_mul_f32_e32 v176, v184, v82
	v_mul_f32_e32 v177, v184, v83
	v_mul_f32_e32 v174, v174, v48
	v_mul_f32_e32 v175, v175, v49
	v_mul_f32_e32 v176, v176, v50
	v_mul_f32_e32 v177, v177, v51
	v_cvt_pk_bf16_f32 v104, v174, v175
	v_cvt_pk_bf16_f32 v105, v176, v177
	global_store_dwordx2 v181, v[104:105], s[38:39] offset:2048
	v_mul_f32_e32 v174, v184, v84
	v_mul_f32_e32 v175, v184, v85
	v_mul_f32_e32 v176, v184, v86
	v_mul_f32_e32 v177, v184, v87
	v_mul_f32_e32 v174, v174, v52
	v_mul_f32_e32 v175, v175, v53
	v_mul_f32_e32 v176, v176, v54
	v_mul_f32_e32 v177, v177, v55
	v_cvt_pk_bf16_f32 v106, v174, v175
	v_cvt_pk_bf16_f32 v107, v176, v177
	global_store_dwordx2 v181, v[106:107], s[38:39] offset:2560
	v_mul_f32_e32 v174, v184, v88
	v_mul_f32_e32 v175, v184, v89
	v_mul_f32_e32 v176, v184, v90
	v_mul_f32_e32 v177, v184, v91
	v_mul_f32_e32 v174, v174, v56
	v_mul_f32_e32 v175, v175, v57
	v_mul_f32_e32 v176, v176, v58
	v_mul_f32_e32 v177, v177, v59
	v_cvt_pk_bf16_f32 v108, v174, v175
	v_cvt_pk_bf16_f32 v109, v176, v177
	global_store_dwordx2 v181, v[108:109], s[38:39] offset:3072
	v_mul_f32_e32 v174, v184, v92
	v_mul_f32_e32 v175, v184, v93
	v_mul_f32_e32 v176, v184, v94
	v_mul_f32_e32 v177, v184, v95
	v_mul_f32_e32 v174, v174, v60
	v_mul_f32_e32 v175, v175, v61
	v_mul_f32_e32 v176, v176, v62
	v_mul_f32_e32 v177, v177, v63
	v_cvt_pk_bf16_f32 v110, v174, v175
	v_cvt_pk_bf16_f32 v111, v176, v177
	global_store_dwordx2 v181, v[110:111], s[38:39] offset:3584
	s_waitcnt vmcnt(33)
	v_cvt_pk_bf16_f32 v114, v114, v115
	v_cvt_pk_bf16_f32 v115, v116, v117
	global_store_dwordx2 v181, v[114:115], s[40:41]
	s_branch .Lp5b_done
; __device__ __forceinline__ float bf_lo(unsigned w) { return __uint_as_float(w << 16); }
; __device__ __forceinline__ float bf_hi(unsigned w) { return __uint_as_float(w & 0xffff0000u); }
; __global__ void __launch_bounds__(512, 2) fwd(Params P) {
;     ...
; #pragma unroll
;             for (int j = 0; j < 8; ++j) { const f32x4 xv = __builtin_nontemporal_load(&xr[64 * j]); const u32x2 yw = __builtin_nontemporal_load(&yr[64 * j]); const f32x4 g = g1[64 * j];
;                 f32x4 t; t.x = xv.x + bf_lo(yw.x) * rsy * g.x; t.y = xv.y + bf_hi(yw.x) * rsy * g.y; t.z = xv.z + bf_lo(yw.y) * rsy * g.z; t.w = xv.w + bf_hi(yw.y) * rsy * g.w;
;                 v[j] = t; __builtin_nontemporal_store(t, &orow[64 * j]); s += (t.x * t.x + t.y * t.y) + (t.z * t.z + t.w * t.w); }
.Lp5b_tail_b:
	s_waitcnt vmcnt(32)
	v_fmamk_f32 v183, v168, 0x3a000000, v182
	v_rsq_f32_e32 v183, v183
	v_lshlrev_b32_e32 v174, 16, v150
	v_and_b32_e32 v175, 0xffff0000, v150
	v_lshlrev_b32_e32 v176, 16, v151
	v_and_b32_e32 v177, 0xffff0000, v151
	v_mul_f32_e32 v174, v183, v174
	v_mul_f32_e32 v175, v183, v175
	v_mul_f32_e32 v176, v183, v176
	v_mul_f32_e32 v177, v183, v177
	v_fma_f32 v118, v0, v174, v118
	v_fma_f32 v119, v1, v175, v119
	v_fma_f32 v120, v2, v176, v120
	v_fma_f32 v121, v3, v177, v121
	global_store_dwordx4 v166, v[118:121], s[36:37] offset:-4096 nt
	v_mul_f32_e32 v185, v118, v118
	v_mul_f32_e32 v186, v119, v119
	v_mul_f32_e32 v187, v120, v120
	v_mul_f32_e32 v188, v121, v121
	s_waitcnt vmcnt(31)
	v_lshlrev_b32_e32 v174, 16, v152
	v_and_b32_e32 v175, 0xffff0000, v152
	v_lshlrev_b32_e32 v176, 16, v153
	v_and_b32_e32 v177, 0xffff0000, v153
	v_mul_f32_e32 v174, v183, v174
	v_mul_f32_e32 v175, v183, v175
	v_mul_f32_e32 v176, v183, v176
	v_mul_f32_e32 v177, v183, v177
	v_fma_f32 v122, v4, v174, v122
	v_fma_f32 v123, v5, v175, v123
	v_fma_f32 v124, v6, v176, v124
	v_fma_f32 v125, v7, v177, v125
	global_store_dwordx4 v166, v[122:125], s[36:37] offset:-3072 nt
	v_fma_f32 v185, v122, v122, v185
	v_fma_f32 v186, v123, v123, v186
	v_fma_f32 v187, v124, v124, v187
	v_fma_f32 v188, v125, v125, v188
	s_waitcnt vmcnt(30)
	v_lshlrev_b32_e32 v174, 16, v154
	v_and_b32_e32 v175, 0xffff0000, v154
	v_lshlrev_b32_e32 v176, 16, v155
	v_and_b32_e32 v177, 0xffff0000, v155
	v_mul_f32_e32 v174, v183, v174
	v_mul_f32_e32 v175, v183, v175
	v_mul_f32_e32 v176, v183, v176
	v_mul_f32_e32 v177, v183, v177
	v_fma_f32 v126, v8, v174, v126
	v_fma_f32 v127, v9, v175, v127
	v_fma_f32 v128, v10, v176, v128
	v_fma_f32 v129, v11, v177, v129
	global_store_dwordx4 v166, v[126:129], s[36:37] offset:-2048 nt
	v_fma_f32 v185, v126, v126, v185
	v_fma_f32 v186, v127, v127, v186
	v_fma_f32 v187, v128, v128, v187
	v_fma_f32 v188, v129, v129, v188
	s_waitcnt vmcnt(29)
	v_lshlrev_b32_e32 v174, 16, v156
	v_and_b32_e32 v175, 0xffff0000, v156
	v_lshlrev_b32_e32 v176, 16, v157
	v_and_b32_e32 v177, 0xffff0000, v157
	v_mul_f32_e32 v174, v183, v174
	v_mul_f32_e32 v175, v183, v175
	v_mul_f32_e32 v176, v183, v176
	v_mul_f32_e32 v177, v183, v177
	v_fma_f32 v130, v12, v174, v130
	v_fma_f32 v131, v13, v175, v131
	v_fma_f32 v132, v14, v176, v132
	v_fma_f32 v133, v15, v177, v133
	global_store_dwordx4 v166, v[130:133], s[36:37] offset:-1024 nt
	v_fma_f32 v185, v130, v130, v185
	v_fma_f32 v186, v131, v131, v186
	v_fma_f32 v187, v132, v132, v187
	v_fma_f32 v188, v133, v133, v188
	s_waitcnt vmcnt(28)
	v_lshlrev_b32_e32 v174, 16, v158
	v_and_b32_e32 v175, 0xffff0000, v158
	v_lshlrev_b32_e32 v176, 16, v159
	v_and_b32_e32 v177, 0xffff0000, v159
	v_mul_f32_e32 v174, v183, v174
	v_mul_f32_e32 v175, v183, v175
	v_mul_f32_e32 v176, v183, v176
	v_mul_f32_e32 v177, v183, v177
	v_fma_f32 v134, v16, v174, v134
	v_fma_f32 v135, v17, v175, v135
	v_fma_f32 v136, v18, v176, v136
	v_fma_f32 v137, v19, v177, v137
	global_store_dwordx4 v166, v[134:137], s[36:37] offset:0 nt
	v_fma_f32 v185, v134, v134, v185
	v_fma_f32 v186, v135, v135, v186
	v_fma_f32 v187, v136, v136, v187
	v_fma_f32 v188, v137, v137, v188
	s_waitcnt vmcnt(27)
	v_lshlrev_b32_e32 v174, 16, v160
	v_and_b32_e32 v175, 0xffff0000, v160
	v_lshlrev_b32_e32 v176, 16, v161
	v_and_b32_e32 v177, 0xffff0000, v161
	v_mul_f32_e32 v174, v183, v174
	v_mul_f32_e32 v175, v183, v175
	v_mul_f32_e32 v176, v183, v176
	v_mul_f32_e32 v177, v183, v177
	v_fma_f32 v138, v20, v174, v138
	v_fma_f32 v139, v21, v175, v139
	v_fma_f32 v140, v22, v176, v140
	v_fma_f32 v141, v23, v177, v141
	global_store_dwordx4 v166, v[138:141], s[36:37] offset:1024 nt
	v_fma_f32 v185, v138, v138, v185
	v_fma_f32 v186, v139, v139, v186
	v_fma_f32 v187, v140, v140, v187
	v_fma_f32 v188, v141, v141, v188
	s_waitcnt vmcnt(26)
	v_lshlrev_b32_e32 v174, 16, v162
	v_and_b32_e32 v175, 0xffff0000, v162
	v_lshlrev_b32_e32 v176, 16, v163
	v_and_b32_e32 v177, 0xffff0000, v163
	v_mul_f32_e32 v174, v183, v174
	v_mul_f32_e32 v175, v183, v175
	v_mul_f32_e32 v176, v183, v176
	v_mul_f32_e32 v177, v183, v177
	v_fma_f32 v142, v24, v174, v142
	v_fma_f32 v143, v25, v175, v143
	v_fma_f32 v144, v26, v176, v144
	v_fma_f32 v145, v27, v177, v145
	global_store_dwordx4 v166, v[142:145], s[36:37] offset:2048 nt
	v_fma_f32 v185, v142, v142, v185
	v_fma_f32 v186, v143, v143, v186
	v_fma_f32 v187, v144, v144, v187
	v_fma_f32 v188, v145, v145, v188
	s_waitcnt vmcnt(25)
; __device__ __forceinline__ unsigned pk2(float lo, float hi) { return pg8::cvt_pk_bf16(lo, hi); }
; __device__ __forceinline__ float bf_lo(unsigned w) { return __uint_as_float(w << 16); }
; __device__ __forceinline__ float bf_hi(unsigned w) { return __uint_as_float(w & 0xffff0000u); }
; #define P_IN INP(1)
; __global__ void __launch_bounds__(512, 2) fwd(Params P) {
;     ...
;             for (int j = 0; j < 8; ++j) { const f32x4 xv = __builtin_nontemporal_load(&xr[64 * j]); const u32x2 yw = __builtin_nontemporal_load(&yr[64 * j]); const f32x4 g = g1[64 * j];
;                 f32x4 t; t.x = xv.x + bf_lo(yw.x) * rsy * g.x; t.y = xv.y + bf_hi(yw.x) * rsy * g.y; t.z = xv.z + bf_lo(yw.y) * rsy * g.z; t.w = xv.w + bf_hi(yw.y) * rsy * g.w;
;                 v[j] = t; __builtin_nontemporal_store(t, &orow[64 * j]); s += (t.x * t.x + t.y * t.y) + (t.z * t.z + t.w * t.w); }
;             const float rs = __builtin_amdgcn_rsqf(wave_sum(s) * (1.f / DM) + EPS);
;             u32x2* o = (u32x2*)(XN + (size_t)m * DM) + lane;
; #pragma unroll
;             for (int j = 0; j < 8; ++j) { const f32x4 g = g2[64 * j]; u32x2 w; w.x = pk2(v[j].x * rs * g.x, v[j].y * rs * g.y); w.y = pk2(v[j].z * rs * g.z, v[j].w * rs * g.w); o[64 * j] = w; }
;             const f32x4 pv = ((const f32x4*)(P_IN + (size_t)m * PLE))[lane]; u32x2 pw; pw.x = pk2(pv.x, pv.y); pw.y = pk2(pv.z, pv.w);
;             ((u32x2*)(PB + (size_t)m * PLE))[lane] = pw;
	v_lshlrev_b32_e32 v174, 16, v164
	v_and_b32_e32 v175, 0xffff0000, v164
	v_lshlrev_b32_e32 v176, 16, v165
	v_and_b32_e32 v177, 0xffff0000, v165
	v_mul_f32_e32 v174, v183, v174
	v_mul_f32_e32 v175, v183, v175
	v_mul_f32_e32 v176, v183, v176
	v_mul_f32_e32 v177, v183, v177
	v_fma_f32 v146, v28, v174, v146
	v_fma_f32 v147, v29, v175, v147
	v_fma_f32 v148, v30, v176, v148
	v_fma_f32 v149, v31, v177, v149
	global_store_dwordx4 v166, v[146:149], s[36:37] offset:3072 nt
	v_fma_f32 v185, v146, v146, v185
	v_fma_f32 v186, v147, v147, v186
	v_fma_f32 v187, v148, v148, v187
	v_fma_f32 v188, v149, v149, v188
	v_add_f32_e32 v185, v185, v186
	v_add_f32_e32 v187, v187, v188
	v_add_f32_e32 v185, v185, v187
	s_nop 1
	v_add_f32_dpp v185, v185, v185 quad_perm:[1,0,3,2] row_mask:0xf bank_mask:0xf
	s_nop 1
	v_add_f32_dpp v185, v185, v185 quad_perm:[2,3,0,1] row_mask:0xf bank_mask:0xf
	s_nop 1
	v_add_f32_dpp v185, v185, v185 row_half_mirror row_mask:0xf bank_mask:0xf
	s_nop 1
	v_add_f32_dpp v185, v185, v185 row_mirror row_mask:0xf bank_mask:0xf
	s_nop 1
	v_readlane_b32 s24, v185, 0
	v_readlane_b32 s25, v185, 16
	v_readlane_b32 s26, v185, 32
	v_readlane_b32 s27, v185, 48
	v_mov_b32_e32 v184, s24
	v_add_f32_e32 v184, s25, v184
	v_add_f32_e32 v184, s26, v184
	v_add_f32_e32 v184, s27, v184
	v_fmamk_f32 v184, v184, 0x3a000000, v182
	v_rsq_f32_e32 v184, v184
	s_nop 0
	v_mul_f32_e32 v174, v184, v118
	v_mul_f32_e32 v175, v184, v119
	v_mul_f32_e32 v176, v184, v120
	v_mul_f32_e32 v177, v184, v121
	v_mul_f32_e32 v174, v174, v32
	v_mul_f32_e32 v175, v175, v33
	v_mul_f32_e32 v176, v176, v34
	v_mul_f32_e32 v177, v177, v35
	v_cvt_pk_bf16_f32 v150, v174, v175
	v_cvt_pk_bf16_f32 v151, v176, v177
	global_store_dwordx2 v181, v[150:151], s[38:39] offset:0
	v_mul_f32_e32 v174, v184, v122
	v_mul_f32_e32 v175, v184, v123
	v_mul_f32_e32 v176, v184, v124
	v_mul_f32_e32 v177, v184, v125
	v_mul_f32_e32 v174, v174, v36
	v_mul_f32_e32 v175, v175, v37
	v_mul_f32_e32 v176, v176, v38
	v_mul_f32_e32 v177, v177, v39
	v_cvt_pk_bf16_f32 v152, v174, v175
	v_cvt_pk_bf16_f32 v153, v176, v177
	global_store_dwordx2 v181, v[152:153], s[38:39] offset:512
	v_mul_f32_e32 v174, v184, v126
	v_mul_f32_e32 v175, v184, v127
	v_mul_f32_e32 v176, v184, v128
	v_mul_f32_e32 v177, v184, v129
	v_mul_f32_e32 v174, v174, v40
	v_mul_f32_e32 v175, v175, v41
	v_mul_f32_e32 v176, v176, v42
	v_mul_f32_e32 v177, v177, v43
	v_cvt_pk_bf16_f32 v154, v174, v175
	v_cvt_pk_bf16_f32 v155, v176, v177
	global_store_dwordx2 v181, v[154:155], s[38:39] offset:1024
	v_mul_f32_e32 v174, v184, v130
	v_mul_f32_e32 v175, v184, v131
	v_mul_f32_e32 v176, v184, v132
	v_mul_f32_e32 v177, v184, v133
	v_mul_f32_e32 v174, v174, v44
	v_mul_f32_e32 v175, v175, v45
	v_mul_f32_e32 v176, v176, v46
	v_mul_f32_e32 v177, v177, v47
	v_cvt_pk_bf16_f32 v156, v174, v175
	v_cvt_pk_bf16_f32 v157, v176, v177
	global_store_dwordx2 v181, v[156:157], s[38:39] offset:1536
	v_mul_f32_e32 v174, v184, v134
	v_mul_f32_e32 v175, v184, v135
	v_mul_f32_e32 v176, v184, v136
	v_mul_f32_e32 v177, v184, v137
	v_mul_f32_e32 v174, v174, v48
	v_mul_f32_e32 v175, v175, v49
	v_mul_f32_e32 v176, v176, v50
	v_mul_f32_e32 v177, v177, v51
	v_cvt_pk_bf16_f32 v158, v174, v175
	v_cvt_pk_bf16_f32 v159, v176, v177
	global_store_dwordx2 v181, v[158:159], s[38:39] offset:2048
	v_mul_f32_e32 v174, v184, v138
	v_mul_f32_e32 v175, v184, v139
	v_mul_f32_e32 v176, v184, v140
	v_mul_f32_e32 v177, v184, v141
	v_mul_f32_e32 v174, v174, v52
	v_mul_f32_e32 v175, v175, v53
	v_mul_f32_e32 v176, v176, v54
	v_mul_f32_e32 v177, v177, v55
	v_cvt_pk_bf16_f32 v160, v174, v175
	v_cvt_pk_bf16_f32 v161, v176, v177
	global_store_dwordx2 v181, v[160:161], s[38:39] offset:2560
	v_mul_f32_e32 v174, v184, v142
	v_mul_f32_e32 v175, v184, v143
	v_mul_f32_e32 v176, v184, v144
	v_mul_f32_e32 v177, v184, v145
	v_mul_f32_e32 v174, v174, v56
	v_mul_f32_e32 v175, v175, v57
	v_mul_f32_e32 v176, v176, v58
	v_mul_f32_e32 v177, v177, v59
	v_cvt_pk_bf16_f32 v162, v174, v175
	v_cvt_pk_bf16_f32 v163, v176, v177
	global_store_dwordx2 v181, v[162:163], s[38:39] offset:3072
	v_mul_f32_e32 v174, v184, v146
	v_mul_f32_e32 v175, v184, v147
	v_mul_f32_e32 v176, v184, v148
	v_mul_f32_e32 v177, v184, v149
	v_mul_f32_e32 v174, v174, v60
	v_mul_f32_e32 v175, v175, v61
	v_mul_f32_e32 v176, v176, v62
	v_mul_f32_e32 v177, v177, v63
	v_cvt_pk_bf16_f32 v164, v174, v175
	v_cvt_pk_bf16_f32 v165, v176, v177
	global_store_dwordx2 v181, v[164:165], s[38:39] offset:3584
	s_waitcnt vmcnt(33)
	v_cvt_pk_bf16_f32 v170, v170, v171
	v_cvt_pk_bf16_f32 v171, v172, v173
	global_store_dwordx2 v181, v[170:171], s[40:41]

; __device__ __forceinline__ unsigned pk2(float lo, float hi) { return pg8::cvt_pk_bf16(lo, hi); }
; __device__ __forceinline__ float bf_lo(unsigned w) { return __uint_as_float(w << 16); }
; __device__ __forceinline__ float bf_hi(unsigned w) { return __uint_as_float(w & 0xffff0000u); }
; #define INP(i) ((const float*)(const GAS float*)KARG(8 * (i)))
; __global__ void __launch_bounds__(512, 2) fwd(Params P) {
;     ...
;         const f32x4* g1 = (const f32x4*)INP(16) + lane;
;         for (int m = gw; m < T_TOK; m += NGW) {
;             const float rsd = __builtin_amdgcn_rsqf(ssq_d[m] * (1.f / DM) + EPS);
;             const u32x2* dr = (const u32x2*)(DN + (size_t)m * DM) + lane;
;             f32x4* orow = (f32x4*)(OUT_P + (size_t)m * DM) + lane; u32x2* o = (u32x2*)(XN + (size_t)m * DM) + lane;
; #pragma unroll
;             for (int j = 0; j < 8; ++j) { const f32x4 xv = __builtin_nontemporal_load(&orow[64 * j]); const u32x2 dw = __builtin_nontemporal_load(&dr[64 * j]); const f32x4 g = g1[64 * j];
;                 f32x4 t; t.x = xv.x + bf_lo(dw.x) * rsd * g.x; t.y = xv.y + bf_hi(dw.x) * rsd * g.y; t.z = xv.z + bf_lo(dw.y) * rsd * g.z; t.w = xv.w + bf_hi(dw.y) * rsd * g.w;
;                 orow[64 * j] = t; u32x2 w; w.x = pk2(t.x, t.y); w.y = pk2(t.z, t.w); o[64 * j] = w; }
.LBB0_1489:
	s_or_b64 exec, exec, s[8:9]
	s_mov_b64 s[8:9], s[0:1]
	s_and_b64 vcc, exec, s[6:7]
	s_waitcnt lgkmcnt(0)
	s_barrier
	s_cbranch_vccnz .LBB0_1492
	s_load_dwordx2 s[6:7], s[0:1], 0x80
	s_load_dwordx2 s[8:9], s[0:1], 0xa0
	s_load_dwordx2 s[10:11], s[0:1], 0xa8
	v_mov_b32_e32 v167, 0
	v_lshlrev_b32_e32 v32, 3, v179
	v_mov_b32_e32 v33, 0x358637bd
	s_waitcnt lgkmcnt(0)
	s_add_u32 s8, s8, 0x1000
	s_addc_u32 s9, s9, 0
	s_add_u32 s12, s10, 0x60000
	s_addc_u32 s13, s11, 0
	s_add_u32 s14, s10, 0x30000000
	s_addc_u32 s15, s11, 0
	s_add_u32 s16, s10, 0x8000000
	s_addc_u32 s17, s11, 0
	s_add_u32 s28, s6, 0x1000
	s_addc_u32 s29, s7, 0
	global_load_dwordx4 v[0:3], v166, s[6:7] offset:0
	global_load_dwordx4 v[4:7], v166, s[6:7] offset:1024
	global_load_dwordx4 v[8:11], v166, s[6:7] offset:2048
	global_load_dwordx4 v[12:15], v166, s[6:7] offset:3072
	global_load_dwordx4 v[16:19], v166, s[28:29] offset:0
	global_load_dwordx4 v[20:23], v166, s[28:29] offset:1024
	global_load_dwordx4 v[24:27], v166, s[28:29] offset:2048
	global_load_dwordx4 v[28:31], v166, s[28:29] offset:3072
	s_lshl_b32 s30, s80, 13
	s_add_u32 s18, s8, s30
	s_addc_u32 s19, s9, 0
	s_lshl_b32 s30, s80, 12
	s_add_u32 s20, s14, s30
	s_addc_u32 s21, s15, 0
	s_lshl_b32 s30, s80, 2
	s_add_u32 s22, s12, s30
	s_addc_u32 s23, s13, 0
	global_load_dword v88, v167, s[22:23]
	global_load_dwordx4 v[40:43], v166, s[18:19] offset:-4096 nt
	global_load_dwordx2 v[72:73], v32, s[20:21] offset:0 nt
	global_load_dwordx4 v[44:47], v166, s[18:19] offset:-3072 nt
	global_load_dwordx2 v[74:75], v32, s[20:21] offset:512 nt
	global_load_dwordx4 v[48:51], v166, s[18:19] offset:-2048 nt
	global_load_dwordx2 v[76:77], v32, s[20:21] offset:1024 nt
	global_load_dwordx4 v[52:55], v166, s[18:19] offset:-1024 nt
	global_load_dwordx2 v[78:79], v32, s[20:21] offset:1536 nt
	global_load_dwordx4 v[56:59], v166, s[18:19] offset:0 nt
	global_load_dwordx2 v[80:81], v32, s[20:21] offset:2048 nt
	global_load_dwordx4 v[60:63], v166, s[18:19] offset:1024 nt
	global_load_dwordx2 v[82:83], v32, s[20:21] offset:2560 nt
	global_load_dwordx4 v[64:67], v166, s[18:19] offset:2048 nt
	global_load_dwordx2 v[84:85], v32, s[20:21] offset:3072 nt
	global_load_dwordx4 v[68:71], v166, s[18:19] offset:3072 nt
	global_load_dwordx2 v[86:87], v32, s[20:21] offset:3584 nt
	s_mov_b64 s[24:25], s[18:19]
	s_lshl_b32 s30, s80, 12
	s_add_u32 s26, s16, s30
	s_addc_u32 s27, s17, 0
	s_add_i32 s31, s80, s82
	s_cmpk_gt_i32 s31, 0x7fff
	s_cbranch_scc1 .Lp7b_tail_a
	s_lshl_b32 s30, s31, 13
	s_add_u32 s18, s8, s30
	s_addc_u32 s19, s9, 0
	s_lshl_b32 s30, s31, 12
	s_add_u32 s20, s14, s30
	s_addc_u32 s21, s15, 0
	s_lshl_b32 s30, s31, 2
	s_add_u32 s22, s12, s30
	s_addc_u32 s23, s13, 0
	global_load_dword v144, v167, s[22:23]
	global_load_dwordx4 v[96:99], v166, s[18:19] offset:-4096 nt
	global_load_dwordx2 v[128:129], v32, s[20:21] offset:0 nt
	global_load_dwordx4 v[100:103], v166, s[18:19] offset:-3072 nt
	global_load_dwordx2 v[130:131], v32, s[20:21] offset:512 nt
	global_load_dwordx4 v[104:107], v166, s[18:19] offset:-2048 nt
	global_load_dwordx2 v[132:133], v32, s[20:21] offset:1024 nt
	global_load_dwordx4 v[108:111], v166, s[18:19] offset:-1024 nt
	global_load_dwordx2 v[134:135], v32, s[20:21] offset:1536 nt
	global_load_dwordx4 v[112:115], v166, s[18:19] offset:0 nt
	global_load_dwordx2 v[136:137], v32, s[20:21] offset:2048 nt
	global_load_dwordx4 v[116:119], v166, s[18:19] offset:1024 nt
	global_load_dwordx2 v[138:139], v32, s[20:21] offset:2560 nt
	global_load_dwordx4 v[120:123], v166, s[18:19] offset:2048 nt
	global_load_dwordx2 v[140:141], v32, s[20:21] offset:3072 nt
	global_load_dwordx4 v[124:127], v166, s[18:19] offset:3072 nt
	global_load_dwordx2 v[142:143], v32, s[20:21] offset:3584 nt
	s_waitcnt vmcnt(31)
	v_fmamk_f32 v34, v88, 0x3a000000, v33
	v_rsq_f32_e32 v34, v34
	v_lshlrev_b32_e32 v35, 16, v72
	v_and_b32_e32 v36, 0xffff0000, v72
	v_lshlrev_b32_e32 v37, 16, v73
	v_and_b32_e32 v38, 0xffff0000, v73
	v_mul_f32_e32 v35, v34, v35
	v_mul_f32_e32 v36, v34, v36
	v_mul_f32_e32 v37, v34, v37
	v_mul_f32_e32 v38, v34, v38
	v_fma_f32 v40, v0, v35, v40
	v_fma_f32 v41, v1, v36, v41
	v_fma_f32 v42, v2, v37, v42
	v_fma_f32 v43, v3, v38, v43
	global_store_dwordx4 v166, v[40:43], s[24:25] offset:-4096
	v_cvt_pk_bf16_f32 v72, v40, v41
	v_cvt_pk_bf16_f32 v73, v42, v43
	global_store_dwordx2 v32, v[72:73], s[26:27] offset:0
	s_waitcnt vmcnt(31)
	v_lshlrev_b32_e32 v35, 16, v74
	v_and_b32_e32 v36, 0xffff0000, v74
	v_lshlrev_b32_e32 v37, 16, v75
	v_and_b32_e32 v38, 0xffff0000, v75
	v_mul_f32_e32 v35, v34, v35
	v_mul_f32_e32 v36, v34, v36
	v_mul_f32_e32 v37, v34, v37
	v_mul_f32_e32 v38, v34, v38
	v_fma_f32 v44, v4, v35, v44
	v_fma_f32 v45, v5, v36, v45
	v_fma_f32 v46, v6, v37, v46
	v_fma_f32 v47, v7, v38, v47
	global_store_dwordx4 v166, v[44:47], s[24:25] offset:-3072
	v_cvt_pk_bf16_f32 v74, v44, v45
	v_cvt_pk_bf16_f32 v75, v46, v47
	global_store_dwordx2 v32, v[74:75], s[26:27] offset:512
	s_waitcnt vmcnt(31)
	v_lshlrev_b32_e32 v35, 16, v76
	v_and_b32_e32 v36, 0xffff0000, v76
	v_lshlrev_b32_e32 v37, 16, v77
	v_and_b32_e32 v38, 0xffff0000, v77
	v_mul_f32_e32 v35, v34, v35
	v_mul_f32_e32 v36, v34, v36
	v_mul_f32_e32 v37, v34, v37
	v_mul_f32_e32 v38, v34, v38
	v_fma_f32 v48, v8, v35, v48
	v_fma_f32 v49, v9, v36, v49
	v_fma_f32 v50, v10, v37, v50
	v_fma_f32 v51, v11, v38, v51
	global_store_dwordx4 v166, v[48:51], s[24:25] offset:-2048
	v_cvt_pk_bf16_f32 v76, v48, v49
	v_cvt_pk_bf16_f32 v77, v50, v51
	global_store_dwordx2 v32, v[76:77], s[26:27] offset:1024
	s_waitcnt vmcnt(31)
; __device__ __forceinline__ unsigned pk2(float lo, float hi) { return pg8::cvt_pk_bf16(lo, hi); }
; __device__ __forceinline__ float bf_lo(unsigned w) { return __uint_as_float(w << 16); }
; __device__ __forceinline__ float bf_hi(unsigned w) { return __uint_as_float(w & 0xffff0000u); }
; __global__ void __launch_bounds__(512, 2) fwd(Params P) {
;     ...
;         for (int m = gw; m < T_TOK; m += NGW) {
;             const float rsd = __builtin_amdgcn_rsqf(ssq_d[m] * (1.f / DM) + EPS);
;             const u32x2* dr = (const u32x2*)(DN + (size_t)m * DM) + lane;
;             f32x4* orow = (f32x4*)(OUT_P + (size_t)m * DM) + lane; u32x2* o = (u32x2*)(XN + (size_t)m * DM) + lane;
; #pragma unroll
;             for (int j = 0; j < 8; ++j) { const f32x4 xv = __builtin_nontemporal_load(&orow[64 * j]); const u32x2 dw = __builtin_nontemporal_load(&dr[64 * j]); const f32x4 g = g1[64 * j];
;                 f32x4 t; t.x = xv.x + bf_lo(dw.x) * rsd * g.x; t.y = xv.y + bf_hi(dw.x) * rsd * g.y; t.z = xv.z + bf_lo(dw.y) * rsd * g.z; t.w = xv.w + bf_hi(dw.y) * rsd * g.w;
;                 orow[64 * j] = t; u32x2 w; w.x = pk2(t.x, t.y); w.y = pk2(t.z, t.w); o[64 * j] = w; }
	v_lshlrev_b32_e32 v35, 16, v78
	v_and_b32_e32 v36, 0xffff0000, v78
	v_lshlrev_b32_e32 v37, 16, v79
	v_and_b32_e32 v38, 0xffff0000, v79
	v_mul_f32_e32 v35, v34, v35
	v_mul_f32_e32 v36, v34, v36
	v_mul_f32_e32 v37, v34, v37
	v_mul_f32_e32 v38, v34, v38
	v_fma_f32 v52, v12, v35, v52
	v_fma_f32 v53, v13, v36, v53
	v_fma_f32 v54, v14, v37, v54
	v_fma_f32 v55, v15, v38, v55
	global_store_dwordx4 v166, v[52:55], s[24:25] offset:-1024
	v_cvt_pk_bf16_f32 v78, v52, v53
	v_cvt_pk_bf16_f32 v79, v54, v55
	global_store_dwordx2 v32, v[78:79], s[26:27] offset:1536
	s_waitcnt vmcnt(31)
	v_lshlrev_b32_e32 v35, 16, v80
	v_and_b32_e32 v36, 0xffff0000, v80
	v_lshlrev_b32_e32 v37, 16, v81
	v_and_b32_e32 v38, 0xffff0000, v81
	v_mul_f32_e32 v35, v34, v35
	v_mul_f32_e32 v36, v34, v36
	v_mul_f32_e32 v37, v34, v37
	v_mul_f32_e32 v38, v34, v38
	v_fma_f32 v56, v16, v35, v56
	v_fma_f32 v57, v17, v36, v57
	v_fma_f32 v58, v18, v37, v58
	v_fma_f32 v59, v19, v38, v59
	global_store_dwordx4 v166, v[56:59], s[24:25] offset:0
	v_cvt_pk_bf16_f32 v80, v56, v57
	v_cvt_pk_bf16_f32 v81, v58, v59
	global_store_dwordx2 v32, v[80:81], s[26:27] offset:2048
	s_waitcnt vmcnt(31)
	v_lshlrev_b32_e32 v35, 16, v82
	v_and_b32_e32 v36, 0xffff0000, v82
	v_lshlrev_b32_e32 v37, 16, v83
	v_and_b32_e32 v38, 0xffff0000, v83
	v_mul_f32_e32 v35, v34, v35
	v_mul_f32_e32 v36, v34, v36
	v_mul_f32_e32 v37, v34, v37
	v_mul_f32_e32 v38, v34, v38
	v_fma_f32 v60, v20, v35, v60
	v_fma_f32 v61, v21, v36, v61
	v_fma_f32 v62, v22, v37, v62
	v_fma_f32 v63, v23, v38, v63
	global_store_dwordx4 v166, v[60:63], s[24:25] offset:1024
	v_cvt_pk_bf16_f32 v82, v60, v61
	v_cvt_pk_bf16_f32 v83, v62, v63
	global_store_dwordx2 v32, v[82:83], s[26:27] offset:2560
	s_waitcnt vmcnt(31)
	v_lshlrev_b32_e32 v35, 16, v84
	v_and_b32_e32 v36, 0xffff0000, v84
	v_lshlrev_b32_e32 v37, 16, v85
	v_and_b32_e32 v38, 0xffff0000, v85
	v_mul_f32_e32 v35, v34, v35
	v_mul_f32_e32 v36, v34, v36
	v_mul_f32_e32 v37, v34, v37
	v_mul_f32_e32 v38, v34, v38
	v_fma_f32 v64, v24, v35, v64
	v_fma_f32 v65, v25, v36, v65
	v_fma_f32 v66, v26, v37, v66
	v_fma_f32 v67, v27, v38, v67
	global_store_dwordx4 v166, v[64:67], s[24:25] offset:2048
	v_cvt_pk_bf16_f32 v84, v64, v65
	v_cvt_pk_bf16_f32 v85, v66, v67
	global_store_dwordx2 v32, v[84:85], s[26:27] offset:3072
	s_waitcnt vmcnt(31)
	v_lshlrev_b32_e32 v35, 16, v86
	v_and_b32_e32 v36, 0xffff0000, v86
	v_lshlrev_b32_e32 v37, 16, v87
	v_and_b32_e32 v38, 0xffff0000, v87
	v_mul_f32_e32 v35, v34, v35
	v_mul_f32_e32 v36, v34, v36
	v_mul_f32_e32 v37, v34, v37
	v_mul_f32_e32 v38, v34, v38
	v_fma_f32 v68, v28, v35, v68
	v_fma_f32 v69, v29, v36, v69
	v_fma_f32 v70, v30, v37, v70
	v_fma_f32 v71, v31, v38, v71
	global_store_dwordx4 v166, v[68:71], s[24:25] offset:3072
	v_cvt_pk_bf16_f32 v86, v68, v69
	v_cvt_pk_bf16_f32 v87, v70, v71
	global_store_dwordx2 v32, v[86:87], s[26:27] offset:3584
	s_mov_b32 s80, s31
.Lp7b_loop:
	s_mov_b64 s[24:25], s[18:19]
	s_lshl_b32 s30, s80, 12
	s_add_u32 s26, s16, s30
	s_addc_u32 s27, s17, 0
	s_add_i32 s31, s80, s82
	s_cmpk_gt_i32 s31, 0x7fff
	s_cbranch_scc1 .Lp7b_tail_b
	s_lshl_b32 s30, s31, 13
	s_add_u32 s18, s8, s30
	s_addc_u32 s19, s9, 0
	s_lshl_b32 s30, s31, 12
	s_add_u32 s20, s14, s30
	s_addc_u32 s21, s15, 0
	s_lshl_b32 s30, s31, 2
	s_add_u32 s22, s12, s30
	s_addc_u32 s23, s13, 0
	global_load_dword v88, v167, s[22:23]
	global_load_dwordx4 v[40:43], v166, s[18:19] offset:-4096 nt
	global_load_dwordx2 v[72:73], v32, s[20:21] offset:0 nt
	global_load_dwordx4 v[44:47], v166, s[18:19] offset:-3072 nt
	global_load_dwordx2 v[74:75], v32, s[20:21] offset:512 nt
	global_load_dwordx4 v[48:51], v166, s[18:19] offset:-2048 nt
	global_load_dwordx2 v[76:77], v32, s[20:21] offset:1024 nt
	global_load_dwordx4 v[52:55], v166, s[18:19] offset:-1024 nt
	global_load_dwordx2 v[78:79], v32, s[20:21] offset:1536 nt
	global_load_dwordx4 v[56:59], v166, s[18:19] offset:0 nt
	global_load_dwordx2 v[80:81], v32, s[20:21] offset:2048 nt
	global_load_dwordx4 v[60:63], v166, s[18:19] offset:1024 nt
	global_load_dwordx2 v[82:83], v32, s[20:21] offset:2560 nt
	global_load_dwordx4 v[64:67], v166, s[18:19] offset:2048 nt
	global_load_dwordx2 v[84:85], v32, s[20:21] offset:3072 nt
	global_load_dwordx4 v[68:71], v166, s[18:19] offset:3072 nt
	global_load_dwordx2 v[86:87], v32, s[20:21] offset:3584 nt
	s_waitcnt vmcnt(47)
	v_fmamk_f32 v34, v144, 0x3a000000, v33
	v_rsq_f32_e32 v34, v34
	v_lshlrev_b32_e32 v35, 16, v128
	v_and_b32_e32 v36, 0xffff0000, v128
	v_lshlrev_b32_e32 v37, 16, v129
	v_and_b32_e32 v38, 0xffff0000, v129
	v_mul_f32_e32 v35, v34, v35
	v_mul_f32_e32 v36, v34, v36
	v_mul_f32_e32 v37, v34, v37
	v_mul_f32_e32 v38, v34, v38
	v_fma_f32 v96, v0, v35, v96
	v_fma_f32 v97, v1, v36, v97
	v_fma_f32 v98, v2, v37, v98
	v_fma_f32 v99, v3, v38, v99
	global_store_dwordx4 v166, v[96:99], s[24:25] offset:-4096
	v_cvt_pk_bf16_f32 v128, v96, v97
	v_cvt_pk_bf16_f32 v129, v98, v99
	global_store_dwordx2 v32, v[128:129], s[26:27] offset:0
	s_waitcnt vmcnt(47)
	v_lshlrev_b32_e32 v35, 16, v130
	v_and_b32_e32 v36, 0xffff0000, v130
	v_lshlrev_b32_e32 v37, 16, v131
	v_and_b32_e32 v38, 0xffff0000, v131
	v_mul_f32_e32 v35, v34, v35
	v_mul_f32_e32 v36, v34, v36
	v_mul_f32_e32 v37, v34, v37
	v_mul_f32_e32 v38, v34, v38
	v_fma_f32 v100, v4, v35, v100
	v_fma_f32 v101, v5, v36, v101
	v_fma_f32 v102, v6, v37, v102
	v_fma_f32 v103, v7, v38, v103
	global_store_dwordx4 v166, v[100:103], s[24:25] offset:-3072
	v_cvt_pk_bf16_f32 v130, v100, v101
	v_cvt_pk_bf16_f32 v131, v102, v103
	global_store_dwordx2 v32, v[130:131], s[26:27] offset:512
	s_waitcnt vmcnt(47)
; __device__ __forceinline__ unsigned pk2(float lo, float hi) { return pg8::cvt_pk_bf16(lo, hi); }
; __device__ __forceinline__ float bf_lo(unsigned w) { return __uint_as_float(w << 16); }
; __device__ __forceinline__ float bf_hi(unsigned w) { return __uint_as_float(w & 0xffff0000u); }
; __global__ void __launch_bounds__(512, 2) fwd(Params P) {
;     ...
;         for (int m = gw; m < T_TOK; m += NGW) {
;             const float rsd = __builtin_amdgcn_rsqf(ssq_d[m] * (1.f / DM) + EPS);
;             const u32x2* dr = (const u32x2*)(DN + (size_t)m * DM) + lane;
;             f32x4* orow = (f32x4*)(OUT_P + (size_t)m * DM) + lane; u32x2* o = (u32x2*)(XN + (size_t)m * DM) + lane;
; #pragma unroll
;             for (int j = 0; j < 8; ++j) { const f32x4 xv = __builtin_nontemporal_load(&orow[64 * j]); const u32x2 dw = __builtin_nontemporal_load(&dr[64 * j]); const f32x4 g = g1[64 * j];
;                 f32x4 t; t.x = xv.x + bf_lo(dw.x) * rsd * g.x; t.y = xv.y + bf_hi(dw.x) * rsd * g.y; t.z = xv.z + bf_lo(dw.y) * rsd * g.z; t.w = xv.w + bf_hi(dw.y) * rsd * g.w;
;                 orow[64 * j] = t; u32x2 w; w.x = pk2(t.x, t.y); w.y = pk2(t.z, t.w); o[64 * j] = w; }
	v_lshlrev_b32_e32 v35, 16, v132
	v_and_b32_e32 v36, 0xffff0000, v132
	v_lshlrev_b32_e32 v37, 16, v133
	v_and_b32_e32 v38, 0xffff0000, v133
	v_mul_f32_e32 v35, v34, v35
	v_mul_f32_e32 v36, v34, v36
	v_mul_f32_e32 v37, v34, v37
	v_mul_f32_e32 v38, v34, v38
	v_fma_f32 v104, v8, v35, v104
	v_fma_f32 v105, v9, v36, v105
	v_fma_f32 v106, v10, v37, v106
	v_fma_f32 v107, v11, v38, v107
	global_store_dwordx4 v166, v[104:107], s[24:25] offset:-2048
	v_cvt_pk_bf16_f32 v132, v104, v105
	v_cvt_pk_bf16_f32 v133, v106, v107
	global_store_dwordx2 v32, v[132:133], s[26:27] offset:1024
	s_waitcnt vmcnt(47)
	v_lshlrev_b32_e32 v35, 16, v134
	v_and_b32_e32 v36, 0xffff0000, v134
	v_lshlrev_b32_e32 v37, 16, v135
	v_and_b32_e32 v38, 0xffff0000, v135
	v_mul_f32_e32 v35, v34, v35
	v_mul_f32_e32 v36, v34, v36
	v_mul_f32_e32 v37, v34, v37
	v_mul_f32_e32 v38, v34, v38
	v_fma_f32 v108, v12, v35, v108
	v_fma_f32 v109, v13, v36, v109
	v_fma_f32 v110, v14, v37, v110
	v_fma_f32 v111, v15, v38, v111
	global_store_dwordx4 v166, v[108:111], s[24:25] offset:-1024
	v_cvt_pk_bf16_f32 v134, v108, v109
	v_cvt_pk_bf16_f32 v135, v110, v111
	global_store_dwordx2 v32, v[134:135], s[26:27] offset:1536
	s_waitcnt vmcnt(47)
	v_lshlrev_b32_e32 v35, 16, v136
	v_and_b32_e32 v36, 0xffff0000, v136
	v_lshlrev_b32_e32 v37, 16, v137
	v_and_b32_e32 v38, 0xffff0000, v137
	v_mul_f32_e32 v35, v34, v35
	v_mul_f32_e32 v36, v34, v36
	v_mul_f32_e32 v37, v34, v37
	v_mul_f32_e32 v38, v34, v38
	v_fma_f32 v112, v16, v35, v112
	v_fma_f32 v113, v17, v36, v113
	v_fma_f32 v114, v18, v37, v114
	v_fma_f32 v115, v19, v38, v115
	global_store_dwordx4 v166, v[112:115], s[24:25] offset:0
	v_cvt_pk_bf16_f32 v136, v112, v113
	v_cvt_pk_bf16_f32 v137, v114, v115
	global_store_dwordx2 v32, v[136:137], s[26:27] offset:2048
	s_waitcnt vmcnt(47)
	v_lshlrev_b32_e32 v35, 16, v138
	v_and_b32_e32 v36, 0xffff0000, v138
	v_lshlrev_b32_e32 v37, 16, v139
	v_and_b32_e32 v38, 0xffff0000, v139
	v_mul_f32_e32 v35, v34, v35
	v_mul_f32_e32 v36, v34, v36
	v_mul_f32_e32 v37, v34, v37
	v_mul_f32_e32 v38, v34, v38
	v_fma_f32 v116, v20, v35, v116
	v_fma_f32 v117, v21, v36, v117
	v_fma_f32 v118, v22, v37, v118
	v_fma_f32 v119, v23, v38, v119
	global_store_dwordx4 v166, v[116:119], s[24:25] offset:1024
	v_cvt_pk_bf16_f32 v138, v116, v117
	v_cvt_pk_bf16_f32 v139, v118, v119
	global_store_dwordx2 v32, v[138:139], s[26:27] offset:2560
	s_waitcnt vmcnt(47)
	v_lshlrev_b32_e32 v35, 16, v140
	v_and_b32_e32 v36, 0xffff0000, v140
	v_lshlrev_b32_e32 v37, 16, v141
	v_and_b32_e32 v38, 0xffff0000, v141
	v_mul_f32_e32 v35, v34, v35
	v_mul_f32_e32 v36, v34, v36
	v_mul_f32_e32 v37, v34, v37
	v_mul_f32_e32 v38, v34, v38
	v_fma_f32 v120, v24, v35, v120
	v_fma_f32 v121, v25, v36, v121
	v_fma_f32 v122, v26, v37, v122
	v_fma_f32 v123, v27, v38, v123
	global_store_dwordx4 v166, v[120:123], s[24:25] offset:2048
	v_cvt_pk_bf16_f32 v140, v120, v121
	v_cvt_pk_bf16_f32 v141, v122, v123
	global_store_dwordx2 v32, v[140:141], s[26:27] offset:3072
	s_waitcnt vmcnt(47)
	v_lshlrev_b32_e32 v35, 16, v142
	v_and_b32_e32 v36, 0xffff0000, v142
	v_lshlrev_b32_e32 v37, 16, v143
	v_and_b32_e32 v38, 0xffff0000, v143
	v_mul_f32_e32 v35, v34, v35
	v_mul_f32_e32 v36, v34, v36
	v_mul_f32_e32 v37, v34, v37
	v_mul_f32_e32 v38, v34, v38
	v_fma_f32 v124, v28, v35, v124
	v_fma_f32 v125, v29, v36, v125
	v_fma_f32 v126, v30, v37, v126
	v_fma_f32 v127, v31, v38, v127
	global_store_dwordx4 v166, v[124:127], s[24:25] offset:3072
	v_cvt_pk_bf16_f32 v142, v124, v125
	v_cvt_pk_bf16_f32 v143, v126, v127
	global_store_dwordx2 v32, v[142:143], s[26:27] offset:3584
	s_mov_b32 s80, s31
	s_mov_b64 s[24:25], s[18:19]
	s_lshl_b32 s30, s80, 12
	s_add_u32 s26, s16, s30
	s_addc_u32 s27, s17, 0
	s_add_i32 s31, s80, s82
	s_cmpk_gt_i32 s31, 0x7fff
	s_cbranch_scc1 .Lp7b_tail_a
	s_lshl_b32 s30, s31, 13
	s_add_u32 s18, s8, s30
	s_addc_u32 s19, s9, 0
	s_lshl_b32 s30, s31, 12
	s_add_u32 s20, s14, s30
	s_addc_u32 s21, s15, 0
	s_lshl_b32 s30, s31, 2
	s_add_u32 s22, s12, s30
	s_addc_u32 s23, s13, 0
	global_load_dword v144, v167, s[22:23]
	global_load_dwordx4 v[96:99], v166, s[18:19] offset:-4096 nt
	global_load_dwordx2 v[128:129], v32, s[20:21] offset:0 nt
	global_load_dwordx4 v[100:103], v166, s[18:19] offset:-3072 nt
	global_load_dwordx2 v[130:131], v32, s[20:21] offset:512 nt
	global_load_dwordx4 v[104:107], v166, s[18:19] offset:-2048 nt
	global_load_dwordx2 v[132:133], v32, s[20:21] offset:1024 nt
	global_load_dwordx4 v[108:111], v166, s[18:19] offset:-1024 nt
	global_load_dwordx2 v[134:135], v32, s[20:21] offset:1536 nt
	global_load_dwordx4 v[112:115], v166, s[18:19] offset:0 nt
	global_load_dwordx2 v[136:137], v32, s[20:21] offset:2048 nt
	global_load_dwordx4 v[116:119], v166, s[18:19] offset:1024 nt
	global_load_dwordx2 v[138:139], v32, s[20:21] offset:2560 nt
	global_load_dwordx4 v[120:123], v166, s[18:19] offset:2048 nt
	global_load_dwordx2 v[140:141], v32, s[20:21] offset:3072 nt
	global_load_dwordx4 v[124:127], v166, s[18:19] offset:3072 nt
	global_load_dwordx2 v[142:143], v32, s[20:21] offset:3584 nt
	s_waitcnt vmcnt(47)
	v_fmamk_f32 v34, v88, 0x3a000000, v33
	v_rsq_f32_e32 v34, v34
	v_lshlrev_b32_e32 v35, 16, v72
	v_and_b32_e32 v36, 0xffff0000, v72
	v_lshlrev_b32_e32 v37, 16, v73
	v_and_b32_e32 v38, 0xffff0000, v73
	v_mul_f32_e32 v35, v34, v35
	v_mul_f32_e32 v36, v34, v36
	v_mul_f32_e32 v37, v34, v37
	v_mul_f32_e32 v38, v34, v38
	v_fma_f32 v40, v0, v35, v40
	v_fma_f32 v41, v1, v36, v41
	v_fma_f32 v42, v2, v37, v42
	v_fma_f32 v43, v3, v38, v43
	global_store_dwordx4 v166, v[40:43], s[24:25] offset:-4096
	v_cvt_pk_bf16_f32 v72, v40, v41
	v_cvt_pk_bf16_f32 v73, v42, v43
	global_store_dwordx2 v32, v[72:73], s[26:27] offset:0
	s_waitcnt vmcnt(47)
; __device__ __forceinline__ unsigned pk2(float lo, float hi) { return pg8::cvt_pk_bf16(lo, hi); }
; __device__ __forceinline__ float bf_lo(unsigned w) { return __uint_as_float(w << 16); }
; __device__ __forceinline__ float bf_hi(unsigned w) { return __uint_as_float(w & 0xffff0000u); }
; __global__ void __launch_bounds__(512, 2) fwd(Params P) {
;     ...
;         for (int m = gw; m < T_TOK; m += NGW) {
;             const float rsd = __builtin_amdgcn_rsqf(ssq_d[m] * (1.f / DM) + EPS);
;             const u32x2* dr = (const u32x2*)(DN + (size_t)m * DM) + lane;
;             f32x4* orow = (f32x4*)(OUT_P + (size_t)m * DM) + lane; u32x2* o = (u32x2*)(XN + (size_t)m * DM) + lane;
; #pragma unroll
;             for (int j = 0; j < 8; ++j) { const f32x4 xv = __builtin_nontemporal_load(&orow[64 * j]); const u32x2 dw = __builtin_nontemporal_load(&dr[64 * j]); const f32x4 g = g1[64 * j];
;                 f32x4 t; t.x = xv.x + bf_lo(dw.x) * rsd * g.x; t.y = xv.y + bf_hi(dw.x) * rsd * g.y; t.z = xv.z + bf_lo(dw.y) * rsd * g.z; t.w = xv.w + bf_hi(dw.y) * rsd * g.w;
;                 orow[64 * j] = t; u32x2 w; w.x = pk2(t.x, t.y); w.y = pk2(t.z, t.w); o[64 * j] = w; }
	v_lshlrev_b32_e32 v35, 16, v74
	v_and_b32_e32 v36, 0xffff0000, v74
	v_lshlrev_b32_e32 v37, 16, v75
	v_and_b32_e32 v38, 0xffff0000, v75
	v_mul_f32_e32 v35, v34, v35
	v_mul_f32_e32 v36, v34, v36
	v_mul_f32_e32 v37, v34, v37
	v_mul_f32_e32 v38, v34, v38
	v_fma_f32 v44, v4, v35, v44
	v_fma_f32 v45, v5, v36, v45
	v_fma_f32 v46, v6, v37, v46
	v_fma_f32 v47, v7, v38, v47
	global_store_dwordx4 v166, v[44:47], s[24:25] offset:-3072
	v_cvt_pk_bf16_f32 v74, v44, v45
	v_cvt_pk_bf16_f32 v75, v46, v47
	global_store_dwordx2 v32, v[74:75], s[26:27] offset:512
	s_waitcnt vmcnt(47)
	v_lshlrev_b32_e32 v35, 16, v76
	v_and_b32_e32 v36, 0xffff0000, v76
	v_lshlrev_b32_e32 v37, 16, v77
	v_and_b32_e32 v38, 0xffff0000, v77
	v_mul_f32_e32 v35, v34, v35
	v_mul_f32_e32 v36, v34, v36
	v_mul_f32_e32 v37, v34, v37
	v_mul_f32_e32 v38, v34, v38
	v_fma_f32 v48, v8, v35, v48
	v_fma_f32 v49, v9, v36, v49
	v_fma_f32 v50, v10, v37, v50
	v_fma_f32 v51, v11, v38, v51
	global_store_dwordx4 v166, v[48:51], s[24:25] offset:-2048
	v_cvt_pk_bf16_f32 v76, v48, v49
	v_cvt_pk_bf16_f32 v77, v50, v51
	global_store_dwordx2 v32, v[76:77], s[26:27] offset:1024
	s_waitcnt vmcnt(47)
	v_lshlrev_b32_e32 v35, 16, v78
	v_and_b32_e32 v36, 0xffff0000, v78
	v_lshlrev_b32_e32 v37, 16, v79
	v_and_b32_e32 v38, 0xffff0000, v79
	v_mul_f32_e32 v35, v34, v35
	v_mul_f32_e32 v36, v34, v36
	v_mul_f32_e32 v37, v34, v37
	v_mul_f32_e32 v38, v34, v38
	v_fma_f32 v52, v12, v35, v52
	v_fma_f32 v53, v13, v36, v53
	v_fma_f32 v54, v14, v37, v54
	v_fma_f32 v55, v15, v38, v55
	global_store_dwordx4 v166, v[52:55], s[24:25] offset:-1024
	v_cvt_pk_bf16_f32 v78, v52, v53
	v_cvt_pk_bf16_f32 v79, v54, v55
	global_store_dwordx2 v32, v[78:79], s[26:27] offset:1536
	s_waitcnt vmcnt(47)
	v_lshlrev_b32_e32 v35, 16, v80
	v_and_b32_e32 v36, 0xffff0000, v80
	v_lshlrev_b32_e32 v37, 16, v81
	v_and_b32_e32 v38, 0xffff0000, v81
	v_mul_f32_e32 v35, v34, v35
	v_mul_f32_e32 v36, v34, v36
	v_mul_f32_e32 v37, v34, v37
	v_mul_f32_e32 v38, v34, v38
	v_fma_f32 v56, v16, v35, v56
	v_fma_f32 v57, v17, v36, v57
	v_fma_f32 v58, v18, v37, v58
	v_fma_f32 v59, v19, v38, v59
	global_store_dwordx4 v166, v[56:59], s[24:25] offset:0
	v_cvt_pk_bf16_f32 v80, v56, v57
	v_cvt_pk_bf16_f32 v81, v58, v59
	global_store_dwordx2 v32, v[80:81], s[26:27] offset:2048
	s_waitcnt vmcnt(47)
	v_lshlrev_b32_e32 v35, 16, v82
	v_and_b32_e32 v36, 0xffff0000, v82
	v_lshlrev_b32_e32 v37, 16, v83
	v_and_b32_e32 v38, 0xffff0000, v83
	v_mul_f32_e32 v35, v34, v35
	v_mul_f32_e32 v36, v34, v36
	v_mul_f32_e32 v37, v34, v37
	v_mul_f32_e32 v38, v34, v38
	v_fma_f32 v60, v20, v35, v60
	v_fma_f32 v61, v21, v36, v61
	v_fma_f32 v62, v22, v37, v62
	v_fma_f32 v63, v23, v38, v63
	global_store_dwordx4 v166, v[60:63], s[24:25] offset:1024
	v_cvt_pk_bf16_f32 v82, v60, v61
	v_cvt_pk_bf16_f32 v83, v62, v63
	global_store_dwordx2 v32, v[82:83], s[26:27] offset:2560
	s_waitcnt vmcnt(47)
	v_lshlrev_b32_e32 v35, 16, v84
	v_and_b32_e32 v36, 0xffff0000, v84
	v_lshlrev_b32_e32 v37, 16, v85
	v_and_b32_e32 v38, 0xffff0000, v85
	v_mul_f32_e32 v35, v34, v35
	v_mul_f32_e32 v36, v34, v36
	v_mul_f32_e32 v37, v34, v37
	v_mul_f32_e32 v38, v34, v38
	v_fma_f32 v64, v24, v35, v64
	v_fma_f32 v65, v25, v36, v65
	v_fma_f32 v66, v26, v37, v66
	v_fma_f32 v67, v27, v38, v67
	global_store_dwordx4 v166, v[64:67], s[24:25] offset:2048
	v_cvt_pk_bf16_f32 v84, v64, v65
	v_cvt_pk_bf16_f32 v85, v66, v67
	global_store_dwordx2 v32, v[84:85], s[26:27] offset:3072
	s_waitcnt vmcnt(47)
	v_lshlrev_b32_e32 v35, 16, v86
	v_and_b32_e32 v36, 0xffff0000, v86
	v_lshlrev_b32_e32 v37, 16, v87
	v_and_b32_e32 v38, 0xffff0000, v87
	v_mul_f32_e32 v35, v34, v35
	v_mul_f32_e32 v36, v34, v36
	v_mul_f32_e32 v37, v34, v37
	v_mul_f32_e32 v38, v34, v38
	v_fma_f32 v68, v28, v35, v68
	v_fma_f32 v69, v29, v36, v69
	v_fma_f32 v70, v30, v37, v70
	v_fma_f32 v71, v31, v38, v71
	global_store_dwordx4 v166, v[68:71], s[24:25] offset:3072
	v_cvt_pk_bf16_f32 v86, v68, v69
	v_cvt_pk_bf16_f32 v87, v70, v71
	global_store_dwordx2 v32, v[86:87], s[26:27] offset:3584
	s_mov_b32 s80, s31
	s_branch .Lp7b_loop
.Lp7b_tail_a:
	s_waitcnt vmcnt(30)
	v_fmamk_f32 v34, v88, 0x3a000000, v33
	v_rsq_f32_e32 v34, v34
	v_lshlrev_b32_e32 v35, 16, v72
	v_and_b32_e32 v36, 0xffff0000, v72
	v_lshlrev_b32_e32 v37, 16, v73
	v_and_b32_e32 v38, 0xffff0000, v73
	v_mul_f32_e32 v35, v34, v35
	v_mul_f32_e32 v36, v34, v36
	v_mul_f32_e32 v37, v34, v37
	v_mul_f32_e32 v38, v34, v38
	v_fma_f32 v40, v0, v35, v40
	v_fma_f32 v41, v1, v36, v41
	v_fma_f32 v42, v2, v37, v42
	v_fma_f32 v43, v3, v38, v43
	global_store_dwordx4 v166, v[40:43], s[24:25] offset:-4096
	v_cvt_pk_bf16_f32 v72, v40, v41
	v_cvt_pk_bf16_f32 v73, v42, v43
	global_store_dwordx2 v32, v[72:73], s[26:27] offset:0
	s_waitcnt vmcnt(30)
	v_lshlrev_b32_e32 v35, 16, v74
	v_and_b32_e32 v36, 0xffff0000, v74
	v_lshlrev_b32_e32 v37, 16, v75
	v_and_b32_e32 v38, 0xffff0000, v75
	v_mul_f32_e32 v35, v34, v35
	v_mul_f32_e32 v36, v34, v36
	v_mul_f32_e32 v37, v34, v37
	v_mul_f32_e32 v38, v34, v38
	v_fma_f32 v44, v4, v35, v44
	v_fma_f32 v45, v5, v36, v45
	v_fma_f32 v46, v6, v37, v46
	v_fma_f32 v47, v7, v38, v47
	global_store_dwordx4 v166, v[44:47], s[24:25] offset:-3072
	v_cvt_pk_bf16_f32 v74, v44, v45
	v_cvt_pk_bf16_f32 v75, v46, v47
	global_store_dwordx2 v32, v[74:75], s[26:27] offset:512
	s_waitcnt vmcnt(30)
	v_lshlrev_b32_e32 v35, 16, v76
	v_and_b32_e32 v36, 0xffff0000, v76
	v_lshlrev_b32_e32 v37, 16, v77
	v_and_b32_e32 v38, 0xffff0000, v77
	v_mul_f32_e32 v35, v34, v35
	v_mul_f32_e32 v36, v34, v36
	v_mul_f32_e32 v37, v34, v37
	v_mul_f32_e32 v38, v34, v38
	v_fma_f32 v48, v8, v35, v48
	v_fma_f32 v49, v9, v36, v49
	v_fma_f32 v50, v10, v37, v50
	v_fma_f32 v51, v11, v38, v51
	global_store_dwordx4 v166, v[48:51], s[24:25] offset:-2048
	v_cvt_pk_bf16_f32 v76, v48, v49
	v_cvt_pk_bf16_f32 v77, v50, v51
	global_store_dwordx2 v32, v[76:77], s[26:27] offset:1024
	s_waitcnt vmcnt(30)
; __device__ __forceinline__ unsigned pk2(float lo, float hi) { return pg8::cvt_pk_bf16(lo, hi); }
; __device__ __forceinline__ float bf_lo(unsigned w) { return __uint_as_float(w << 16); }
; __device__ __forceinline__ float bf_hi(unsigned w) { return __uint_as_float(w & 0xffff0000u); }
; __global__ void __launch_bounds__(512, 2) fwd(Params P) {
;     ...
;         for (int m = gw; m < T_TOK; m += NGW) {
;             const float rsd = __builtin_amdgcn_rsqf(ssq_d[m] * (1.f / DM) + EPS);
;             const u32x2* dr = (const u32x2*)(DN + (size_t)m * DM) + lane;
;             f32x4* orow = (f32x4*)(OUT_P + (size_t)m * DM) + lane; u32x2* o = (u32x2*)(XN + (size_t)m * DM) + lane;
; #pragma unroll
;             for (int j = 0; j < 8; ++j) { const f32x4 xv = __builtin_nontemporal_load(&orow[64 * j]); const u32x2 dw = __builtin_nontemporal_load(&dr[64 * j]); const f32x4 g = g1[64 * j];
;                 f32x4 t; t.x = xv.x + bf_lo(dw.x) * rsd * g.x; t.y = xv.y + bf_hi(dw.x) * rsd * g.y; t.z = xv.z + bf_lo(dw.y) * rsd * g.z; t.w = xv.w + bf_hi(dw.y) * rsd * g.w;
;                 orow[64 * j] = t; u32x2 w; w.x = pk2(t.x, t.y); w.y = pk2(t.z, t.w); o[64 * j] = w; }
	v_lshlrev_b32_e32 v35, 16, v78
	v_and_b32_e32 v36, 0xffff0000, v78
	v_lshlrev_b32_e32 v37, 16, v79
	v_and_b32_e32 v38, 0xffff0000, v79
	v_mul_f32_e32 v35, v34, v35
	v_mul_f32_e32 v36, v34, v36
	v_mul_f32_e32 v37, v34, v37
	v_mul_f32_e32 v38, v34, v38
	v_fma_f32 v52, v12, v35, v52
	v_fma_f32 v53, v13, v36, v53
	v_fma_f32 v54, v14, v37, v54
	v_fma_f32 v55, v15, v38, v55
	global_store_dwordx4 v166, v[52:55], s[24:25] offset:-1024
	v_cvt_pk_bf16_f32 v78, v52, v53
	v_cvt_pk_bf16_f32 v79, v54, v55
	global_store_dwordx2 v32, v[78:79], s[26:27] offset:1536
	s_waitcnt vmcnt(30)
	v_lshlrev_b32_e32 v35, 16, v80
	v_and_b32_e32 v36, 0xffff0000, v80
	v_lshlrev_b32_e32 v37, 16, v81
	v_and_b32_e32 v38, 0xffff0000, v81
	v_mul_f32_e32 v35, v34, v35
	v_mul_f32_e32 v36, v34, v36
	v_mul_f32_e32 v37, v34, v37
	v_mul_f32_e32 v38, v34, v38
	v_fma_f32 v56, v16, v35, v56
	v_fma_f32 v57, v17, v36, v57
	v_fma_f32 v58, v18, v37, v58
	v_fma_f32 v59, v19, v38, v59
	global_store_dwordx4 v166, v[56:59], s[24:25] offset:0
	v_cvt_pk_bf16_f32 v80, v56, v57
	v_cvt_pk_bf16_f32 v81, v58, v59
	global_store_dwordx2 v32, v[80:81], s[26:27] offset:2048
	s_waitcnt vmcnt(30)
	v_lshlrev_b32_e32 v35, 16, v82
	v_and_b32_e32 v36, 0xffff0000, v82
	v_lshlrev_b32_e32 v37, 16, v83
	v_and_b32_e32 v38, 0xffff0000, v83
	v_mul_f32_e32 v35, v34, v35
	v_mul_f32_e32 v36, v34, v36
	v_mul_f32_e32 v37, v34, v37
	v_mul_f32_e32 v38, v34, v38
	v_fma_f32 v60, v20, v35, v60
	v_fma_f32 v61, v21, v36, v61
	v_fma_f32 v62, v22, v37, v62
	v_fma_f32 v63, v23, v38, v63
	global_store_dwordx4 v166, v[60:63], s[24:25] offset:1024
	v_cvt_pk_bf16_f32 v82, v60, v61
	v_cvt_pk_bf16_f32 v83, v62, v63
	global_store_dwordx2 v32, v[82:83], s[26:27] offset:2560
	s_waitcnt vmcnt(30)
	v_lshlrev_b32_e32 v35, 16, v84
	v_and_b32_e32 v36, 0xffff0000, v84
	v_lshlrev_b32_e32 v37, 16, v85
	v_and_b32_e32 v38, 0xffff0000, v85
	v_mul_f32_e32 v35, v34, v35
	v_mul_f32_e32 v36, v34, v36
	v_mul_f32_e32 v37, v34, v37
	v_mul_f32_e32 v38, v34, v38
	v_fma_f32 v64, v24, v35, v64
	v_fma_f32 v65, v25, v36, v65
	v_fma_f32 v66, v26, v37, v66
	v_fma_f32 v67, v27, v38, v67
	global_store_dwordx4 v166, v[64:67], s[24:25] offset:2048
	v_cvt_pk_bf16_f32 v84, v64, v65
	v_cvt_pk_bf16_f32 v85, v66, v67
	global_store_dwordx2 v32, v[84:85], s[26:27] offset:3072
	s_waitcnt vmcnt(30)
	v_lshlrev_b32_e32 v35, 16, v86
	v_and_b32_e32 v36, 0xffff0000, v86
	v_lshlrev_b32_e32 v37, 16, v87
	v_and_b32_e32 v38, 0xffff0000, v87
	v_mul_f32_e32 v35, v34, v35
	v_mul_f32_e32 v36, v34, v36
	v_mul_f32_e32 v37, v34, v37
	v_mul_f32_e32 v38, v34, v38
	v_fma_f32 v68, v28, v35, v68
	v_fma_f32 v69, v29, v36, v69
	v_fma_f32 v70, v30, v37, v70
	v_fma_f32 v71, v31, v38, v71
	global_store_dwordx4 v166, v[68:71], s[24:25] offset:3072
	v_cvt_pk_bf16_f32 v86, v68, v69
	v_cvt_pk_bf16_f32 v87, v70, v71
	global_store_dwordx2 v32, v[86:87], s[26:27] offset:3584
	s_branch .Lp7b_done
; __device__ __forceinline__ unsigned pk2(float lo, float hi) { return pg8::cvt_pk_bf16(lo, hi); }
; __device__ __forceinline__ float bf_lo(unsigned w) { return __uint_as_float(w << 16); }
; __device__ __forceinline__ float bf_hi(unsigned w) { return __uint_as_float(w & 0xffff0000u); }
; __global__ void __launch_bounds__(512, 2) fwd(Params P) {
;     ...
;         for (int m = gw; m < T_TOK; m += NGW) {
;             const float rsd = __builtin_amdgcn_rsqf(ssq_d[m] * (1.f / DM) + EPS);
;             const u32x2* dr = (const u32x2*)(DN + (size_t)m * DM) + lane;
;             f32x4* orow = (f32x4*)(OUT_P + (size_t)m * DM) + lane; u32x2* o = (u32x2*)(XN + (size_t)m * DM) + lane;
; #pragma unroll
;             for (int j = 0; j < 8; ++j) { const f32x4 xv = __builtin_nontemporal_load(&orow[64 * j]); const u32x2 dw = __builtin_nontemporal_load(&dr[64 * j]); const f32x4 g = g1[64 * j];
;                 f32x4 t; t.x = xv.x + bf_lo(dw.x) * rsd * g.x; t.y = xv.y + bf_hi(dw.x) * rsd * g.y; t.z = xv.z + bf_lo(dw.y) * rsd * g.z; t.w = xv.w + bf_hi(dw.y) * rsd * g.w;
;                 orow[64 * j] = t; u32x2 w; w.x = pk2(t.x, t.y); w.y = pk2(t.z, t.w); o[64 * j] = w; }
.Lp7b_tail_b:
	s_waitcnt vmcnt(30)
	v_fmamk_f32 v34, v144, 0x3a000000, v33
	v_rsq_f32_e32 v34, v34
	v_lshlrev_b32_e32 v35, 16, v128
	v_and_b32_e32 v36, 0xffff0000, v128
	v_lshlrev_b32_e32 v37, 16, v129
	v_and_b32_e32 v38, 0xffff0000, v129
	v_mul_f32_e32 v35, v34, v35
	v_mul_f32_e32 v36, v34, v36
	v_mul_f32_e32 v37, v34, v37
	v_mul_f32_e32 v38, v34, v38
	v_fma_f32 v96, v0, v35, v96
	v_fma_f32 v97, v1, v36, v97
	v_fma_f32 v98, v2, v37, v98
	v_fma_f32 v99, v3, v38, v99
	global_store_dwordx4 v166, v[96:99], s[24:25] offset:-4096
	v_cvt_pk_bf16_f32 v128, v96, v97
	v_cvt_pk_bf16_f32 v129, v98, v99
	global_store_dwordx2 v32, v[128:129], s[26:27] offset:0
	s_waitcnt vmcnt(30)
	v_lshlrev_b32_e32 v35, 16, v130
	v_and_b32_e32 v36, 0xffff0000, v130
	v_lshlrev_b32_e32 v37, 16, v131
	v_and_b32_e32 v38, 0xffff0000, v131
	v_mul_f32_e32 v35, v34, v35
	v_mul_f32_e32 v36, v34, v36
	v_mul_f32_e32 v37, v34, v37
	v_mul_f32_e32 v38, v34, v38
	v_fma_f32 v100, v4, v35, v100
	v_fma_f32 v101, v5, v36, v101
	v_fma_f32 v102, v6, v37, v102
	v_fma_f32 v103, v7, v38, v103
	global_store_dwordx4 v166, v[100:103], s[24:25] offset:-3072
	v_cvt_pk_bf16_f32 v130, v100, v101
	v_cvt_pk_bf16_f32 v131, v102, v103
	global_store_dwordx2 v32, v[130:131], s[26:27] offset:512
	s_waitcnt vmcnt(30)
	v_lshlrev_b32_e32 v35, 16, v132
	v_and_b32_e32 v36, 0xffff0000, v132
	v_lshlrev_b32_e32 v37, 16, v133
	v_and_b32_e32 v38, 0xffff0000, v133
	v_mul_f32_e32 v35, v34, v35
	v_mul_f32_e32 v36, v34, v36
	v_mul_f32_e32 v37, v34, v37
	v_mul_f32_e32 v38, v34, v38
	v_fma_f32 v104, v8, v35, v104
	v_fma_f32 v105, v9, v36, v105
	v_fma_f32 v106, v10, v37, v106
	v_fma_f32 v107, v11, v38, v107
	global_store_dwordx4 v166, v[104:107], s[24:25] offset:-2048
	v_cvt_pk_bf16_f32 v132, v104, v105
	v_cvt_pk_bf16_f32 v133, v106, v107
	global_store_dwordx2 v32, v[132:133], s[26:27] offset:1024
	s_waitcnt vmcnt(30)
	v_lshlrev_b32_e32 v35, 16, v134
	v_and_b32_e32 v36, 0xffff0000, v134
	v_lshlrev_b32_e32 v37, 16, v135
	v_and_b32_e32 v38, 0xffff0000, v135
	v_mul_f32_e32 v35, v34, v35
	v_mul_f32_e32 v36, v34, v36
	v_mul_f32_e32 v37, v34, v37
	v_mul_f32_e32 v38, v34, v38
	v_fma_f32 v108, v12, v35, v108
	v_fma_f32 v109, v13, v36, v109
	v_fma_f32 v110, v14, v37, v110
	v_fma_f32 v111, v15, v38, v111
	global_store_dwordx4 v166, v[108:111], s[24:25] offset:-1024
	v_cvt_pk_bf16_f32 v134, v108, v109
	v_cvt_pk_bf16_f32 v135, v110, v111
	global_store_dwordx2 v32, v[134:135], s[26:27] offset:1536
	s_waitcnt vmcnt(30)
	v_lshlrev_b32_e32 v35, 16, v136
	v_and_b32_e32 v36, 0xffff0000, v136
	v_lshlrev_b32_e32 v37, 16, v137
	v_and_b32_e32 v38, 0xffff0000, v137
	v_mul_f32_e32 v35, v34, v35
	v_mul_f32_e32 v36, v34, v36
	v_mul_f32_e32 v37, v34, v37
	v_mul_f32_e32 v38, v34, v38
	v_fma_f32 v112, v16, v35, v112
	v_fma_f32 v113, v17, v36, v113
	v_fma_f32 v114, v18, v37, v114
	v_fma_f32 v115, v19, v38, v115
	global_store_dwordx4 v166, v[112:115], s[24:25] offset:0
	v_cvt_pk_bf16_f32 v136, v112, v113
	v_cvt_pk_bf16_f32 v137, v114, v115
	global_store_dwordx2 v32, v[136:137], s[26:27] offset:2048
	s_waitcnt vmcnt(30)
	v_lshlrev_b32_e32 v35, 16, v138
	v_and_b32_e32 v36, 0xffff0000, v138
	v_lshlrev_b32_e32 v37, 16, v139
	v_and_b32_e32 v38, 0xffff0000, v139
	v_mul_f32_e32 v35, v34, v35
	v_mul_f32_e32 v36, v34, v36
	v_mul_f32_e32 v37, v34, v37
	v_mul_f32_e32 v38, v34, v38
	v_fma_f32 v116, v20, v35, v116
	v_fma_f32 v117, v21, v36, v117
	v_fma_f32 v118, v22, v37, v118
	v_fma_f32 v119, v23, v38, v119
	global_store_dwordx4 v166, v[116:119], s[24:25] offset:1024
	v_cvt_pk_bf16_f32 v138, v116, v117
	v_cvt_pk_bf16_f32 v139, v118, v119
	global_store_dwordx2 v32, v[138:139], s[26:27] offset:2560
	s_waitcnt vmcnt(30)
	v_lshlrev_b32_e32 v35, 16, v140
	v_and_b32_e32 v36, 0xffff0000, v140
	v_lshlrev_b32_e32 v37, 16, v141
	v_and_b32_e32 v38, 0xffff0000, v141
	v_mul_f32_e32 v35, v34, v35
	v_mul_f32_e32 v36, v34, v36
	v_mul_f32_e32 v37, v34, v37
	v_mul_f32_e32 v38, v34, v38
	v_fma_f32 v120, v24, v35, v120
	v_fma_f32 v121, v25, v36, v121
	v_fma_f32 v122, v26, v37, v122
	v_fma_f32 v123, v27, v38, v123
	global_store_dwordx4 v166, v[120:123], s[24:25] offset:2048
	v_cvt_pk_bf16_f32 v140, v120, v121
	v_cvt_pk_bf16_f32 v141, v122, v123
	global_store_dwordx2 v32, v[140:141], s[26:27] offset:3072
	s_waitcnt vmcnt(30)
	v_lshlrev_b32_e32 v35, 16, v142
	v_and_b32_e32 v36, 0xffff0000, v142
	v_lshlrev_b32_e32 v37, 16, v143
	v_and_b32_e32 v38, 0xffff0000, v143
	v_mul_f32_e32 v35, v34, v35
	v_mul_f32_e32 v36, v34, v36
	v_mul_f32_e32 v37, v34, v37
	v_mul_f32_e32 v38, v34, v38
	v_fma_f32 v124, v28, v35, v124
	v_fma_f32 v125, v29, v36, v125
	v_fma_f32 v126, v30, v37, v126
	v_fma_f32 v127, v31, v38, v127
	global_store_dwordx4 v166, v[124:127], s[24:25] offset:3072
	v_cvt_pk_bf16_f32 v142, v124, v125
	v_cvt_pk_bf16_f32 v143, v126, v127
	global_store_dwordx2 v32, v[142:143], s[26:27] offset:3584
